# adds: gate/up epilogue vmcnt(7) waits to s_nop, s_nop between LDS-DMA blocks removed, in-proj heavy/light unit order rotated per XCD pair
# baseline (speedup 1.0000x reference)
; #define LAS __attribute__((address_space(3)))
; #define PG8_BAR __builtin_amdgcn_s_barrier()
;     __device__ bool next(int i, Unit& u) const {
;         if (G == 256) { if (i >= R) return false; const int xcd = c & 7, r = c >> 3; u.pm = (xcd >> 1) * 8 + (r & 7); u.pn = (2 * i + (xcd & 1)) * 4 + (r >> 3); return true; }
;         const int L = i * G + c; if (L >= 32 * 8 * R) return false; u.pm = L & 31; u.pn = L >> 5; return true;
;     }
; template <class Epi, class Sched, bool ALIGN_EPI>
; __device__ __forceinline__ void gemm_phase(LAS unsigned char* lds, const Gemm g, const Sched& S, const Epi& E) {
;     const int tid = otid(), wid = __builtin_amdgcn_readfirstlane(tid >> 6), lane = tid & 63, wr = wid >> 2, wc = wid & 3, fr = lane & 15, fq = lane >> 4;
;     const int K = g.K, nt = K / BK;
;     unsigned voffA[2], voffB[2];
; #pragma unroll
;     for (int i = 0; i < 2; ++i) { int R, C; stage_rc(tid * 16 + i * 8192, R, C); const int Rb = (R & ~31) + perm32(R & 31);
;         voffA[i] = (unsigned)(R * g.lda + C) * 2u; voffB[i] = (unsigned)(Rb * g.ldb + C) * 2u; }
;     const size_t kstep = (size_t)(BK * 2);
;     const size_t hstepA = (size_t)HALF * g.lda * 2, hstepB = (size_t)HALF * g.ldb * 2;
;     const size_t tstepA = 2 * hstepA, tstepB = 2 * hstepB;
;     const unsigned ldsw = (unsigned)wid * 1024u;
;     const int aoff = lds_byte(wr * 64 + fr, fq * 8), boff = lds_byte(wc * 32 + fr, fq * 8);
;     ...
;     const unsigned ldsb0 = (unsigned)(uintptr_t)lds + ldsw;
;     ...
;     Unit cur, nxt; int ui = 0;
;     if (!S.next(0, cur)) return;
;     f32x4 acc[2][2][4][2];
; #pragma unroll
;     for (int a = 0; a < 2; ++a)
; #pragma unroll
;         for (int b = 0; b < 2; ++b)
; #pragma unroll
;             for (int m = 0; m < 4; ++m)
; #pragma unroll
;                 for (int n = 0; n < 2; ++n) acc[a][b][m][n] = (f32x4){0.f, 0.f, 0.f, 0.f};
;     bf16x8 At[4][2], B0[2][2], B1[2][2];
;     float pre[Epi::NPRE > 0 ? Epi::NPRE : 1];
;     if constexpr (Epi::NPRE > 0) E.preload(cur, wr, fr, pre);
;     const char* cA = (const char*)g.A + (size_t)cur.pm * tstepA + (size_t)cur.pn * g.a_koff * 2; const char* cB = (const char*)g.Bt + (size_t)cur.pn * tstepB;
;     PG8_STAGE(PG8_SB(0, 0), cB, voffB); PG8_STAGE(PG8_SB(0, 1), cB + hstepB, voffB); PG8_STAGE(PG8_SA(0, 0), cA, voffA); PG8_STAGE(PG8_SA(0, 1), cA + hstepA, voffA);
;     if (wr == 1) PG8_BAR;
;     PG8_WAIT_V(2); PG8_BAR;
.LBB0_99:
	s_or_b64 exec, exec, s[4:5]
	s_cmpk_lg_i32 s76, 0x100
	s_cselect_b64 s[20:21], -1, 0
	s_cmpk_gt_i32 s86, 0x1ff
	s_cselect_b64 s[18:19], -1, 0
	s_lshl_b32 s2, s86, 2
	s_and_b32 s4, s2, 24
	s_bfe_u32 s5, s86, 0x30003
	s_or_b32 s26, s4, s5
	s_and_b32 s2, s2, 4
	s_ashr_i32 s4, s86, 6
	s_ashr_i32 s24, s86, 5
	s_and_b32 s25, s86, 31
	s_add_i32 s27, s2, s4
	s_cmpk_eq_i32 s76, 0x100
	s_cselect_b64 s[22:23], -1, 0
	v_writelane_b32 v242, s22, 10
	s_mov_b64 s[10:11], s[0:1]
	s_mov_b64 s[12:13], s[0:1]
	v_writelane_b32 v242, s23, 11
	s_and_b64 s[22:23], s[22:23], exec
	s_mov_b64 s[14:15], s[0:1]
	s_mov_b64 s[6:7], s[0:1]
	s_mov_b64 s[16:17], s[0:1]
	s_mov_b64 s[4:5], s[0:1]
	s_mov_b64 s[8:9], s[0:1]
	s_mov_b64 s[28:29], s[0:1]
	s_mov_b64 s[30:31], s[0:1]
	s_mov_b64 s[34:35], s[0:1]
	s_waitcnt lgkmcnt(0)
	v_mov_b32_e32 v2, v0
	s_cselect_b32 s22, s27, s24
	s_cselect_b32 s60, s26, s25
	s_and_b64 s[18:19], s[20:21], s[18:19]
	s_lshl_b32 s99, s86, 2
	s_and_b32 s99, s99, 8
	s_add_i32 s22, s22, s99
	s_barrier
	v_writelane_b32 v242, s27, 12
	v_readfirstlane_b32 s2, v2
	s_and_b64 vcc, exec, s[18:19]
	v_writelane_b32 v242, s26, 13
	s_cbranch_vccnz .LBB0_376
	v_bfe_i32 v4, v2, 27, 1
	v_lshlrev_b32_e32 v6, 4, v2
	v_lshrrev_b32_e32 v4, 22, v4
	v_add_u32_e32 v4, v6, v4
	v_and_b32_e32 v4, 0xfffffc00, v4
	v_sub_u32_e32 v4, v6, v4
	s_load_dwordx2 s[10:11], s[10:11], 0xb0
	s_nop 0
	s_load_dwordx2 s[12:13], s[12:13], 0xb0
	s_nop 0
	s_load_dwordx2 s[18:19], s[14:15], 0xb0
	s_nop 0
	s_load_dwordx2 s[14:15], s[6:7], 0xb0
	s_nop 0
	s_load_dwordx2 s[16:17], s[16:17], 0xa8
	v_ashrrev_i32_e32 v3, 31, v2
	v_lshrrev_b32_e32 v5, 4, v4
	s_waitcnt lgkmcnt(0)
	s_add_u32 s53, s10, 0x1d800000
	v_lshrrev_b32_e32 v3, 26, v3
	v_bitop3_b32 v5, v5, v4, 32 bitop3:0x6c
	v_ashrrev_i32_e32 v4, 31, v4
	s_addc_u32 s54, s11, 0
	v_add_u32_e32 v3, v2, v3
	v_lshrrev_b32_e32 v4, 26, v4
	s_add_u32 s55, s12, 0x100000
	v_ashrrev_i32_e32 v3, 6, v3
	v_add_u32_e32 v4, v5, v4
	s_addc_u32 s57, s13, 0
	v_lshlrev_b32_e32 v7, 3, v3
	v_ashrrev_i32_e32 v8, 6, v4
	v_lshlrev_b32_e32 v3, 5, v3
	s_add_u32 s10, s18, 0x10000
	v_and_b32_e32 v9, 32, v3
	v_mul_i32_i24_e32 v3, 64, v8
	s_addc_u32 s11, s19, 0
	s_ashr_i32 s25, s2, 8
	v_sub_u32_e32 v3, v5, v3
	v_mov_b32_e32 v10, 1
	s_load_dwordx2 s[18:19], s[4:5], 0xb0
	s_load_dwordx2 s[26:27], s[8:9], 0xb0
	s_nop 0
	s_load_dwordx2 s[28:29], s[28:29], 0xb0
	s_nop 0
	s_load_dwordx2 s[30:31], s[30:31], 0xa8
	s_nop 0
	s_load_dwordx2 s[8:9], s[34:35], 0xa8
	v_ashrrev_i16_sdwa v3, v10, sext(v3) dst_sel:DWORD dst_unused:UNUSED_PAD src0_sel:DWORD src1_sel:BYTE_0
	s_lshl_b32 s36, s25, 6
	s_lshl_b32 s4, s60, 8
	v_bfe_i32 v11, v3, 0, 16
	v_and_b32_e32 v3, 15, v2
	s_add_i32 s4, s4, s36
	v_or_b32_e32 v4, s4, v3
	v_ashrrev_i32_e32 v5, 31, v4
	v_lshl_add_u64 v[4:5], v[4:5], 2, s[10:11]
	global_load_dword v134, v[4:5], off
	global_load_dword v170, v[4:5], off offset:64
	global_load_dword v169, v[4:5], off offset:128
	global_load_dword v168, v[4:5], off offset:192
	global_load_dword v167, v[4:5], off offset:512
	global_load_dword v165, v[4:5], off offset:576
	global_load_dword v164, v[4:5], off offset:640
	global_load_dword v163, v[4:5], off offset:704
	v_and_b32_e32 v7, -16, v7
	v_add_u32_e32 v7, v8, v7
	v_lshlrev_b32_e32 v4, 1, v7
	v_lshrrev_b32_e32 v5, 2, v7
	v_and_b32_e32 v8, 3, v8
	s_mov_b32 s4, 0xfffe0
	v_and_b32_e32 v4, 24, v4
	v_and_b32_e32 v5, 4, v5
	v_and_or_b32 v8, v7, s4, v8
	v_or3_b32 v4, v8, v5, v4
	v_add_lshl_u32 v5, v9, v11, 1
	v_lshl_add_u32 v152, v4, 12, v5
	v_add_u32_e32 v4, 0x2000, v6
	v_lshl_add_u32 v151, v7, 12, v5
	v_ashrrev_i32_e32 v5, 31, v4
	v_lshrrev_b32_e32 v5, 22, v5
	v_add_u32_e32 v5, v4, v5
	v_ashrrev_i32_e32 v5, 10, v5
	v_mul_i32_i24_e32 v6, 0x400, v5
	v_sub_u32_e32 v4, v4, v6
	v_lshrrev_b32_e32 v6, 4, v4
	v_bitop3_b32 v4, v6, v4, 32 bitop3:0x6c
	v_ashrrev_i32_e32 v7, 31, v4
	v_lshrrev_b32_e32 v7, 26, v7
	v_lshlrev_b32_e32 v6, 3, v5
	v_add_u32_e32 v7, v4, v7
	v_and_b32_e32 v6, -16, v6
	v_ashrrev_i32_e32 v8, 6, v7
	v_add_u32_e32 v6, v8, v6
	v_and_b32_e32 v7, 0xc0, v7
	v_and_b32_e32 v8, 3, v8
	s_ashr_i32 s37, s2, 6
	v_sub_u32_e32 v4, v4, v7
	v_and_or_b32 v8, v6, s4, v8
	s_lshl_b32 s4, s37, 10
	s_ashr_i32 s23, s22, 31
	v_lshlrev_b32_e32 v5, 5, v5
	v_ashrrev_i16_sdwa v4, v10, sext(v4) dst_sel:DWORD dst_unused:UNUSED_PAD src0_sel:DWORD src1_sel:BYTE_0
	v_lshlrev_b32_e32 v7, 1, v6
	v_lshrrev_b32_e32 v9, 2, v6
	s_add_i32 s61, s4, 0
	s_lshl_b32 s12, s60, 20
	s_lshl_b64 s[4:5], s[22:23], 20
	v_and_b32_e32 v5, 32, v5
	v_bfe_i32 v4, v4, 0, 16
	v_and_b32_e32 v7, 24, v7
	v_and_b32_e32 v9, 4, v9
	s_add_u32 s6, s55, s4
	v_or3_b32 v7, v8, v9, v7
	v_add_lshl_u32 v4, v5, v4, 1
	s_addc_u32 s7, s57, s5
	s_add_i32 s23, s61, 0x10000
	s_mov_b32 m0, s23
	s_nop 0
	global_load_lds_dwordx4 v152, s[6:7]
	v_lshl_add_u32 v154, v7, 12, v4
	s_add_i32 s62, s61, 0x12000
	s_mov_b32 m0, s62
	s_nop 0
	global_load_lds_dwordx4 v154, s[6:7]
	s_add_u32 s4, s6, 0x80000
	s_addc_u32 s5, s7, 0
	s_add_i32 s63, s61, 0x14000
	s_mov_b32 m0, s63
	s_nop 0
	global_load_lds_dwordx4 v152, s[4:5]
	s_add_i32 s64, s61, 0x16000
	s_mov_b32 m0, s64
	s_nop 0
	global_load_lds_dwordx4 v154, s[4:5]
	s_add_u32 s4, s53, s12
	s_addc_u32 s5, s54, 0
	s_mov_b32 m0, s61
	s_nop 0
	global_load_lds_dwordx4 v151, s[4:5]
	s_add_i32 s65, s61, 0x2000
	v_lshl_add_u32 v153, v6, 12, v4
	s_mov_b32 m0, s65
	s_nop 0
	global_load_lds_dwordx4 v153, s[4:5]
	s_add_u32 s34, s4, 0x80000
	s_addc_u32 s35, s5, 0
	s_add_i32 s66, s61, 0x4000
	s_mov_b32 m0, s66
	s_nop 0
	global_load_lds_dwordx4 v151, s[34:35]
	s_add_i32 s67, s61, 0x6000
	s_mov_b32 m0, s67
	s_nop 0
	global_load_lds_dwordx4 v153, s[34:35]
	s_cmp_eq_u32 s25, 1
	s_mov_b32 s24, 0
	s_cselect_b64 s[12:13], -1, 0
	s_cmp_lg_u32 s25, 1
	s_cbranch_scc1 .LBB0_102
	s_barrier
; #define PG8_STAGE(bufoff, gbase, voff) do { _Pragma("unroll") for (int _i = 0; _i < 2; ++_i) { unsigned keep_; \
;         asm volatile("s_mov_b32 %0, m0\n\ts_mov_b32 m0, %3\n\ts_nop 0\n\tglobal_load_lds_dwordx4 %1, %2\n\ts_mov_b32 m0, %0" \
;             : "=&s"(keep_) : "v"((voff)[_i]), "s"((const void*)(gbase)), "s"(ldsb0 + (unsigned)(bufoff) + (unsigned)(_i * 8192)) : "memory"); } } while (0)
; #define PG8_WAIT_V(n) asm volatile("s_waitcnt vmcnt(" #n ")" ::: "memory")
; #define PG8_BAR __builtin_amdgcn_s_barrier()
; template <class Epi, class Sched, bool ALIGN_EPI>
; __device__ __forceinline__ void gemm_phase(LAS unsigned char* lds, const Gemm g, const Sched& S, const Epi& E) {
;     ...
;     PG8_STAGE(PG8_SB(1, 0), cB + kstep, voffB); PG8_STAGE(PG8_SA(1, 0), cA + kstep, voffA); PG8_STAGE(PG8_SB(1, 1), cB + hstepB + kstep, voffB);
;     PG8_WAIT_V(6); PG8_BAR;
;     for (;;) {
;         const bool has_next = S.next(ui + 1, nxt);
;         const char* nA = has_next ? (const char*)g.A + (size_t)nxt.pm * tstepA + (size_t)nxt.pn * g.a_koff * 2 : cA; const char* nB = has_next ? (const char*)g.Bt + (size_t)nxt.pn * tstepB : cB;
.LBB0_102:
	v_readlane_b32 s34, v242, 12
	s_add_i32 s68, s22, 8
	s_and_b32 s68, s68, 15
	s_add_u32 s14, s14, 0xe000000
	s_addc_u32 s15, s15, 0
	s_add_u32 s16, s16, 0x4100000
	s_addc_u32 s17, s17, 0
	s_waitcnt lgkmcnt(0)
	s_add_u32 s18, s18, 0x10100000
	s_addc_u32 s19, s19, 0
	s_add_u32 s26, s26, 0x12200000
	s_addc_u32 s27, s27, 0
	s_add_u32 s28, s28, 0x14300000
	s_addc_u32 s29, s29, 0
	s_add_u32 s30, s30, 0x410f000
	v_lshrrev_b32_e32 v2, 1, v2
	s_addc_u32 s31, s31, 0
	v_or_b32_e32 v155, s36, v3
	v_and_b32_e32 v2, 24, v2
	s_add_u32 s34, s8, 0x610f000
	v_lshlrev_b32_e32 v4, 6, v155
	v_lshlrev_b32_e32 v5, 1, v2
	s_movk_i32 s8, 0x3c0
	v_lshlrev_b32_e32 v6, 2, v155
	s_addc_u32 s35, s9, 0
	v_and_or_b32 v4, v4, s8, v5
	s_lshl_b32 s8, s25, 13
	v_and_b32_e32 v6, 32, v6
	v_bitop3_b32 v4, v4, s8, v6 bitop3:0xde
	s_lshl_b32 s8, s37, 5
	s_and_b32 s25, s8, 0x60
	v_lshl_or_b32 v5, v3, 6, v5
	v_lshlrev_b32_e32 v3, 2, v3
	s_lshl_b32 s8, s25, 7
	v_and_b32_e32 v3, 32, v3
	v_bitop3_b32 v3, v5, s8, v3 bitop3:0xde
	s_add_u32 s8, s6, 0x80
	s_waitcnt vmcnt(2)
	s_barrier
	s_addc_u32 s9, s7, 0
	s_add_i32 s69, s61, 0x18000
	s_mov_b32 m0, s69
	s_nop 0
	global_load_lds_dwordx4 v152, s[8:9]
	s_add_i32 s70, s61, 0x1a000
	s_mov_b32 m0, s70
	s_nop 0
	global_load_lds_dwordx4 v154, s[8:9]
	s_add_u32 s8, s4, 0x80
	s_addc_u32 s9, s5, 0
	s_add_i32 s71, s61, 0x8000
	s_mov_b32 m0, s71
	s_nop 0
	global_load_lds_dwordx4 v151, s[8:9]
	s_add_i32 s72, s61, 0xa000
	s_mov_b32 m0, s72
	s_nop 0
	global_load_lds_dwordx4 v153, s[8:9]
	s_add_u32 s8, s6, 0x80080
	s_addc_u32 s9, s7, 0
	s_add_i32 s73, s61, 0x1c000
	s_mov_b32 m0, s73
	s_nop 0
	global_load_lds_dwordx4 v152, s[8:9]
	s_add_i32 s74, s61, 0x1e000
	s_mov_b32 m0, s74
	s_nop 0
	global_load_lds_dwordx4 v154, s[8:9]
	s_waitcnt vmcnt(6)
	s_add_i32 s75, s61, 0xc000
	s_cmpk_lt_u32 s2, 0x100
	v_or_b32_e32 v156, s25, v2
	v_add_u32_e32 v2, 0, v3
	s_cselect_b64 s[36:37], -1, 0
	s_add_i32 s77, s61, 0xe000
	v_add_u32_e32 v157, 0x10000, v2
	v_add_u32_e32 v158, 0x14000, v2
	v_add_u32_e32 v159, 0, v4
	v_add_u32_e32 v160, 0x18000, v2
	v_add_u32_e32 v161, 0x1c000, v2
	v_mov_b32_e32 v162, 0x358637bd
	s_movk_i32 s78, 0x1ff0
	v_mov_b32_e32 v135, 0
	s_mov_b32 s2, s22
	s_mov_b32 s25, s60
	s_barrier
	s_branch .LBB0_105

; #define PG8_STAGE(bufoff, gbase, voff) do { _Pragma("unroll") for (int _i = 0; _i < 2; ++_i) { unsigned keep_; \
;         asm volatile("s_mov_b32 %0, m0\n\ts_mov_b32 m0, %3\n\ts_nop 0\n\tglobal_load_lds_dwordx4 %1, %2\n\ts_mov_b32 m0, %0" \
;             : "=&s"(keep_) : "v"((voff)[_i]), "s"((const void*)(gbase)), "s"(ldsb0 + (unsigned)(bufoff) + (unsigned)(_i * 8192)) : "memory"); } } while (0)
; #define PG8_LDA(dst, b, h) do { _Pragma("unroll") for (int m = 0; m < 4; ++m) _Pragma("unroll") for (int k = 0; k < 2; ++k) dst[m][k] = *(const LAS bf16x8*)(lds + PG8_SA(b, h) + aoff + m * 2048 + k * 1024); } while (0)
; #define PG8_LDB(dst, b, h) do { _Pragma("unroll") for (int n = 0; n < 2; ++n) _Pragma("unroll") for (int k = 0; k < 2; ++k) dst[n][k] = *(const LAS bf16x8*)(lds + PG8_SB(b, h) + boff + n * 2048 + k * 1024); } while (0)
; #define PG8_MMA(ai, bj, At, Bt) do { __builtin_amdgcn_s_setprio(1); _Pragma("unroll") for (int m = 0; m < 4; ++m) _Pragma("unroll") for (int n = 0; n < 2; ++n) _Pragma("unroll") for (int k = 0; k < 2; ++k) \
;         acc[ai][bj][m][n] = __builtin_amdgcn_mfma_f32_16x16x32_bf16(Bt[n][k], At[m][k], acc[ai][bj][m][n], 0, 0, 0); __builtin_amdgcn_s_setprio(0); } while (0)
; #define PG8_WAIT_V(n) asm volatile("s_waitcnt vmcnt(" #n ")" ::: "memory")
; #define PG8_BAR __builtin_amdgcn_s_barrier()
; template <class Epi, class Sched, bool ALIGN_EPI>
; __device__ __forceinline__ void gemm_phase(LAS unsigned char* lds, const Gemm g, const Sched& S, const Epi& E) {
;     ...
;         for (int t = 0; t < nt; t += 2) {
;             const bool last = (t == nt - 2);
;             const char* a1 = cA + (size_t)(t + 1) * kstep;
;             const char* a2 = last ? nA : cA + (size_t)(t + 2) * kstep; const char* b2 = last ? nB : cB + (size_t)(t + 2) * kstep;
;             const char* a3 = a2 + kstep; const char* b3 = b2 + kstep;
;             PG8_LDB(B0, 0, 0); PG8_LDB(B1, 0, 1); PG8_SCHED; PG8_LDA(At, 0, 0); PG8_STAGE(PG8_SA(1, 1), a1 + hstepA, voffA);
;             PG8_WAIT_V(8); PG8_WAIT_L(0); PG8_BAR; PG8_MMA(0, 0, At, B0); PG8_MMA(0, 1, At, B1); PG8_BAR; PG8_SCHED;
;             PG8_LDA(At, 0, 1); PG8_STAGE(PG8_SB(0, 0), b2, voffB); PG8_STAGE(PG8_SB(0, 1), b2 + hstepB, voffB); PG8_STAGE(PG8_SA(0, 0), a2, voffA);
;             PG8_WAIT_V(8); PG8_WAIT_L(0); PG8_BAR; PG8_MMA(1, 0, At, B0); PG8_MMA(1, 1, At, B1); PG8_BAR; PG8_SCHED;
.LBB0_113:
	ds_read_b128 v[136:139], v157
	ds_read_b128 v[140:143], v157 offset:1024
	ds_read_b128 v[144:147], v157 offset:2048
	ds_read_b128 v[172:175], v157 offset:3072
	ds_read_b128 v[180:183], v158
	ds_read_b128 v[184:187], v158 offset:1024
	ds_read_b128 v[188:191], v158 offset:2048
	ds_read_b128 v[192:195], v158 offset:3072
	s_add_u32 s6, s4, 0x100
	s_addc_u32 s7, s5, 0
	s_cmp_eq_u32 s81, 28
	s_cselect_b32 s50, s39, s6
	s_cselect_b32 s51, s24, s7
	s_cselect_b32 s48, s58, s59
	s_cselect_b32 s49, s41, s80
	s_add_u32 s8, s50, 0x80
	s_addc_u32 s9, s51, 0
	ds_read_b128 v[196:199], v159
	ds_read_b128 v[206:209], v159 offset:1024
	ds_read_b128 v[210:213], v159 offset:2048
	ds_read_b128 v[214:217], v159 offset:3072
	ds_read_b128 v[218:221], v159 offset:4096
	ds_read_b128 v[222:225], v159 offset:5120
	ds_read_b128 v[226:229], v159 offset:6144
	ds_read_b128 v[230:233], v159 offset:7168
	s_add_u32 s4, s4, 0x80080
	s_addc_u32 s5, s5, 0
	s_mov_b32 m0, s75
	s_nop 0
	global_load_lds_dwordx4 v151, s[4:5]
	s_mov_b32 m0, s77
	s_nop 0
	global_load_lds_dwordx4 v153, s[4:5]
	s_waitcnt vmcnt(8)
	s_waitcnt lgkmcnt(0)
	s_barrier
	s_setprio 1
	v_mfma_f32_16x16x32_bf16 v[126:129], v[136:139], v[196:199], v[126:129]
	v_mfma_f32_16x16x32_bf16 v[122:125], v[144:147], v[196:199], v[122:125]
	v_mfma_f32_16x16x32_bf16 v[110:113], v[136:139], v[210:213], v[110:113]
	v_mfma_f32_16x16x32_bf16 v[106:109], v[144:147], v[210:213], v[106:109]
	v_mfma_f32_16x16x32_bf16 v[94:97], v[136:139], v[218:221], v[94:97]
	v_mfma_f32_16x16x32_bf16 v[90:93], v[144:147], v[218:221], v[90:93]
	v_mfma_f32_16x16x32_bf16 v[78:81], v[136:139], v[226:229], v[78:81]
	v_mfma_f32_16x16x32_bf16 v[74:77], v[144:147], v[226:229], v[74:77]
	v_mfma_f32_16x16x32_bf16 v[126:129], v[140:143], v[206:209], v[126:129]
	v_mfma_f32_16x16x32_bf16 v[122:125], v[172:175], v[206:209], v[122:125]
	v_mfma_f32_16x16x32_bf16 v[110:113], v[140:143], v[214:217], v[110:113]
	v_mfma_f32_16x16x32_bf16 v[106:109], v[172:175], v[214:217], v[106:109]
	v_mfma_f32_16x16x32_bf16 v[94:97], v[140:143], v[222:225], v[94:97]
	v_mfma_f32_16x16x32_bf16 v[90:93], v[172:175], v[222:225], v[90:93]
	v_mfma_f32_16x16x32_bf16 v[78:81], v[140:143], v[230:233], v[78:81]
	v_mfma_f32_16x16x32_bf16 v[74:77], v[172:175], v[230:233], v[74:77]
	v_mfma_f32_16x16x32_bf16 v[118:121], v[180:183], v[196:199], v[118:121]
	v_mfma_f32_16x16x32_bf16 v[114:117], v[188:191], v[196:199], v[114:117]
	v_mfma_f32_16x16x32_bf16 v[102:105], v[180:183], v[210:213], v[102:105]
	v_mfma_f32_16x16x32_bf16 v[98:101], v[188:191], v[210:213], v[98:101]
	v_mfma_f32_16x16x32_bf16 v[86:89], v[180:183], v[218:221], v[86:89]
	v_mfma_f32_16x16x32_bf16 v[82:85], v[188:191], v[218:221], v[82:85]
	v_mfma_f32_16x16x32_bf16 v[70:73], v[180:183], v[226:229], v[70:73]
	v_mfma_f32_16x16x32_bf16 v[66:69], v[188:191], v[226:229], v[66:69]
	v_mfma_f32_16x16x32_bf16 v[118:121], v[184:187], v[206:209], v[118:121]
	v_mfma_f32_16x16x32_bf16 v[114:117], v[192:195], v[206:209], v[114:117]
	v_mfma_f32_16x16x32_bf16 v[102:105], v[184:187], v[214:217], v[102:105]
	v_mfma_f32_16x16x32_bf16 v[98:101], v[192:195], v[214:217], v[98:101]
	v_mfma_f32_16x16x32_bf16 v[86:89], v[184:187], v[222:225], v[86:89]
	v_mfma_f32_16x16x32_bf16 v[82:85], v[192:195], v[222:225], v[82:85]
	v_mfma_f32_16x16x32_bf16 v[70:73], v[184:187], v[230:233], v[70:73]
	v_mfma_f32_16x16x32_bf16 v[66:69], v[192:195], v[230:233], v[66:69]
	s_setprio 0
	s_barrier
	ds_read_b128 v[196:199], v159 offset:16384
	ds_read_b128 v[206:209], v159 offset:17408
	ds_read_b128 v[210:213], v159 offset:18432
	ds_read_b128 v[214:217], v159 offset:19456
	ds_read_b128 v[218:221], v159 offset:20480
	ds_read_b128 v[222:225], v159 offset:21504
	ds_read_b128 v[226:229], v159 offset:22528
	ds_read_b128 v[230:233], v159 offset:23552
	s_mov_b32 m0, s23
	s_nop 0
	global_load_lds_dwordx4 v152, s[48:49]
	s_mov_b32 m0, s62
	s_nop 0
	global_load_lds_dwordx4 v154, s[48:49]
	s_add_u32 s4, s48, 0x80000
	s_addc_u32 s5, s49, 0
	s_mov_b32 m0, s63
	s_nop 0
	global_load_lds_dwordx4 v152, s[4:5]
	s_mov_b32 m0, s64
	s_nop 0
	global_load_lds_dwordx4 v154, s[4:5]
	s_mov_b32 m0, s61
	s_nop 0
	global_load_lds_dwordx4 v151, s[50:51]
	s_mov_b32 m0, s65
	s_nop 0
	global_load_lds_dwordx4 v153, s[50:51]
	s_waitcnt vmcnt(8)
	s_waitcnt lgkmcnt(0)
	s_barrier
	s_setprio 1
	v_mfma_f32_16x16x32_bf16 v[62:65], v[136:139], v[196:199], v[62:65]
	v_mfma_f32_16x16x32_bf16 v[58:61], v[144:147], v[196:199], v[58:61]
	v_mfma_f32_16x16x32_bf16 v[46:49], v[136:139], v[210:213], v[46:49]
	v_mfma_f32_16x16x32_bf16 v[42:45], v[144:147], v[210:213], v[42:45]
	v_mfma_f32_16x16x32_bf16 v[30:33], v[136:139], v[218:221], v[30:33]
	v_mfma_f32_16x16x32_bf16 v[26:29], v[144:147], v[218:221], v[26:29]
	v_mfma_f32_16x16x32_bf16 v[14:17], v[136:139], v[226:229], v[14:17]
	v_mfma_f32_16x16x32_bf16 v[10:13], v[144:147], v[226:229], v[10:13]
	v_mfma_f32_16x16x32_bf16 v[62:65], v[140:143], v[206:209], v[62:65]
	v_mfma_f32_16x16x32_bf16 v[58:61], v[172:175], v[206:209], v[58:61]
	v_mfma_f32_16x16x32_bf16 v[46:49], v[140:143], v[214:217], v[46:49]
	v_mfma_f32_16x16x32_bf16 v[42:45], v[172:175], v[214:217], v[42:45]
	v_mfma_f32_16x16x32_bf16 v[30:33], v[140:143], v[222:225], v[30:33]
	v_mfma_f32_16x16x32_bf16 v[26:29], v[172:175], v[222:225], v[26:29]
	v_mfma_f32_16x16x32_bf16 v[14:17], v[140:143], v[230:233], v[14:17]
	v_mfma_f32_16x16x32_bf16 v[10:13], v[172:175], v[230:233], v[10:13]
	v_mfma_f32_16x16x32_bf16 v[54:57], v[180:183], v[196:199], v[54:57]
	v_mfma_f32_16x16x32_bf16 v[50:53], v[188:191], v[196:199], v[50:53]
	v_mfma_f32_16x16x32_bf16 v[38:41], v[180:183], v[210:213], v[38:41]
	v_mfma_f32_16x16x32_bf16 v[34:37], v[188:191], v[210:213], v[34:37]
	v_mfma_f32_16x16x32_bf16 v[22:25], v[180:183], v[218:221], v[22:25]
	v_mfma_f32_16x16x32_bf16 v[18:21], v[188:191], v[218:221], v[18:21]
	v_mfma_f32_16x16x32_bf16 v[6:9], v[180:183], v[226:229], v[6:9]
	v_mfma_f32_16x16x32_bf16 v[2:5], v[188:191], v[226:229], v[2:5]
	v_mfma_f32_16x16x32_bf16 v[54:57], v[184:187], v[206:209], v[54:57]
	v_mfma_f32_16x16x32_bf16 v[50:53], v[192:195], v[206:209], v[50:53]
	v_mfma_f32_16x16x32_bf16 v[38:41], v[184:187], v[214:217], v[38:41]
	v_mfma_f32_16x16x32_bf16 v[34:37], v[192:195], v[214:217], v[34:37]
	v_mfma_f32_16x16x32_bf16 v[22:25], v[184:187], v[222:225], v[22:25]
	v_mfma_f32_16x16x32_bf16 v[18:21], v[192:195], v[222:225], v[18:21]
	v_mfma_f32_16x16x32_bf16 v[6:9], v[184:187], v[230:233], v[6:9]
	v_mfma_f32_16x16x32_bf16 v[2:5], v[192:195], v[230:233], v[2:5]
	s_setprio 0
	s_barrier
; #define PG8_STAGE(bufoff, gbase, voff) do { _Pragma("unroll") for (int _i = 0; _i < 2; ++_i) { unsigned keep_; \
;         asm volatile("s_mov_b32 %0, m0\n\ts_mov_b32 m0, %3\n\ts_nop 0\n\tglobal_load_lds_dwordx4 %1, %2\n\ts_mov_b32 m0, %0" \
;             : "=&s"(keep_) : "v"((voff)[_i]), "s"((const void*)(gbase)), "s"(ldsb0 + (unsigned)(bufoff) + (unsigned)(_i * 8192)) : "memory"); } } while (0)
; #define PG8_LDA(dst, b, h) do { _Pragma("unroll") for (int m = 0; m < 4; ++m) _Pragma("unroll") for (int k = 0; k < 2; ++k) dst[m][k] = *(const LAS bf16x8*)(lds + PG8_SA(b, h) + aoff + m * 2048 + k * 1024); } while (0)
; #define PG8_LDB(dst, b, h) do { _Pragma("unroll") for (int n = 0; n < 2; ++n) _Pragma("unroll") for (int k = 0; k < 2; ++k) dst[n][k] = *(const LAS bf16x8*)(lds + PG8_SB(b, h) + boff + n * 2048 + k * 1024); } while (0)
; #define PG8_MMA(ai, bj, At, Bt) do { __builtin_amdgcn_s_setprio(1); _Pragma("unroll") for (int m = 0; m < 4; ++m) _Pragma("unroll") for (int n = 0; n < 2; ++n) _Pragma("unroll") for (int k = 0; k < 2; ++k) \
;         acc[ai][bj][m][n] = __builtin_amdgcn_mfma_f32_16x16x32_bf16(Bt[n][k], At[m][k], acc[ai][bj][m][n], 0, 0, 0); __builtin_amdgcn_s_setprio(0); } while (0)
; #define PG8_WAIT_V(n) asm volatile("s_waitcnt vmcnt(" #n ")" ::: "memory")
; #define PG8_WAIT_L(n) asm volatile("s_waitcnt lgkmcnt(" #n ")" ::: "memory")
; #define PG8_BAR __builtin_amdgcn_s_barrier()
; #define PG8_SCHED __builtin_amdgcn_sched_barrier(0)
; template <class Epi, class Sched, bool ALIGN_EPI>
; __device__ __forceinline__ void gemm_phase(LAS unsigned char* lds, const Gemm g, const Sched& S, const Epi& E) {
;     ...
;             PG8_LDB(B0, 1, 0); PG8_LDB(B1, 1, 1); PG8_SCHED; PG8_LDA(At, 1, 0); PG8_STAGE(PG8_SA(0, 1), a2 + hstepA, voffA);
;             PG8_WAIT_V(8); PG8_WAIT_L(0); PG8_BAR; PG8_MMA(0, 0, At, B0); PG8_MMA(0, 1, At, B1); PG8_BAR; PG8_SCHED;
;             PG8_LDA(At, 1, 1); PG8_STAGE(PG8_SB(1, 0), b3, voffB); PG8_STAGE(PG8_SB(1, 1), b3 + hstepB, voffB); PG8_STAGE(PG8_SA(1, 0), a3, voffA);
;             PG8_WAIT_V(8); PG8_WAIT_L(0); PG8_BAR; PG8_MMA(1, 0, At, B0); PG8_MMA(1, 1, At, B1); PG8_BAR; PG8_SCHED;
;         }
	ds_read_b128 v[136:139], v160
	ds_read_b128 v[140:143], v160 offset:1024
	ds_read_b128 v[144:147], v160 offset:2048
	ds_read_b128 v[172:175], v160 offset:3072
	ds_read_b128 v[180:183], v161
	ds_read_b128 v[184:187], v161 offset:1024
	ds_read_b128 v[188:191], v161 offset:2048
	ds_read_b128 v[192:195], v161 offset:3072
	ds_read_b128 v[196:199], v159 offset:32768
	ds_read_b128 v[206:209], v159 offset:33792
	ds_read_b128 v[210:213], v159 offset:34816
	ds_read_b128 v[214:217], v159 offset:35840
	ds_read_b128 v[218:221], v159 offset:36864
	ds_read_b128 v[222:225], v159 offset:37888
	ds_read_b128 v[226:229], v159 offset:38912
	ds_read_b128 v[230:233], v159 offset:39936
	s_add_u32 s4, s50, 0x80000
	s_addc_u32 s5, s51, 0
	s_mov_b32 m0, s66
	s_nop 0
	global_load_lds_dwordx4 v151, s[4:5]
	s_mov_b32 m0, s67
	s_nop 0
	global_load_lds_dwordx4 v153, s[4:5]
	s_waitcnt vmcnt(8)
	s_waitcnt lgkmcnt(0)
	s_barrier
	s_setprio 1
	v_mfma_f32_16x16x32_bf16 v[126:129], v[136:139], v[196:199], v[126:129]
	v_mfma_f32_16x16x32_bf16 v[122:125], v[144:147], v[196:199], v[122:125]
	v_mfma_f32_16x16x32_bf16 v[110:113], v[136:139], v[210:213], v[110:113]
	v_mfma_f32_16x16x32_bf16 v[106:109], v[144:147], v[210:213], v[106:109]
	v_mfma_f32_16x16x32_bf16 v[94:97], v[136:139], v[218:221], v[94:97]
	v_mfma_f32_16x16x32_bf16 v[90:93], v[144:147], v[218:221], v[90:93]
	v_mfma_f32_16x16x32_bf16 v[78:81], v[136:139], v[226:229], v[78:81]
	v_mfma_f32_16x16x32_bf16 v[74:77], v[144:147], v[226:229], v[74:77]
	v_mfma_f32_16x16x32_bf16 v[126:129], v[140:143], v[206:209], v[126:129]
	v_mfma_f32_16x16x32_bf16 v[122:125], v[172:175], v[206:209], v[122:125]
	v_mfma_f32_16x16x32_bf16 v[110:113], v[140:143], v[214:217], v[110:113]
	v_mfma_f32_16x16x32_bf16 v[106:109], v[172:175], v[214:217], v[106:109]
	v_mfma_f32_16x16x32_bf16 v[94:97], v[140:143], v[222:225], v[94:97]
	v_mfma_f32_16x16x32_bf16 v[90:93], v[172:175], v[222:225], v[90:93]
	v_mfma_f32_16x16x32_bf16 v[78:81], v[140:143], v[230:233], v[78:81]
	v_mfma_f32_16x16x32_bf16 v[74:77], v[172:175], v[230:233], v[74:77]
	v_mfma_f32_16x16x32_bf16 v[118:121], v[180:183], v[196:199], v[118:121]
	v_mfma_f32_16x16x32_bf16 v[114:117], v[188:191], v[196:199], v[114:117]
	v_mfma_f32_16x16x32_bf16 v[102:105], v[180:183], v[210:213], v[102:105]
	v_mfma_f32_16x16x32_bf16 v[98:101], v[188:191], v[210:213], v[98:101]
	v_mfma_f32_16x16x32_bf16 v[86:89], v[180:183], v[218:221], v[86:89]
	v_mfma_f32_16x16x32_bf16 v[82:85], v[188:191], v[218:221], v[82:85]
	v_mfma_f32_16x16x32_bf16 v[70:73], v[180:183], v[226:229], v[70:73]
	v_mfma_f32_16x16x32_bf16 v[66:69], v[188:191], v[226:229], v[66:69]
	v_mfma_f32_16x16x32_bf16 v[118:121], v[184:187], v[206:209], v[118:121]
	v_mfma_f32_16x16x32_bf16 v[114:117], v[192:195], v[206:209], v[114:117]
	v_mfma_f32_16x16x32_bf16 v[102:105], v[184:187], v[214:217], v[102:105]
	v_mfma_f32_16x16x32_bf16 v[98:101], v[192:195], v[214:217], v[98:101]
	v_mfma_f32_16x16x32_bf16 v[86:89], v[184:187], v[222:225], v[86:89]
	v_mfma_f32_16x16x32_bf16 v[82:85], v[192:195], v[222:225], v[82:85]
	v_mfma_f32_16x16x32_bf16 v[70:73], v[184:187], v[230:233], v[70:73]
	v_mfma_f32_16x16x32_bf16 v[66:69], v[192:195], v[230:233], v[66:69]
	s_setprio 0
	s_barrier
	ds_read_b128 v[196:199], v159 offset:49152
	ds_read_b128 v[206:209], v159 offset:50176
	ds_read_b128 v[210:213], v159 offset:51200
	ds_read_b128 v[214:217], v159 offset:52224
	ds_read_b128 v[218:221], v159 offset:53248
	ds_read_b128 v[222:225], v159 offset:54272
	ds_read_b128 v[226:229], v159 offset:55296
	ds_read_b128 v[230:233], v159 offset:56320
	s_add_u32 s4, s48, 0x80
	s_addc_u32 s5, s49, 0
	s_mov_b32 m0, s69
	s_nop 0
	global_load_lds_dwordx4 v152, s[4:5]
	s_mov_b32 m0, s70
	s_nop 0
	global_load_lds_dwordx4 v154, s[4:5]
	s_add_u32 s4, s48, 0x80080
	s_addc_u32 s5, s49, 0
	s_mov_b32 m0, s73
	s_nop 0
	global_load_lds_dwordx4 v152, s[4:5]
	s_mov_b32 m0, s74
	s_nop 0
	global_load_lds_dwordx4 v154, s[4:5]
	s_mov_b32 m0, s71
	s_nop 0
	global_load_lds_dwordx4 v151, s[8:9]
	s_mov_b32 m0, s72
	s_nop 0
	global_load_lds_dwordx4 v153, s[8:9]
	s_waitcnt vmcnt(8)
	s_waitcnt lgkmcnt(0)
	s_barrier
	s_setprio 1
	v_mfma_f32_16x16x32_bf16 v[62:65], v[136:139], v[196:199], v[62:65]
	v_mfma_f32_16x16x32_bf16 v[58:61], v[144:147], v[196:199], v[58:61]
	v_mfma_f32_16x16x32_bf16 v[46:49], v[136:139], v[210:213], v[46:49]
	v_mfma_f32_16x16x32_bf16 v[42:45], v[144:147], v[210:213], v[42:45]
	v_mfma_f32_16x16x32_bf16 v[30:33], v[136:139], v[218:221], v[30:33]
	v_mfma_f32_16x16x32_bf16 v[26:29], v[144:147], v[218:221], v[26:29]
	v_mfma_f32_16x16x32_bf16 v[14:17], v[136:139], v[226:229], v[14:17]
	v_mfma_f32_16x16x32_bf16 v[10:13], v[144:147], v[226:229], v[10:13]
	v_mfma_f32_16x16x32_bf16 v[62:65], v[140:143], v[206:209], v[62:65]
	v_mfma_f32_16x16x32_bf16 v[58:61], v[172:175], v[206:209], v[58:61]
	v_mfma_f32_16x16x32_bf16 v[46:49], v[140:143], v[214:217], v[46:49]
	v_mfma_f32_16x16x32_bf16 v[42:45], v[172:175], v[214:217], v[42:45]
	v_mfma_f32_16x16x32_bf16 v[30:33], v[140:143], v[222:225], v[30:33]
	v_mfma_f32_16x16x32_bf16 v[26:29], v[172:175], v[222:225], v[26:29]
	v_mfma_f32_16x16x32_bf16 v[14:17], v[140:143], v[230:233], v[14:17]
	v_mfma_f32_16x16x32_bf16 v[10:13], v[172:175], v[230:233], v[10:13]
	v_mfma_f32_16x16x32_bf16 v[54:57], v[180:183], v[196:199], v[54:57]
	v_mfma_f32_16x16x32_bf16 v[50:53], v[188:191], v[196:199], v[50:53]
	v_mfma_f32_16x16x32_bf16 v[38:41], v[180:183], v[210:213], v[38:41]
	v_mfma_f32_16x16x32_bf16 v[34:37], v[188:191], v[210:213], v[34:37]
	v_mfma_f32_16x16x32_bf16 v[22:25], v[180:183], v[218:221], v[22:25]
	v_mfma_f32_16x16x32_bf16 v[18:21], v[188:191], v[218:221], v[18:21]
	v_mfma_f32_16x16x32_bf16 v[6:9], v[180:183], v[226:229], v[6:9]
	v_mfma_f32_16x16x32_bf16 v[2:5], v[188:191], v[226:229], v[2:5]
	v_mfma_f32_16x16x32_bf16 v[54:57], v[184:187], v[206:209], v[54:57]
	v_mfma_f32_16x16x32_bf16 v[50:53], v[192:195], v[206:209], v[50:53]
	v_mfma_f32_16x16x32_bf16 v[38:41], v[184:187], v[214:217], v[38:41]
	v_mfma_f32_16x16x32_bf16 v[34:37], v[192:195], v[214:217], v[34:37]
	v_mfma_f32_16x16x32_bf16 v[22:25], v[184:187], v[222:225], v[22:25]
	v_mfma_f32_16x16x32_bf16 v[18:21], v[192:195], v[222:225], v[18:21]
	v_mfma_f32_16x16x32_bf16 v[6:9], v[184:187], v[230:233], v[6:9]
	v_mfma_f32_16x16x32_bf16 v[2:5], v[192:195], v[230:233], v[2:5]
	s_setprio 0
	s_barrier
	s_add_i32 s81, s81, 2
	s_add_u32 s59, s59, 0x100
	s_addc_u32 s80, s80, 0
	s_cmp_gt_u32 s81, 29
	s_mov_b64 s[4:5], s[6:7]
	s_cbranch_scc0 .LBB0_113
	s_and_b64 vcc, exec, s[36:37]
	s_cbranch_vccz .LBB0_116
	s_barrier

; #define cache_pool KIN(2)
; __global__ void __launch_bounds__(NT, 2) fwd(Args args) {
;     ...
;         const int c0 = 4 * (tid & 255), grp = __builtin_amdgcn_readfirstlane((tid >> 6) & 3), w = 2 << grp, hlf = __builtin_amdgcn_readfirstlane(tid >> 8);
;         const int NSC_ = SEQ / 1024 + DECB * ((NKS + 1023) / 1024), GP = G > 2 * NSC_ ? G - NSC_ : G;
;         for (int pit = (G > 2 * NSC_ && bx >= GP) ? (1 << 30) : bx; pit < (512 + DECB) / 2; pit += GP) {
;             const int it = 2 * pit + hlf;
;             const bool smp = it >= 512; const int b = it - 512;
;             const int r0 = smp ? 0 : it * 16, base = smp ? SEQ + b * DECS : 0;
;             const float* ub = U + (size_t)base * PW + c0;
;             const float* pre = cache_pool + (size_t)(smp ? b : 0) * 15 * PW + c0;
;             f32x4 a[31], u[16];
.LBB0_469:
	s_or_b64 exec, exec, s[4:5]
	s_sub_i32 s22, s22, s99
	s_sub_i32 s6, s76, 48
	s_cmpk_lt_i32 s76, 0x61
	s_cselect_b64 s[4:5], -1, 0
	s_and_b64 s[2:3], s[4:5], exec
	s_cselect_b32 s3, s76, s6
	s_cmp_lt_i32 s86, s3
	s_cselect_b64 s[6:7], -1, 0
	s_or_b64 s[10:11], s[4:5], s[6:7]
	s_cmpk_lt_i32 s86, 0x104
	s_cselect_b64 s[4:5], -1, 0
	s_and_b64 s[6:7], s[10:11], s[4:5]
	v_readfirstlane_b32 s4, v150
	v_readfirstlane_b32 s2, v148
	s_and_b64 vcc, exec, s[6:7]
	s_waitcnt lgkmcnt(0)
	s_barrier
	s_cbranch_vccz .LBB0_549
	s_and_b32 s4, s4, 3
	s_lshl_b32 s23, 2, s4
	s_ashr_i32 s2, s2, 8
	s_cmp_lg_u32 s4, 0
	s_cselect_b64 s[14:15], -1, 0
	s_cmp_gt_u32 s4, 1
	s_cselect_b64 s[16:17], -1, 0
	s_cmp_eq_u32 s4, 3
	v_lshlrev_b32_e32 v2, 2, v148
	s_cselect_b64 s[26:27], -1, 0
	s_lshl_b32 s4, s86, 1
	v_and_b32_e32 v126, 0x3fc, v2
	s_add_i32 s24, s2, s4
	s_lshl_b32 s4, s86, 5
	s_lshl_b32 s2, s2, 4
	v_mov_b32_e32 v129, 0
	s_mov_b32 s13, 0
	v_cvt_f32_ubyte0_e32 v127, s23
	s_lshl_b32 s25, s3, 1
	s_add_i32 s28, s4, s2
	s_lshl_b32 s40, s3, 5
	s_mov_b64 s[30:31], 0xe000000
	s_movk_i32 s41, 0x2000
	s_movk_i32 s42, 0x4000
	s_movk_i32 s43, 0x6000
	s_mov_b32 s44, 0x8000
	s_mov_b32 s45, 0xa000
	s_mov_b32 s46, 0xc000
	s_mov_b32 s47, 0xe000
	s_mov_b32 s48, 0xe001000
	s_mov_b32 s49, 0xe003000
	s_mov_b32 s50, 0xe005000
	s_mov_b32 s51, 0xe007000
	s_mov_b32 s52, 0xe009000
	s_mov_b32 s53, 0xe00b000
	s_mov_b32 s54, 0xe00c000
	v_lshlrev_b32_e32 v128, 1, v126
	s_mov_b32 s55, 0x16400000
	s_mov_b32 s57, s86
	s_branch .LBB0_472

; #define PG8_STAGE(bufoff, gbase, voff) do { _Pragma("unroll") for (int _i = 0; _i < 2; ++_i) { unsigned keep_; \
;         asm volatile("s_mov_b32 %0, m0\n\ts_mov_b32 m0, %3\n\ts_nop 0\n\tglobal_load_lds_dwordx4 %1, %2\n\ts_mov_b32 m0, %0" \
;             : "=&s"(keep_) : "v"((voff)[_i]), "s"((const void*)(gbase)), "s"(ldsb0 + (unsigned)(bufoff) + (unsigned)(_i * 8192)) : "memory"); } } while (0)
; #define PG8_WAIT_V(n) asm volatile("s_waitcnt vmcnt(" #n ")" ::: "memory")
; #define PG8_WAIT_L(n) asm volatile("s_waitcnt lgkmcnt(" #n ")" ::: "memory")
; template <class Epi, class Sched, bool ALIGN_EPI>
; __device__ __forceinline__ void gemm_phase(LAS unsigned char* lds, const Gemm g, const Sched& S, const Epi& E) {
;     ...
;         const bool has_next = S.next(ui + 1, nxt);
;         const char* nA = has_next ? (const char*)g.A + (size_t)nxt.pm * tstepA + (size_t)nxt.pn * g.a_koff * 2 : cA; const char* nB = has_next ? (const char*)g.Bt + (size_t)nxt.pn * tstepB : cB;
; #pragma unroll 1
;         for (int t = 0; t < nt; t += 2) {
;             const bool last = (t == nt - 2);
;             const char* a1 = cA + (size_t)(t + 1) * kstep;
;             const char* a2 = last ? nA : cA + (size_t)(t + 2) * kstep; const char* b2 = last ? nB : cB + (size_t)(t + 2) * kstep;
;             const char* a3 = a2 + kstep; const char* b3 = b2 + kstep;
;             PG8_LDB(B0, 0, 0); PG8_LDB(B1, 0, 1); PG8_SCHED; PG8_LDA(At, 0, 0); PG8_STAGE(PG8_SA(1, 1), a1 + hstepA, voffA);
;             PG8_WAIT_V(8); PG8_WAIT_L(0); PG8_BAR; PG8_MMA(0, 0, At, B0); PG8_MMA(0, 1, At, B1); PG8_BAR; PG8_SCHED;
;             PG8_LDA(At, 0, 1); PG8_STAGE(PG8_SB(0, 0), b2, voffB); PG8_STAGE(PG8_SB(0, 1), b2 + hstepB, voffB); PG8_STAGE(PG8_SA(0, 0), a2, voffA);
;             PG8_WAIT_V(8); PG8_WAIT_L(0); PG8_BAR; PG8_MMA(1, 0, At, B0); PG8_MMA(1, 1, At, B1); PG8_BAR; PG8_SCHED;
;             PG8_LDB(B0, 1, 0); PG8_LDB(B1, 1, 1); PG8_SCHED; PG8_LDA(At, 1, 0); PG8_STAGE(PG8_SA(0, 1), a2 + hstepA, voffA);
;             PG8_WAIT_V(8); PG8_WAIT_L(0); PG8_BAR; PG8_MMA(0, 0, At, B0); PG8_MMA(0, 1, At, B1); PG8_BAR; PG8_SCHED;
;             PG8_LDA(At, 1, 1); PG8_STAGE(PG8_SB(1, 0), b3, voffB); PG8_STAGE(PG8_SB(1, 1), b3 + hstepB, voffB); PG8_STAGE(PG8_SA(1, 0), a3, voffA);
;             PG8_WAIT_V(8); PG8_WAIT_L(0); PG8_BAR; PG8_MMA(1, 0, At, B0); PG8_MMA(1, 1, At, B1); PG8_BAR; PG8_SCHED;
.LBB0_805:
	s_add_u32 s48, s34, s40
	s_addc_u32 s49, s35, s41
	s_add_u32 s44, s48, 0x100
	s_addc_u32 s45, s49, 0
	s_and_b64 s[42:43], s[38:39], exec
	s_cselect_b32 s45, s3, s45
	s_cselect_b32 s44, s17, s44
	s_add_u32 s40, s30, s40
	s_addc_u32 s41, s31, s41
	s_add_u32 s42, s40, 0x100
	s_addc_u32 s43, s41, 0
	s_add_u32 s40, s44, 0x80
	s_addc_u32 s41, s45, 0
	ds_read_b128 v[130:133], v151
	s_waitcnt vmcnt(7)
	ds_read_b128 v[134:137], v151 offset:1024
	ds_read_b128 v[156:159], v151 offset:2048
	s_waitcnt vmcnt(0)
	ds_read_b128 v[160:163], v151 offset:3072
	ds_read_b128 v[164:167], v152
	ds_read_b128 v[168:171], v152 offset:1024
	ds_read_b128 v[172:175], v152 offset:2048
	ds_read_b128 v[180:183], v152 offset:3072
	s_and_b64 s[38:39], s[38:39], exec
	s_cselect_b32 s47, s15, s43
	s_cselect_b32 s46, s72, s42
	s_add_u32 s52, s48, 0x40080
	s_addc_u32 s53, s49, 0
	s_add_u32 s48, s46, 0x10000
	s_addc_u32 s49, s47, 0
	s_add_u32 s42, s44, 0x40000
	s_addc_u32 s43, s45, 0
	s_add_u32 s38, s46, 0x80
	s_addc_u32 s39, s47, 0
	s_add_u32 s50, s46, 0x10080
	s_addc_u32 s51, s47, 0
	ds_read_b128 v[184:187], v153
	ds_read_b128 v[188:191], v153 offset:1024
	ds_read_b128 v[192:195], v153 offset:2048
	ds_read_b128 v[196:199], v153 offset:3072
	ds_read_b128 v[200:203], v153 offset:4096
	ds_read_b128 v[204:207], v153 offset:5120
	ds_read_b128 v[208:211], v153 offset:6144
	ds_read_b128 v[212:215], v153 offset:7168
	s_mov_b32 m0, s70
	s_nop 0
	global_load_lds_dwordx4 v144, s[52:53]
	s_mov_b32 m0, s71
	s_nop 0
	global_load_lds_dwordx4 v146, s[52:53]
	s_waitcnt vmcnt(8)
	s_waitcnt lgkmcnt(0)
	s_barrier
	s_setprio 1
	v_mfma_f32_16x16x32_bf16 v[126:129], v[130:133], v[184:187], v[126:129]
	v_mfma_f32_16x16x32_bf16 v[122:125], v[156:159], v[184:187], v[122:125]
	v_mfma_f32_16x16x32_bf16 v[118:121], v[130:133], v[192:195], v[118:121]
	v_mfma_f32_16x16x32_bf16 v[114:117], v[156:159], v[192:195], v[114:117]
	v_mfma_f32_16x16x32_bf16 v[110:113], v[130:133], v[200:203], v[110:113]
	v_mfma_f32_16x16x32_bf16 v[106:109], v[156:159], v[200:203], v[106:109]
	v_mfma_f32_16x16x32_bf16 v[102:105], v[130:133], v[208:211], v[102:105]
	v_mfma_f32_16x16x32_bf16 v[98:101], v[156:159], v[208:211], v[98:101]
	v_mfma_f32_16x16x32_bf16 v[126:129], v[134:137], v[188:191], v[126:129]
	v_mfma_f32_16x16x32_bf16 v[122:125], v[160:163], v[188:191], v[122:125]
	v_mfma_f32_16x16x32_bf16 v[118:121], v[134:137], v[196:199], v[118:121]
	v_mfma_f32_16x16x32_bf16 v[114:117], v[160:163], v[196:199], v[114:117]
	v_mfma_f32_16x16x32_bf16 v[110:113], v[134:137], v[204:207], v[110:113]
	v_mfma_f32_16x16x32_bf16 v[106:109], v[160:163], v[204:207], v[106:109]
	v_mfma_f32_16x16x32_bf16 v[102:105], v[134:137], v[212:215], v[102:105]
	v_mfma_f32_16x16x32_bf16 v[98:101], v[160:163], v[212:215], v[98:101]
	v_mfma_f32_16x16x32_bf16 v[70:73], v[164:167], v[184:187], v[70:73]
	v_mfma_f32_16x16x32_bf16 v[66:69], v[172:175], v[184:187], v[66:69]
	v_mfma_f32_16x16x32_bf16 v[58:61], v[164:167], v[192:195], v[58:61]
	v_mfma_f32_16x16x32_bf16 v[50:53], v[172:175], v[192:195], v[50:53]
	v_mfma_f32_16x16x32_bf16 v[46:49], v[164:167], v[200:203], v[46:49]
	v_mfma_f32_16x16x32_bf16 v[42:45], v[172:175], v[200:203], v[42:45]
	v_mfma_f32_16x16x32_bf16 v[38:41], v[164:167], v[208:211], v[38:41]
	v_mfma_f32_16x16x32_bf16 v[34:37], v[172:175], v[208:211], v[34:37]
	v_mfma_f32_16x16x32_bf16 v[70:73], v[168:171], v[188:191], v[70:73]
	v_mfma_f32_16x16x32_bf16 v[66:69], v[180:183], v[188:191], v[66:69]
	v_mfma_f32_16x16x32_bf16 v[58:61], v[168:171], v[196:199], v[58:61]
	v_mfma_f32_16x16x32_bf16 v[50:53], v[180:183], v[196:199], v[50:53]
	v_mfma_f32_16x16x32_bf16 v[46:49], v[168:171], v[204:207], v[46:49]
	v_mfma_f32_16x16x32_bf16 v[42:45], v[180:183], v[204:207], v[42:45]
	v_mfma_f32_16x16x32_bf16 v[38:41], v[168:171], v[212:215], v[38:41]
	v_mfma_f32_16x16x32_bf16 v[34:37], v[180:183], v[212:215], v[34:37]
	s_setprio 0
	s_barrier
	ds_read_b128 v[184:187], v153 offset:16384
	ds_read_b128 v[188:191], v153 offset:17408
	ds_read_b128 v[192:195], v153 offset:18432
	ds_read_b128 v[196:199], v153 offset:19456
	ds_read_b128 v[200:203], v153 offset:20480
	ds_read_b128 v[204:207], v153 offset:21504
	ds_read_b128 v[208:211], v153 offset:22528
	ds_read_b128 v[212:215], v153 offset:23552
	s_mov_b32 m0, s29
	s_nop 0
	global_load_lds_dwordx4 v145, s[46:47]
	s_mov_b32 m0, s57
	s_nop 0
	global_load_lds_dwordx4 v147, s[46:47]
	s_mov_b32 m0, s58
	s_nop 0
	global_load_lds_dwordx4 v145, s[48:49]
	s_mov_b32 m0, s59
	s_nop 0
	global_load_lds_dwordx4 v147, s[48:49]
	s_mov_b32 m0, s56
	s_nop 0
	global_load_lds_dwordx4 v144, s[44:45]
	s_mov_b32 m0, s61
	s_nop 0
	global_load_lds_dwordx4 v146, s[44:45]
	s_waitcnt vmcnt(8)
	s_waitcnt lgkmcnt(0)
	s_barrier
; #define PG8_STAGE(bufoff, gbase, voff) do { _Pragma("unroll") for (int _i = 0; _i < 2; ++_i) { unsigned keep_; \
;         asm volatile("s_mov_b32 %0, m0\n\ts_mov_b32 m0, %3\n\ts_nop 0\n\tglobal_load_lds_dwordx4 %1, %2\n\ts_mov_b32 m0, %0" \
;             : "=&s"(keep_) : "v"((voff)[_i]), "s"((const void*)(gbase)), "s"(ldsb0 + (unsigned)(bufoff) + (unsigned)(_i * 8192)) : "memory"); } } while (0)
; #define PG8_LDA(dst, b, h) do { _Pragma("unroll") for (int m = 0; m < 4; ++m) _Pragma("unroll") for (int k = 0; k < 2; ++k) dst[m][k] = *(const LAS bf16x8*)(lds + PG8_SA(b, h) + aoff + m * 2048 + k * 1024); } while (0)
; #define PG8_LDB(dst, b, h) do { _Pragma("unroll") for (int n = 0; n < 2; ++n) _Pragma("unroll") for (int k = 0; k < 2; ++k) dst[n][k] = *(const LAS bf16x8*)(lds + PG8_SB(b, h) + boff + n * 2048 + k * 1024); } while (0)
; #define PG8_WAIT_V(n) asm volatile("s_waitcnt vmcnt(" #n ")" ::: "memory")
; #define PG8_WAIT_L(n) asm volatile("s_waitcnt lgkmcnt(" #n ")" ::: "memory")
; #define PG8_BAR __builtin_amdgcn_s_barrier()
; #define PG8_SCHED __builtin_amdgcn_sched_barrier(0)
; template <class Epi, class Sched, bool ALIGN_EPI>
; __device__ __forceinline__ void gemm_phase(LAS unsigned char* lds, const Gemm g, const Sched& S, const Epi& E) {
;     ...
;             PG8_LDB(B0, 0, 0); PG8_LDB(B1, 0, 1); PG8_SCHED; PG8_LDA(At, 0, 0); PG8_STAGE(PG8_SA(1, 1), a1 + hstepA, voffA);
;             PG8_WAIT_V(8); PG8_WAIT_L(0); PG8_BAR; PG8_MMA(0, 0, At, B0); PG8_MMA(0, 1, At, B1); PG8_BAR; PG8_SCHED;
;             PG8_LDA(At, 0, 1); PG8_STAGE(PG8_SB(0, 0), b2, voffB); PG8_STAGE(PG8_SB(0, 1), b2 + hstepB, voffB); PG8_STAGE(PG8_SA(0, 0), a2, voffA);
;             PG8_WAIT_V(8); PG8_WAIT_L(0); PG8_BAR; PG8_MMA(1, 0, At, B0); PG8_MMA(1, 1, At, B1); PG8_BAR; PG8_SCHED;
;             PG8_LDB(B0, 1, 0); PG8_LDB(B1, 1, 1); PG8_SCHED; PG8_LDA(At, 1, 0); PG8_STAGE(PG8_SA(0, 1), a2 + hstepA, voffA);
;             PG8_WAIT_V(8); PG8_WAIT_L(0); PG8_BAR; PG8_MMA(0, 0, At, B0); PG8_MMA(0, 1, At, B1); PG8_BAR; PG8_SCHED;
;             PG8_LDA(At, 1, 1); PG8_STAGE(PG8_SB(1, 0), b3, voffB); PG8_STAGE(PG8_SB(1, 1), b3 + hstepB, voffB); PG8_STAGE(PG8_SA(1, 0), a3, voffA);
;             PG8_WAIT_V(8); PG8_WAIT_L(0); PG8_BAR; PG8_MMA(1, 0, At, B0); PG8_MMA(1, 1, At, B1); PG8_BAR; PG8_SCHED;
	s_setprio 1
	v_mfma_f32_16x16x32_bf16 v[94:97], v[130:133], v[184:187], v[94:97]
	v_mfma_f32_16x16x32_bf16 v[90:93], v[156:159], v[184:187], v[90:93]
	v_mfma_f32_16x16x32_bf16 v[86:89], v[130:133], v[192:195], v[86:89]
	v_mfma_f32_16x16x32_bf16 v[82:85], v[156:159], v[192:195], v[82:85]
	v_mfma_f32_16x16x32_bf16 v[78:81], v[130:133], v[200:203], v[78:81]
	v_mfma_f32_16x16x32_bf16 v[74:77], v[156:159], v[200:203], v[74:77]
	v_mfma_f32_16x16x32_bf16 v[62:65], v[130:133], v[208:211], v[62:65]
	v_mfma_f32_16x16x32_bf16 v[54:57], v[156:159], v[208:211], v[54:57]
	v_mfma_f32_16x16x32_bf16 v[94:97], v[134:137], v[188:191], v[94:97]
	v_mfma_f32_16x16x32_bf16 v[90:93], v[160:163], v[188:191], v[90:93]
	v_mfma_f32_16x16x32_bf16 v[86:89], v[134:137], v[196:199], v[86:89]
	v_mfma_f32_16x16x32_bf16 v[82:85], v[160:163], v[196:199], v[82:85]
	v_mfma_f32_16x16x32_bf16 v[78:81], v[134:137], v[204:207], v[78:81]
	v_mfma_f32_16x16x32_bf16 v[74:77], v[160:163], v[204:207], v[74:77]
	v_mfma_f32_16x16x32_bf16 v[62:65], v[134:137], v[212:215], v[62:65]
	v_mfma_f32_16x16x32_bf16 v[54:57], v[160:163], v[212:215], v[54:57]
	v_mfma_f32_16x16x32_bf16 v[30:33], v[164:167], v[184:187], v[30:33]
	v_mfma_f32_16x16x32_bf16 v[26:29], v[172:175], v[184:187], v[26:29]
	v_mfma_f32_16x16x32_bf16 v[22:25], v[164:167], v[192:195], v[22:25]
	v_mfma_f32_16x16x32_bf16 v[18:21], v[172:175], v[192:195], v[18:21]
	v_mfma_f32_16x16x32_bf16 v[14:17], v[164:167], v[200:203], v[14:17]
	v_mfma_f32_16x16x32_bf16 v[10:13], v[172:175], v[200:203], v[10:13]
	v_mfma_f32_16x16x32_bf16 v[6:9], v[164:167], v[208:211], v[6:9]
	v_mfma_f32_16x16x32_bf16 v[2:5], v[172:175], v[208:211], v[2:5]
	v_mfma_f32_16x16x32_bf16 v[30:33], v[168:171], v[188:191], v[30:33]
	v_mfma_f32_16x16x32_bf16 v[26:29], v[180:183], v[188:191], v[26:29]
	v_mfma_f32_16x16x32_bf16 v[22:25], v[168:171], v[196:199], v[22:25]
	v_mfma_f32_16x16x32_bf16 v[18:21], v[180:183], v[196:199], v[18:21]
	v_mfma_f32_16x16x32_bf16 v[14:17], v[168:171], v[204:207], v[14:17]
	v_mfma_f32_16x16x32_bf16 v[10:13], v[180:183], v[204:207], v[10:13]
	v_mfma_f32_16x16x32_bf16 v[6:9], v[168:171], v[212:215], v[6:9]
	v_mfma_f32_16x16x32_bf16 v[2:5], v[180:183], v[212:215], v[2:5]
	s_setprio 0
	s_barrier
	ds_read_b128 v[130:133], v154
	ds_read_b128 v[134:137], v154 offset:1024
	ds_read_b128 v[156:159], v154 offset:2048
	ds_read_b128 v[160:163], v154 offset:3072
	ds_read_b128 v[164:167], v155
	ds_read_b128 v[168:171], v155 offset:1024
	ds_read_b128 v[172:175], v155 offset:2048
	ds_read_b128 v[180:183], v155 offset:3072
	ds_read_b128 v[184:187], v153 offset:32768
	ds_read_b128 v[188:191], v153 offset:33792
	ds_read_b128 v[192:195], v153 offset:34816
	ds_read_b128 v[196:199], v153 offset:35840
	ds_read_b128 v[200:203], v153 offset:36864
	ds_read_b128 v[204:207], v153 offset:37888
	ds_read_b128 v[208:211], v153 offset:38912
	ds_read_b128 v[212:215], v153 offset:39936
	s_mov_b32 m0, s62
	s_nop 0
	global_load_lds_dwordx4 v144, s[42:43]
	s_mov_b32 m0, s63
	s_nop 0
	global_load_lds_dwordx4 v146, s[42:43]
	s_waitcnt vmcnt(8)
	s_waitcnt lgkmcnt(0)
	s_barrier
	s_setprio 1
	v_mfma_f32_16x16x32_bf16 v[126:129], v[130:133], v[184:187], v[126:129]
	v_mfma_f32_16x16x32_bf16 v[122:125], v[156:159], v[184:187], v[122:125]
	v_mfma_f32_16x16x32_bf16 v[118:121], v[130:133], v[192:195], v[118:121]
	v_mfma_f32_16x16x32_bf16 v[114:117], v[156:159], v[192:195], v[114:117]
	v_mfma_f32_16x16x32_bf16 v[110:113], v[130:133], v[200:203], v[110:113]
	v_mfma_f32_16x16x32_bf16 v[106:109], v[156:159], v[200:203], v[106:109]
	v_mfma_f32_16x16x32_bf16 v[102:105], v[130:133], v[208:211], v[102:105]
	v_mfma_f32_16x16x32_bf16 v[98:101], v[156:159], v[208:211], v[98:101]
	v_mfma_f32_16x16x32_bf16 v[126:129], v[134:137], v[188:191], v[126:129]
	v_mfma_f32_16x16x32_bf16 v[122:125], v[160:163], v[188:191], v[122:125]
	v_mfma_f32_16x16x32_bf16 v[118:121], v[134:137], v[196:199], v[118:121]
	v_mfma_f32_16x16x32_bf16 v[114:117], v[160:163], v[196:199], v[114:117]
	v_mfma_f32_16x16x32_bf16 v[110:113], v[134:137], v[204:207], v[110:113]
	v_mfma_f32_16x16x32_bf16 v[106:109], v[160:163], v[204:207], v[106:109]
	v_mfma_f32_16x16x32_bf16 v[102:105], v[134:137], v[212:215], v[102:105]
	v_mfma_f32_16x16x32_bf16 v[98:101], v[160:163], v[212:215], v[98:101]
	v_mfma_f32_16x16x32_bf16 v[70:73], v[164:167], v[184:187], v[70:73]
	v_mfma_f32_16x16x32_bf16 v[66:69], v[172:175], v[184:187], v[66:69]
	v_mfma_f32_16x16x32_bf16 v[58:61], v[164:167], v[192:195], v[58:61]
	v_mfma_f32_16x16x32_bf16 v[50:53], v[172:175], v[192:195], v[50:53]
	v_mfma_f32_16x16x32_bf16 v[46:49], v[164:167], v[200:203], v[46:49]
	v_mfma_f32_16x16x32_bf16 v[42:45], v[172:175], v[200:203], v[42:45]
	v_mfma_f32_16x16x32_bf16 v[38:41], v[164:167], v[208:211], v[38:41]
	v_mfma_f32_16x16x32_bf16 v[34:37], v[172:175], v[208:211], v[34:37]
	v_mfma_f32_16x16x32_bf16 v[70:73], v[168:171], v[188:191], v[70:73]
	v_mfma_f32_16x16x32_bf16 v[66:69], v[180:183], v[188:191], v[66:69]
	v_mfma_f32_16x16x32_bf16 v[58:61], v[168:171], v[196:199], v[58:61]
	v_mfma_f32_16x16x32_bf16 v[50:53], v[180:183], v[196:199], v[50:53]
	v_mfma_f32_16x16x32_bf16 v[46:49], v[168:171], v[204:207], v[46:49]
	v_mfma_f32_16x16x32_bf16 v[42:45], v[180:183], v[204:207], v[42:45]
	v_mfma_f32_16x16x32_bf16 v[38:41], v[168:171], v[212:215], v[38:41]
	v_mfma_f32_16x16x32_bf16 v[34:37], v[180:183], v[212:215], v[34:37]
	s_setprio 0
	s_barrier
; #define PG8_STAGE(bufoff, gbase, voff) do { _Pragma("unroll") for (int _i = 0; _i < 2; ++_i) { unsigned keep_; \
;         asm volatile("s_mov_b32 %0, m0\n\ts_mov_b32 m0, %3\n\ts_nop 0\n\tglobal_load_lds_dwordx4 %1, %2\n\ts_mov_b32 m0, %0" \
;             : "=&s"(keep_) : "v"((voff)[_i]), "s"((const void*)(gbase)), "s"(ldsb0 + (unsigned)(bufoff) + (unsigned)(_i * 8192)) : "memory"); } } while (0)
; #define PG8_LDA(dst, b, h) do { _Pragma("unroll") for (int m = 0; m < 4; ++m) _Pragma("unroll") for (int k = 0; k < 2; ++k) dst[m][k] = *(const LAS bf16x8*)(lds + PG8_SA(b, h) + aoff + m * 2048 + k * 1024); } while (0)
; #define PG8_LDB(dst, b, h) do { _Pragma("unroll") for (int n = 0; n < 2; ++n) _Pragma("unroll") for (int k = 0; k < 2; ++k) dst[n][k] = *(const LAS bf16x8*)(lds + PG8_SB(b, h) + boff + n * 2048 + k * 1024); } while (0)
; #define PG8_WAIT_V(n) asm volatile("s_waitcnt vmcnt(" #n ")" ::: "memory")
; #define PG8_WAIT_L(n) asm volatile("s_waitcnt lgkmcnt(" #n ")" ::: "memory")
; #define PG8_BAR __builtin_amdgcn_s_barrier()
; #define PG8_SCHED __builtin_amdgcn_sched_barrier(0)
; template <class Epi, class Sched, bool ALIGN_EPI>
; __device__ __forceinline__ void gemm_phase(LAS unsigned char* lds, const Gemm g, const Sched& S, const Epi& E) {
;     ...
;             PG8_LDB(B0, 0, 0); PG8_LDB(B1, 0, 1); PG8_SCHED; PG8_LDA(At, 0, 0); PG8_STAGE(PG8_SA(1, 1), a1 + hstepA, voffA);
;             PG8_WAIT_V(8); PG8_WAIT_L(0); PG8_BAR; PG8_MMA(0, 0, At, B0); PG8_MMA(0, 1, At, B1); PG8_BAR; PG8_SCHED;
;             PG8_LDA(At, 0, 1); PG8_STAGE(PG8_SB(0, 0), b2, voffB); PG8_STAGE(PG8_SB(0, 1), b2 + hstepB, voffB); PG8_STAGE(PG8_SA(0, 0), a2, voffA);
;             PG8_WAIT_V(8); PG8_WAIT_L(0); PG8_BAR; PG8_MMA(1, 0, At, B0); PG8_MMA(1, 1, At, B1); PG8_BAR; PG8_SCHED;
;             PG8_LDB(B0, 1, 0); PG8_LDB(B1, 1, 1); PG8_SCHED; PG8_LDA(At, 1, 0); PG8_STAGE(PG8_SA(0, 1), a2 + hstepA, voffA);
;             PG8_WAIT_V(8); PG8_WAIT_L(0); PG8_BAR; PG8_MMA(0, 0, At, B0); PG8_MMA(0, 1, At, B1); PG8_BAR; PG8_SCHED;
;             PG8_LDA(At, 1, 1); PG8_STAGE(PG8_SB(1, 0), b3, voffB); PG8_STAGE(PG8_SB(1, 1), b3 + hstepB, voffB); PG8_STAGE(PG8_SA(1, 0), a3, voffA);
;             PG8_WAIT_V(8); PG8_WAIT_L(0); PG8_BAR; PG8_MMA(1, 0, At, B0); PG8_MMA(1, 1, At, B1); PG8_BAR; PG8_SCHED;
;         }
;         if constexpr (ALIGN_EPI) { if (wr == 0) PG8_BAR; }
	ds_read_b128 v[184:187], v153 offset:49152
	ds_read_b128 v[188:191], v153 offset:50176
	ds_read_b128 v[192:195], v153 offset:51200
	ds_read_b128 v[196:199], v153 offset:52224
	ds_read_b128 v[200:203], v153 offset:53248
	ds_read_b128 v[204:207], v153 offset:54272
	ds_read_b128 v[208:211], v153 offset:55296
	ds_read_b128 v[212:215], v153 offset:56320
	s_mov_b32 m0, s64
	s_nop 0
	global_load_lds_dwordx4 v145, s[38:39]
	s_mov_b32 m0, s65
	s_nop 0
	global_load_lds_dwordx4 v147, s[38:39]
	s_mov_b32 m0, s68
	s_nop 0
	global_load_lds_dwordx4 v145, s[50:51]
	s_mov_b32 m0, s69
	s_nop 0
	global_load_lds_dwordx4 v147, s[50:51]
	s_mov_b32 m0, s66
	s_nop 0
	global_load_lds_dwordx4 v144, s[40:41]
	s_mov_b32 m0, s67
	s_nop 0
	global_load_lds_dwordx4 v146, s[40:41]
	s_waitcnt vmcnt(8)
	s_waitcnt lgkmcnt(0)
	s_barrier
	s_setprio 1
	v_mfma_f32_16x16x32_bf16 v[94:97], v[130:133], v[184:187], v[94:97]
	v_mfma_f32_16x16x32_bf16 v[90:93], v[156:159], v[184:187], v[90:93]
	v_mfma_f32_16x16x32_bf16 v[86:89], v[130:133], v[192:195], v[86:89]
	v_mfma_f32_16x16x32_bf16 v[82:85], v[156:159], v[192:195], v[82:85]
	v_mfma_f32_16x16x32_bf16 v[78:81], v[130:133], v[200:203], v[78:81]
	v_mfma_f32_16x16x32_bf16 v[74:77], v[156:159], v[200:203], v[74:77]
	v_mfma_f32_16x16x32_bf16 v[62:65], v[130:133], v[208:211], v[62:65]
	v_mfma_f32_16x16x32_bf16 v[54:57], v[156:159], v[208:211], v[54:57]
	v_mfma_f32_16x16x32_bf16 v[94:97], v[134:137], v[188:191], v[94:97]
	v_mfma_f32_16x16x32_bf16 v[90:93], v[160:163], v[188:191], v[90:93]
	v_mfma_f32_16x16x32_bf16 v[86:89], v[134:137], v[196:199], v[86:89]
	v_mfma_f32_16x16x32_bf16 v[82:85], v[160:163], v[196:199], v[82:85]
	v_mfma_f32_16x16x32_bf16 v[78:81], v[134:137], v[204:207], v[78:81]
	v_mfma_f32_16x16x32_bf16 v[74:77], v[160:163], v[204:207], v[74:77]
	v_mfma_f32_16x16x32_bf16 v[62:65], v[134:137], v[212:215], v[62:65]
	v_mfma_f32_16x16x32_bf16 v[54:57], v[160:163], v[212:215], v[54:57]
	v_mfma_f32_16x16x32_bf16 v[30:33], v[164:167], v[184:187], v[30:33]
	v_mfma_f32_16x16x32_bf16 v[26:29], v[172:175], v[184:187], v[26:29]
	v_mfma_f32_16x16x32_bf16 v[22:25], v[164:167], v[192:195], v[22:25]
	v_mfma_f32_16x16x32_bf16 v[18:21], v[172:175], v[192:195], v[18:21]
	v_mfma_f32_16x16x32_bf16 v[14:17], v[164:167], v[200:203], v[14:17]
	v_mfma_f32_16x16x32_bf16 v[10:13], v[172:175], v[200:203], v[10:13]
	v_mfma_f32_16x16x32_bf16 v[6:9], v[164:167], v[208:211], v[6:9]
	v_mfma_f32_16x16x32_bf16 v[2:5], v[172:175], v[208:211], v[2:5]
	v_mfma_f32_16x16x32_bf16 v[30:33], v[168:171], v[188:191], v[30:33]
	v_mfma_f32_16x16x32_bf16 v[26:29], v[180:183], v[188:191], v[26:29]
	v_mfma_f32_16x16x32_bf16 v[22:25], v[168:171], v[196:199], v[22:25]
	v_mfma_f32_16x16x32_bf16 v[18:21], v[180:183], v[196:199], v[18:21]
	v_mfma_f32_16x16x32_bf16 v[14:17], v[168:171], v[204:207], v[14:17]
	v_mfma_f32_16x16x32_bf16 v[10:13], v[180:183], v[204:207], v[10:13]
	v_mfma_f32_16x16x32_bf16 v[6:9], v[168:171], v[212:215], v[6:9]
	v_mfma_f32_16x16x32_bf16 v[2:5], v[180:183], v[212:215], v[2:5]
	s_setprio 0
	s_barrier
	s_andn2_b64 vcc, exec, s[36:37]
	s_mov_b64 s[38:39], -1
	s_mov_b64 s[36:37], 0
	s_mov_b64 s[40:41], 0x100
	s_cbranch_vccz .LBB0_805
	s_and_b64 vcc, exec, s[12:13]
	s_cbranch_vccz .LBB0_808
	s_barrier

; #define PG8_STAGE(bufoff, gbase, voff) do { _Pragma("unroll") for (int _i = 0; _i < 2; ++_i) { unsigned keep_; \
;         asm volatile("s_mov_b32 %0, m0\n\ts_mov_b32 m0, %3\n\ts_nop 0\n\tglobal_load_lds_dwordx4 %1, %2\n\ts_mov_b32 m0, %0" \
;             : "=&s"(keep_) : "v"((voff)[_i]), "s"((const void*)(gbase)), "s"(ldsb0 + (unsigned)(bufoff) + (unsigned)(_i * 8192)) : "memory"); } } while (0)
; #define PG8_LDA(dst, b, h) do { _Pragma("unroll") for (int m = 0; m < 4; ++m) _Pragma("unroll") for (int k = 0; k < 2; ++k) dst[m][k] = *(const LAS bf16x8*)(lds + PG8_SA(b, h) + aoff + m * 2048 + k * 1024); } while (0)
; #define PG8_LDB(dst, b, h) do { _Pragma("unroll") for (int n = 0; n < 2; ++n) _Pragma("unroll") for (int k = 0; k < 2; ++k) dst[n][k] = *(const LAS bf16x8*)(lds + PG8_SB(b, h) + boff + n * 2048 + k * 1024); } while (0)
; #define PG8_WAIT_V(n) asm volatile("s_waitcnt vmcnt(" #n ")" ::: "memory")
; #define PG8_WAIT_L(n) asm volatile("s_waitcnt lgkmcnt(" #n ")" ::: "memory")
; #define PG8_BAR __builtin_amdgcn_s_barrier()
; #define PG8_SCHED __builtin_amdgcn_sched_barrier(0)
; template <class Epi, class Sched, bool ALIGN_EPI>
; __device__ __forceinline__ void gemm_phase(LAS unsigned char* lds, const Gemm g, const Sched& S, const Epi& E) {
;     ...
;             PG8_LDB(B0, 0, 0); PG8_LDB(B1, 0, 1); PG8_SCHED; PG8_LDA(At, 0, 0); PG8_STAGE(PG8_SA(1, 1), a1 + hstepA, voffA);
;             PG8_WAIT_V(8); PG8_WAIT_L(0); PG8_BAR; PG8_MMA(0, 0, At, B0); PG8_MMA(0, 1, At, B1); PG8_BAR; PG8_SCHED;
;             PG8_LDA(At, 0, 1); PG8_STAGE(PG8_SB(0, 0), b2, voffB); PG8_STAGE(PG8_SB(0, 1), b2 + hstepB, voffB); PG8_STAGE(PG8_SA(0, 0), a2, voffA);
;             PG8_WAIT_V(8); PG8_WAIT_L(0); PG8_BAR; PG8_MMA(1, 0, At, B0); PG8_MMA(1, 1, At, B1); PG8_BAR; PG8_SCHED;
;             PG8_LDB(B0, 1, 0); PG8_LDB(B1, 1, 1); PG8_SCHED; PG8_LDA(At, 1, 0); PG8_STAGE(PG8_SA(0, 1), a2 + hstepA, voffA);
;             PG8_WAIT_V(8); PG8_WAIT_L(0); PG8_BAR; PG8_MMA(0, 0, At, B0); PG8_MMA(0, 1, At, B1); PG8_BAR; PG8_SCHED;
;             PG8_LDA(At, 1, 1); PG8_STAGE(PG8_SB(1, 0), b3, voffB); PG8_STAGE(PG8_SB(1, 1), b3 + hstepB, voffB); PG8_STAGE(PG8_SA(1, 0), a3, voffA);
;             PG8_WAIT_V(8); PG8_WAIT_L(0); PG8_BAR; PG8_MMA(1, 0, At, B0); PG8_MMA(1, 1, At, B1); PG8_BAR; PG8_SCHED;
.LBB0_1137:
	ds_read_b128 v[110:113], v206
	ds_read_b128 v[126:129], v206 offset:1024
	ds_read_b128 v[130:133], v206 offset:2048
	ds_read_b128 v[142:145], v206 offset:3072
	ds_read_b128 v[146:149], v207
	ds_read_b128 v[150:153], v207 offset:1024
	ds_read_b128 v[154:157], v207 offset:2048
	ds_read_b128 v[158:161], v207 offset:3072
	s_cmp_eq_u32 s63, 28
	s_cselect_b32 s40, s5, s19
	s_cselect_b32 s41, s3, s27
	s_cselect_b32 s38, s7, s61
	s_cselect_b32 s39, s6, s62
	s_add_u32 s36, s40, 0x80
	s_addc_u32 s37, s41, 0
	ds_read_b128 v[162:165], v208
	ds_read_b128 v[166:169], v208 offset:1024
	ds_read_b128 v[170:173], v208 offset:2048
	ds_read_b128 v[174:177], v208 offset:3072
	ds_read_b128 v[188:191], v208 offset:4096
	ds_read_b128 v[192:195], v208 offset:5120
	ds_read_b128 v[196:199], v208 offset:6144
	ds_read_b128 v[212:215], v208 offset:7168
	s_mov_b32 m0, s58
	s_nop 0
	global_load_lds_dwordx4 v179, s[34:35]
	s_mov_b32 m0, s59
	s_nop 0
	global_load_lds_dwordx4 v201, s[34:35]
	s_waitcnt vmcnt(8)
	s_waitcnt lgkmcnt(0)
	s_barrier
	s_setprio 1
	v_mfma_f32_16x16x32_bf16 v[138:141], v[110:113], v[162:165], v[138:141]
	v_mfma_f32_16x16x32_bf16 v[134:137], v[130:133], v[162:165], v[134:137]
	v_mfma_f32_16x16x32_bf16 v[114:117], v[110:113], v[170:173], v[114:117]
	v_mfma_f32_16x16x32_bf16 v[106:109], v[130:133], v[170:173], v[106:109]
	v_mfma_f32_16x16x32_bf16 v[94:97], v[110:113], v[188:191], v[94:97]
	v_mfma_f32_16x16x32_bf16 v[90:93], v[130:133], v[188:191], v[90:93]
	v_mfma_f32_16x16x32_bf16 v[78:81], v[110:113], v[196:199], v[78:81]
	v_mfma_f32_16x16x32_bf16 v[74:77], v[130:133], v[196:199], v[74:77]
	v_mfma_f32_16x16x32_bf16 v[138:141], v[126:129], v[166:169], v[138:141]
	v_mfma_f32_16x16x32_bf16 v[134:137], v[142:145], v[166:169], v[134:137]
	v_mfma_f32_16x16x32_bf16 v[114:117], v[126:129], v[174:177], v[114:117]
	v_mfma_f32_16x16x32_bf16 v[106:109], v[142:145], v[174:177], v[106:109]
	v_mfma_f32_16x16x32_bf16 v[94:97], v[126:129], v[192:195], v[94:97]
	v_mfma_f32_16x16x32_bf16 v[90:93], v[142:145], v[192:195], v[90:93]
	v_mfma_f32_16x16x32_bf16 v[78:81], v[126:129], v[212:215], v[78:81]
	v_mfma_f32_16x16x32_bf16 v[74:77], v[142:145], v[212:215], v[74:77]
	v_mfma_f32_16x16x32_bf16 v[122:125], v[146:149], v[162:165], v[122:125]
	v_mfma_f32_16x16x32_bf16 v[118:121], v[154:157], v[162:165], v[118:121]
	v_mfma_f32_16x16x32_bf16 v[102:105], v[146:149], v[170:173], v[102:105]
	v_mfma_f32_16x16x32_bf16 v[98:101], v[154:157], v[170:173], v[98:101]
	v_mfma_f32_16x16x32_bf16 v[86:89], v[146:149], v[188:191], v[86:89]
	v_mfma_f32_16x16x32_bf16 v[82:85], v[154:157], v[188:191], v[82:85]
	v_mfma_f32_16x16x32_bf16 v[70:73], v[146:149], v[196:199], v[70:73]
	v_mfma_f32_16x16x32_bf16 v[66:69], v[154:157], v[196:199], v[66:69]
	v_mfma_f32_16x16x32_bf16 v[122:125], v[150:153], v[166:169], v[122:125]
	v_mfma_f32_16x16x32_bf16 v[118:121], v[158:161], v[166:169], v[118:121]
	v_mfma_f32_16x16x32_bf16 v[102:105], v[150:153], v[174:177], v[102:105]
	v_mfma_f32_16x16x32_bf16 v[98:101], v[158:161], v[174:177], v[98:101]
	v_mfma_f32_16x16x32_bf16 v[86:89], v[150:153], v[192:195], v[86:89]
	v_mfma_f32_16x16x32_bf16 v[82:85], v[158:161], v[192:195], v[82:85]
	v_mfma_f32_16x16x32_bf16 v[70:73], v[150:153], v[212:215], v[70:73]
	v_mfma_f32_16x16x32_bf16 v[66:69], v[158:161], v[212:215], v[66:69]
	s_setprio 0
	s_barrier
	ds_read_b128 v[162:165], v208 offset:16384
	ds_read_b128 v[166:169], v208 offset:17408
	ds_read_b128 v[170:173], v208 offset:18432
	ds_read_b128 v[174:177], v208 offset:19456
	ds_read_b128 v[188:191], v208 offset:20480
	ds_read_b128 v[192:195], v208 offset:21504
	ds_read_b128 v[196:199], v208 offset:22528
	ds_read_b128 v[212:215], v208 offset:23552
	s_mov_b32 m0, s45
	s_nop 0
	global_load_lds_dwordx4 v200, s[38:39]
	s_mov_b32 m0, s46
	s_nop 0
	global_load_lds_dwordx4 v203, s[38:39]
	s_add_u32 s64, s38, 0x80000
	s_addc_u32 s65, s39, 0
	s_mov_b32 m0, s47
	s_nop 0
	global_load_lds_dwordx4 v200, s[64:65]
	s_mov_b32 m0, s48
	s_nop 0
	global_load_lds_dwordx4 v203, s[64:65]
	s_mov_b32 m0, s44
	s_nop 0
	global_load_lds_dwordx4 v179, s[40:41]
	s_mov_b32 m0, s49
	s_nop 0
	global_load_lds_dwordx4 v201, s[40:41]
	s_waitcnt vmcnt(8)
	s_waitcnt lgkmcnt(0)
	s_barrier
	s_setprio 1
	v_mfma_f32_16x16x32_bf16 v[62:65], v[110:113], v[162:165], v[62:65]
	v_mfma_f32_16x16x32_bf16 v[58:61], v[130:133], v[162:165], v[58:61]
	v_mfma_f32_16x16x32_bf16 v[46:49], v[110:113], v[170:173], v[46:49]
	v_mfma_f32_16x16x32_bf16 v[42:45], v[130:133], v[170:173], v[42:45]
	v_mfma_f32_16x16x32_bf16 v[30:33], v[110:113], v[188:191], v[30:33]
	v_mfma_f32_16x16x32_bf16 v[26:29], v[130:133], v[188:191], v[26:29]
	v_mfma_f32_16x16x32_bf16 v[14:17], v[110:113], v[196:199], v[14:17]
	v_mfma_f32_16x16x32_bf16 v[10:13], v[130:133], v[196:199], v[10:13]
	v_mfma_f32_16x16x32_bf16 v[62:65], v[126:129], v[166:169], v[62:65]
	v_mfma_f32_16x16x32_bf16 v[58:61], v[142:145], v[166:169], v[58:61]
	v_mfma_f32_16x16x32_bf16 v[46:49], v[126:129], v[174:177], v[46:49]
	v_mfma_f32_16x16x32_bf16 v[42:45], v[142:145], v[174:177], v[42:45]
	v_mfma_f32_16x16x32_bf16 v[30:33], v[126:129], v[192:195], v[30:33]
	v_mfma_f32_16x16x32_bf16 v[26:29], v[142:145], v[192:195], v[26:29]
	v_mfma_f32_16x16x32_bf16 v[14:17], v[126:129], v[212:215], v[14:17]
	v_mfma_f32_16x16x32_bf16 v[10:13], v[142:145], v[212:215], v[10:13]
	v_mfma_f32_16x16x32_bf16 v[54:57], v[146:149], v[162:165], v[54:57]
	v_mfma_f32_16x16x32_bf16 v[50:53], v[154:157], v[162:165], v[50:53]
	v_mfma_f32_16x16x32_bf16 v[38:41], v[146:149], v[170:173], v[38:41]
	v_mfma_f32_16x16x32_bf16 v[34:37], v[154:157], v[170:173], v[34:37]
	v_mfma_f32_16x16x32_bf16 v[22:25], v[146:149], v[188:191], v[22:25]
	v_mfma_f32_16x16x32_bf16 v[18:21], v[154:157], v[188:191], v[18:21]
	v_mfma_f32_16x16x32_bf16 v[6:9], v[146:149], v[196:199], v[6:9]
	v_mfma_f32_16x16x32_bf16 v[2:5], v[154:157], v[196:199], v[2:5]
	v_mfma_f32_16x16x32_bf16 v[54:57], v[150:153], v[166:169], v[54:57]
	v_mfma_f32_16x16x32_bf16 v[50:53], v[158:161], v[166:169], v[50:53]
	v_mfma_f32_16x16x32_bf16 v[38:41], v[150:153], v[174:177], v[38:41]
	v_mfma_f32_16x16x32_bf16 v[34:37], v[158:161], v[174:177], v[34:37]
	v_mfma_f32_16x16x32_bf16 v[22:25], v[150:153], v[192:195], v[22:25]
	v_mfma_f32_16x16x32_bf16 v[18:21], v[158:161], v[192:195], v[18:21]
	v_mfma_f32_16x16x32_bf16 v[6:9], v[150:153], v[212:215], v[6:9]
	v_mfma_f32_16x16x32_bf16 v[2:5], v[158:161], v[212:215], v[2:5]
	s_setprio 0
	s_barrier
; #define PG8_STAGE(bufoff, gbase, voff) do { _Pragma("unroll") for (int _i = 0; _i < 2; ++_i) { unsigned keep_; \
;         asm volatile("s_mov_b32 %0, m0\n\ts_mov_b32 m0, %3\n\ts_nop 0\n\tglobal_load_lds_dwordx4 %1, %2\n\ts_mov_b32 m0, %0" \
;             : "=&s"(keep_) : "v"((voff)[_i]), "s"((const void*)(gbase)), "s"(ldsb0 + (unsigned)(bufoff) + (unsigned)(_i * 8192)) : "memory"); } } while (0)
; #define PG8_LDA(dst, b, h) do { _Pragma("unroll") for (int m = 0; m < 4; ++m) _Pragma("unroll") for (int k = 0; k < 2; ++k) dst[m][k] = *(const LAS bf16x8*)(lds + PG8_SA(b, h) + aoff + m * 2048 + k * 1024); } while (0)
; #define PG8_LDB(dst, b, h) do { _Pragma("unroll") for (int n = 0; n < 2; ++n) _Pragma("unroll") for (int k = 0; k < 2; ++k) dst[n][k] = *(const LAS bf16x8*)(lds + PG8_SB(b, h) + boff + n * 2048 + k * 1024); } while (0)
; #define PG8_WAIT_V(n) asm volatile("s_waitcnt vmcnt(" #n ")" ::: "memory")
; #define PG8_WAIT_L(n) asm volatile("s_waitcnt lgkmcnt(" #n ")" ::: "memory")
; #define PG8_BAR __builtin_amdgcn_s_barrier()
; #define PG8_SCHED __builtin_amdgcn_sched_barrier(0)
; template <class Epi, class Sched, bool ALIGN_EPI>
; __device__ __forceinline__ void gemm_phase(LAS unsigned char* lds, const Gemm g, const Sched& S, const Epi& E) {
;     ...
;             PG8_LDB(B0, 0, 0); PG8_LDB(B1, 0, 1); PG8_SCHED; PG8_LDA(At, 0, 0); PG8_STAGE(PG8_SA(1, 1), a1 + hstepA, voffA);
;             PG8_WAIT_V(8); PG8_WAIT_L(0); PG8_BAR; PG8_MMA(0, 0, At, B0); PG8_MMA(0, 1, At, B1); PG8_BAR; PG8_SCHED;
;             PG8_LDA(At, 0, 1); PG8_STAGE(PG8_SB(0, 0), b2, voffB); PG8_STAGE(PG8_SB(0, 1), b2 + hstepB, voffB); PG8_STAGE(PG8_SA(0, 0), a2, voffA);
;             PG8_WAIT_V(8); PG8_WAIT_L(0); PG8_BAR; PG8_MMA(1, 0, At, B0); PG8_MMA(1, 1, At, B1); PG8_BAR; PG8_SCHED;
;             PG8_LDB(B0, 1, 0); PG8_LDB(B1, 1, 1); PG8_SCHED; PG8_LDA(At, 1, 0); PG8_STAGE(PG8_SA(0, 1), a2 + hstepA, voffA);
;             PG8_WAIT_V(8); PG8_WAIT_L(0); PG8_BAR; PG8_MMA(0, 0, At, B0); PG8_MMA(0, 1, At, B1); PG8_BAR; PG8_SCHED;
;             PG8_LDA(At, 1, 1); PG8_STAGE(PG8_SB(1, 0), b3, voffB); PG8_STAGE(PG8_SB(1, 1), b3 + hstepB, voffB); PG8_STAGE(PG8_SA(1, 0), a3, voffA);
;             PG8_WAIT_V(8); PG8_WAIT_L(0); PG8_BAR; PG8_MMA(1, 0, At, B0); PG8_MMA(1, 1, At, B1); PG8_BAR; PG8_SCHED;
;         }
;         if constexpr (ALIGN_EPI) { if (wr == 0) PG8_BAR; }
	ds_read_b128 v[110:113], v209
	ds_read_b128 v[126:129], v209 offset:1024
	ds_read_b128 v[130:133], v209 offset:2048
	ds_read_b128 v[142:145], v209 offset:3072
	ds_read_b128 v[146:149], v210
	ds_read_b128 v[150:153], v210 offset:1024
	ds_read_b128 v[154:157], v210 offset:2048
	ds_read_b128 v[158:161], v210 offset:3072
	ds_read_b128 v[162:165], v208 offset:32768
	ds_read_b128 v[166:169], v208 offset:33792
	ds_read_b128 v[170:173], v208 offset:34816
	ds_read_b128 v[174:177], v208 offset:35840
	ds_read_b128 v[188:191], v208 offset:36864
	ds_read_b128 v[192:195], v208 offset:37888
	ds_read_b128 v[196:199], v208 offset:38912
	ds_read_b128 v[212:215], v208 offset:39936
	s_add_u32 s40, s40, 0x80000
	s_addc_u32 s41, s41, 0
	s_mov_b32 m0, s50
	s_nop 0
	global_load_lds_dwordx4 v179, s[40:41]
	s_mov_b32 m0, s51
	s_nop 0
	global_load_lds_dwordx4 v201, s[40:41]
	s_waitcnt vmcnt(8)
	s_waitcnt lgkmcnt(0)
	s_barrier
	s_setprio 1
	v_mfma_f32_16x16x32_bf16 v[138:141], v[110:113], v[162:165], v[138:141]
	v_mfma_f32_16x16x32_bf16 v[134:137], v[130:133], v[162:165], v[134:137]
	v_mfma_f32_16x16x32_bf16 v[114:117], v[110:113], v[170:173], v[114:117]
	v_mfma_f32_16x16x32_bf16 v[106:109], v[130:133], v[170:173], v[106:109]
	v_mfma_f32_16x16x32_bf16 v[94:97], v[110:113], v[188:191], v[94:97]
	v_mfma_f32_16x16x32_bf16 v[90:93], v[130:133], v[188:191], v[90:93]
	v_mfma_f32_16x16x32_bf16 v[78:81], v[110:113], v[196:199], v[78:81]
	v_mfma_f32_16x16x32_bf16 v[74:77], v[130:133], v[196:199], v[74:77]
	v_mfma_f32_16x16x32_bf16 v[138:141], v[126:129], v[166:169], v[138:141]
	v_mfma_f32_16x16x32_bf16 v[134:137], v[142:145], v[166:169], v[134:137]
	v_mfma_f32_16x16x32_bf16 v[114:117], v[126:129], v[174:177], v[114:117]
	v_mfma_f32_16x16x32_bf16 v[106:109], v[142:145], v[174:177], v[106:109]
	v_mfma_f32_16x16x32_bf16 v[94:97], v[126:129], v[192:195], v[94:97]
	v_mfma_f32_16x16x32_bf16 v[90:93], v[142:145], v[192:195], v[90:93]
	v_mfma_f32_16x16x32_bf16 v[78:81], v[126:129], v[212:215], v[78:81]
	v_mfma_f32_16x16x32_bf16 v[74:77], v[142:145], v[212:215], v[74:77]
	v_mfma_f32_16x16x32_bf16 v[122:125], v[146:149], v[162:165], v[122:125]
	v_mfma_f32_16x16x32_bf16 v[118:121], v[154:157], v[162:165], v[118:121]
	v_mfma_f32_16x16x32_bf16 v[102:105], v[146:149], v[170:173], v[102:105]
	v_mfma_f32_16x16x32_bf16 v[98:101], v[154:157], v[170:173], v[98:101]
	v_mfma_f32_16x16x32_bf16 v[86:89], v[146:149], v[188:191], v[86:89]
	v_mfma_f32_16x16x32_bf16 v[82:85], v[154:157], v[188:191], v[82:85]
	v_mfma_f32_16x16x32_bf16 v[70:73], v[146:149], v[196:199], v[70:73]
	v_mfma_f32_16x16x32_bf16 v[66:69], v[154:157], v[196:199], v[66:69]
	v_mfma_f32_16x16x32_bf16 v[122:125], v[150:153], v[166:169], v[122:125]
	v_mfma_f32_16x16x32_bf16 v[118:121], v[158:161], v[166:169], v[118:121]
	v_mfma_f32_16x16x32_bf16 v[102:105], v[150:153], v[174:177], v[102:105]
	v_mfma_f32_16x16x32_bf16 v[98:101], v[158:161], v[174:177], v[98:101]
	v_mfma_f32_16x16x32_bf16 v[86:89], v[150:153], v[192:195], v[86:89]
	v_mfma_f32_16x16x32_bf16 v[82:85], v[158:161], v[192:195], v[82:85]
	v_mfma_f32_16x16x32_bf16 v[70:73], v[150:153], v[212:215], v[70:73]
	v_mfma_f32_16x16x32_bf16 v[66:69], v[158:161], v[212:215], v[66:69]
	s_setprio 0
	s_barrier
	ds_read_b128 v[162:165], v208 offset:49152
	ds_read_b128 v[166:169], v208 offset:50176
	ds_read_b128 v[170:173], v208 offset:51200
	ds_read_b128 v[174:177], v208 offset:52224
	ds_read_b128 v[188:191], v208 offset:53248
	ds_read_b128 v[192:195], v208 offset:54272
	ds_read_b128 v[196:199], v208 offset:55296
	ds_read_b128 v[212:215], v208 offset:56320
	s_add_u32 s40, s38, 0x80
	s_addc_u32 s41, s39, 0
	s_mov_b32 m0, s52
	s_nop 0
	global_load_lds_dwordx4 v200, s[40:41]
	s_add_u32 s38, s38, 0x80080
	s_mov_b32 m0, s53
	s_nop 0
	global_load_lds_dwordx4 v203, s[40:41]
	s_addc_u32 s39, s39, 0
	s_mov_b32 m0, s56
	s_nop 0
	global_load_lds_dwordx4 v200, s[38:39]
	s_mov_b32 m0, s57
	s_nop 0
	global_load_lds_dwordx4 v203, s[38:39]
	s_mov_b32 m0, s54
	s_nop 0
	global_load_lds_dwordx4 v179, s[36:37]
	s_mov_b32 m0, s55
	s_nop 0
	global_load_lds_dwordx4 v201, s[36:37]
	s_waitcnt vmcnt(8)
	s_waitcnt lgkmcnt(0)
	s_barrier
	s_setprio 1
	v_mfma_f32_16x16x32_bf16 v[62:65], v[110:113], v[162:165], v[62:65]
	v_mfma_f32_16x16x32_bf16 v[58:61], v[130:133], v[162:165], v[58:61]
	v_mfma_f32_16x16x32_bf16 v[46:49], v[110:113], v[170:173], v[46:49]
	v_mfma_f32_16x16x32_bf16 v[42:45], v[130:133], v[170:173], v[42:45]
	v_mfma_f32_16x16x32_bf16 v[30:33], v[110:113], v[188:191], v[30:33]
	v_mfma_f32_16x16x32_bf16 v[26:29], v[130:133], v[188:191], v[26:29]
	v_mfma_f32_16x16x32_bf16 v[14:17], v[110:113], v[196:199], v[14:17]
	v_mfma_f32_16x16x32_bf16 v[10:13], v[130:133], v[196:199], v[10:13]
	v_mfma_f32_16x16x32_bf16 v[62:65], v[126:129], v[166:169], v[62:65]
	v_mfma_f32_16x16x32_bf16 v[58:61], v[142:145], v[166:169], v[58:61]
	v_mfma_f32_16x16x32_bf16 v[46:49], v[126:129], v[174:177], v[46:49]
	v_mfma_f32_16x16x32_bf16 v[42:45], v[142:145], v[174:177], v[42:45]
	v_mfma_f32_16x16x32_bf16 v[30:33], v[126:129], v[192:195], v[30:33]
	v_mfma_f32_16x16x32_bf16 v[26:29], v[142:145], v[192:195], v[26:29]
	v_mfma_f32_16x16x32_bf16 v[14:17], v[126:129], v[212:215], v[14:17]
	v_mfma_f32_16x16x32_bf16 v[10:13], v[142:145], v[212:215], v[10:13]
	v_mfma_f32_16x16x32_bf16 v[54:57], v[146:149], v[162:165], v[54:57]
	v_mfma_f32_16x16x32_bf16 v[50:53], v[154:157], v[162:165], v[50:53]
	v_mfma_f32_16x16x32_bf16 v[38:41], v[146:149], v[170:173], v[38:41]
	v_mfma_f32_16x16x32_bf16 v[34:37], v[154:157], v[170:173], v[34:37]
	v_mfma_f32_16x16x32_bf16 v[22:25], v[146:149], v[188:191], v[22:25]
	v_mfma_f32_16x16x32_bf16 v[18:21], v[154:157], v[188:191], v[18:21]
	v_mfma_f32_16x16x32_bf16 v[6:9], v[146:149], v[196:199], v[6:9]
	v_mfma_f32_16x16x32_bf16 v[2:5], v[154:157], v[196:199], v[2:5]
	v_mfma_f32_16x16x32_bf16 v[54:57], v[150:153], v[166:169], v[54:57]
	v_mfma_f32_16x16x32_bf16 v[50:53], v[158:161], v[166:169], v[50:53]
	v_mfma_f32_16x16x32_bf16 v[38:41], v[150:153], v[174:177], v[38:41]
	v_mfma_f32_16x16x32_bf16 v[34:37], v[158:161], v[174:177], v[34:37]
	v_mfma_f32_16x16x32_bf16 v[22:25], v[150:153], v[192:195], v[22:25]
	v_mfma_f32_16x16x32_bf16 v[18:21], v[158:161], v[192:195], v[18:21]
	v_mfma_f32_16x16x32_bf16 v[6:9], v[150:153], v[212:215], v[6:9]
	v_mfma_f32_16x16x32_bf16 v[2:5], v[158:161], v[212:215], v[2:5]
	s_setprio 0
	s_barrier
	s_add_i32 s63, s63, 2
	s_add_u32 s19, s19, 0x100
	s_addc_u32 s27, s27, 0
	s_add_u32 s61, s61, 0x100
	s_addc_u32 s62, s62, 0
	s_add_u32 s34, s34, 0x100
	s_addc_u32 s35, s35, 0
	s_cmp_gt_u32 s63, 29
	s_cbranch_scc0 .LBB0_1137
	s_and_b64 vcc, exec, s[16:17]
	s_cbranch_vccz .LBB0_1140
	s_barrier

; #define PG8_STAGE(bufoff, gbase, voff) do { _Pragma("unroll") for (int _i = 0; _i < 2; ++_i) { unsigned keep_; \
;         asm volatile("s_mov_b32 %0, m0\n\ts_mov_b32 m0, %3\n\ts_nop 0\n\tglobal_load_lds_dwordx4 %1, %2\n\ts_mov_b32 m0, %0" \
;             : "=&s"(keep_) : "v"((voff)[_i]), "s"((const void*)(gbase)), "s"(ldsb0 + (unsigned)(bufoff) + (unsigned)(_i * 8192)) : "memory"); } } while (0)
; #define PG8_LDA(dst, b, h) do { _Pragma("unroll") for (int m = 0; m < 4; ++m) _Pragma("unroll") for (int k = 0; k < 2; ++k) dst[m][k] = *(const LAS bf16x8*)(lds + PG8_SA(b, h) + aoff + m * 2048 + k * 1024); } while (0)
; #define PG8_LDB(dst, b, h) do { _Pragma("unroll") for (int n = 0; n < 2; ++n) _Pragma("unroll") for (int k = 0; k < 2; ++k) dst[n][k] = *(const LAS bf16x8*)(lds + PG8_SB(b, h) + boff + n * 2048 + k * 1024); } while (0)
; #define PG8_WAIT_V(n) asm volatile("s_waitcnt vmcnt(" #n ")" ::: "memory")
; #define PG8_WAIT_L(n) asm volatile("s_waitcnt lgkmcnt(" #n ")" ::: "memory")
; #define PG8_BAR __builtin_amdgcn_s_barrier()
; #define PG8_SCHED __builtin_amdgcn_sched_barrier(0)
; template <class Epi, class Sched, bool ALIGN_EPI>
; __device__ __forceinline__ void gemm_phase(LAS unsigned char* lds, const Gemm g, const Sched& S, const Epi& E) {
;     ...
;             PG8_LDB(B0, 0, 0); PG8_LDB(B1, 0, 1); PG8_SCHED; PG8_LDA(At, 0, 0); PG8_STAGE(PG8_SA(1, 1), a1 + hstepA, voffA);
;             PG8_WAIT_V(8); PG8_WAIT_L(0); PG8_BAR; PG8_MMA(0, 0, At, B0); PG8_MMA(0, 1, At, B1); PG8_BAR; PG8_SCHED;
;             PG8_LDA(At, 0, 1); PG8_STAGE(PG8_SB(0, 0), b2, voffB); PG8_STAGE(PG8_SB(0, 1), b2 + hstepB, voffB); PG8_STAGE(PG8_SA(0, 0), a2, voffA);
;             PG8_WAIT_V(8); PG8_WAIT_L(0); PG8_BAR; PG8_MMA(1, 0, At, B0); PG8_MMA(1, 1, At, B1); PG8_BAR; PG8_SCHED;
;             PG8_LDB(B0, 1, 0); PG8_LDB(B1, 1, 1); PG8_SCHED; PG8_LDA(At, 1, 0); PG8_STAGE(PG8_SA(0, 1), a2 + hstepA, voffA);
;             PG8_WAIT_V(8); PG8_WAIT_L(0); PG8_BAR; PG8_MMA(0, 0, At, B0); PG8_MMA(0, 1, At, B1); PG8_BAR; PG8_SCHED;
;             PG8_LDA(At, 1, 1); PG8_STAGE(PG8_SB(1, 0), b3, voffB); PG8_STAGE(PG8_SB(1, 1), b3 + hstepB, voffB); PG8_STAGE(PG8_SA(1, 0), a3, voffA);
;             PG8_WAIT_V(8); PG8_WAIT_L(0); PG8_BAR; PG8_MMA(1, 0, At, B0); PG8_MMA(1, 1, At, B1); PG8_BAR; PG8_SCHED;
.LBB0_1218:
	ds_read_b128 v[154:157], v141
	ds_read_b128 v[158:161], v141 offset:1024
	ds_read_b128 v[162:165], v141 offset:2048
	ds_read_b128 v[166:169], v141 offset:3072
	ds_read_b128 v[170:173], v142
	ds_read_b128 v[174:177], v142 offset:1024
	ds_read_b128 v[180:183], v142 offset:2048
	ds_read_b128 v[184:187], v142 offset:3072
	s_add_u32 s36, s34, 0x100
	s_addc_u32 s37, s35, 0
	s_cmp_eq_u32 s64, 28
	s_cselect_b32 s42, s5, s36
	s_cselect_b32 s43, s3, s37
	s_cselect_b32 s40, s7, s19
	s_cselect_b32 s41, s6, s27
	s_add_u32 s38, s42, 0x80
	s_addc_u32 s39, s43, 0
	ds_read_b128 v[188:191], v143
	ds_read_b128 v[192:195], v143 offset:1024
	ds_read_b128 v[196:199], v143 offset:2048
	ds_read_b128 v[204:207], v143 offset:3072
	ds_read_b128 v[208:211], v143 offset:4096
	ds_read_b128 v[212:215], v143 offset:5120
	ds_read_b128 v[216:219], v143 offset:6144
	ds_read_b128 v[220:223], v143 offset:7168
	s_add_u32 s34, s34, 0x80080
	s_addc_u32 s35, s35, 0
	s_mov_b32 m0, s61
	s_nop 0
	global_load_lds_dwordx4 v134, s[34:35]
	s_mov_b32 m0, s62
	s_nop 0
	global_load_lds_dwordx4 v136, s[34:35]
	s_waitcnt vmcnt(8)
	s_waitcnt lgkmcnt(0)
	s_barrier
	s_setprio 1
	v_mfma_f32_16x16x32_bf16 v[126:129], v[154:157], v[188:191], v[126:129]
	v_mfma_f32_16x16x32_bf16 v[122:125], v[162:165], v[188:191], v[122:125]
	v_mfma_f32_16x16x32_bf16 v[110:113], v[154:157], v[196:199], v[110:113]
	v_mfma_f32_16x16x32_bf16 v[106:109], v[162:165], v[196:199], v[106:109]
	v_mfma_f32_16x16x32_bf16 v[94:97], v[154:157], v[208:211], v[94:97]
	v_mfma_f32_16x16x32_bf16 v[90:93], v[162:165], v[208:211], v[90:93]
	v_mfma_f32_16x16x32_bf16 v[78:81], v[154:157], v[216:219], v[78:81]
	v_mfma_f32_16x16x32_bf16 v[74:77], v[162:165], v[216:219], v[74:77]
	v_mfma_f32_16x16x32_bf16 v[126:129], v[158:161], v[192:195], v[126:129]
	v_mfma_f32_16x16x32_bf16 v[122:125], v[166:169], v[192:195], v[122:125]
	v_mfma_f32_16x16x32_bf16 v[110:113], v[158:161], v[204:207], v[110:113]
	v_mfma_f32_16x16x32_bf16 v[106:109], v[166:169], v[204:207], v[106:109]
	v_mfma_f32_16x16x32_bf16 v[94:97], v[158:161], v[212:215], v[94:97]
	v_mfma_f32_16x16x32_bf16 v[90:93], v[166:169], v[212:215], v[90:93]
	v_mfma_f32_16x16x32_bf16 v[78:81], v[158:161], v[220:223], v[78:81]
	v_mfma_f32_16x16x32_bf16 v[74:77], v[166:169], v[220:223], v[74:77]
	v_mfma_f32_16x16x32_bf16 v[118:121], v[170:173], v[188:191], v[118:121]
	v_mfma_f32_16x16x32_bf16 v[114:117], v[180:183], v[188:191], v[114:117]
	v_mfma_f32_16x16x32_bf16 v[102:105], v[170:173], v[196:199], v[102:105]
	v_mfma_f32_16x16x32_bf16 v[98:101], v[180:183], v[196:199], v[98:101]
	v_mfma_f32_16x16x32_bf16 v[86:89], v[170:173], v[208:211], v[86:89]
	v_mfma_f32_16x16x32_bf16 v[82:85], v[180:183], v[208:211], v[82:85]
	v_mfma_f32_16x16x32_bf16 v[70:73], v[170:173], v[216:219], v[70:73]
	v_mfma_f32_16x16x32_bf16 v[66:69], v[180:183], v[216:219], v[66:69]
	v_mfma_f32_16x16x32_bf16 v[118:121], v[174:177], v[192:195], v[118:121]
	v_mfma_f32_16x16x32_bf16 v[114:117], v[184:187], v[192:195], v[114:117]
	v_mfma_f32_16x16x32_bf16 v[102:105], v[174:177], v[204:207], v[102:105]
	v_mfma_f32_16x16x32_bf16 v[98:101], v[184:187], v[204:207], v[98:101]
	v_mfma_f32_16x16x32_bf16 v[86:89], v[174:177], v[212:215], v[86:89]
	v_mfma_f32_16x16x32_bf16 v[82:85], v[184:187], v[212:215], v[82:85]
	v_mfma_f32_16x16x32_bf16 v[70:73], v[174:177], v[220:223], v[70:73]
	v_mfma_f32_16x16x32_bf16 v[66:69], v[184:187], v[220:223], v[66:69]
	s_setprio 0
	s_barrier
	ds_read_b128 v[188:191], v143 offset:16384
	ds_read_b128 v[192:195], v143 offset:17408
	ds_read_b128 v[196:199], v143 offset:18432
	ds_read_b128 v[204:207], v143 offset:19456
	ds_read_b128 v[208:211], v143 offset:20480
	ds_read_b128 v[212:215], v143 offset:21504
	ds_read_b128 v[216:219], v143 offset:22528
	ds_read_b128 v[220:223], v143 offset:23552
	s_mov_b32 m0, s47
	s_nop 0
	global_load_lds_dwordx4 v135, s[40:41]
	s_mov_b32 m0, s48
	s_nop 0
	global_load_lds_dwordx4 v137, s[40:41]
	s_add_u32 s34, s40, 0x80000
	s_addc_u32 s35, s41, 0
	s_mov_b32 m0, s49
	s_nop 0
	global_load_lds_dwordx4 v135, s[34:35]
	s_mov_b32 m0, s50
	s_nop 0
	global_load_lds_dwordx4 v137, s[34:35]
	s_mov_b32 m0, s45
	s_nop 0
	global_load_lds_dwordx4 v134, s[42:43]
	s_mov_b32 m0, s51
	s_nop 0
	global_load_lds_dwordx4 v136, s[42:43]
	s_waitcnt vmcnt(8)
	s_waitcnt lgkmcnt(0)
	s_barrier
	s_setprio 1
	v_mfma_f32_16x16x32_bf16 v[62:65], v[154:157], v[188:191], v[62:65]
	v_mfma_f32_16x16x32_bf16 v[58:61], v[162:165], v[188:191], v[58:61]
	v_mfma_f32_16x16x32_bf16 v[46:49], v[154:157], v[196:199], v[46:49]
	v_mfma_f32_16x16x32_bf16 v[42:45], v[162:165], v[196:199], v[42:45]
	v_mfma_f32_16x16x32_bf16 v[30:33], v[154:157], v[208:211], v[30:33]
	v_mfma_f32_16x16x32_bf16 v[26:29], v[162:165], v[208:211], v[26:29]
	v_mfma_f32_16x16x32_bf16 v[14:17], v[154:157], v[216:219], v[14:17]
	v_mfma_f32_16x16x32_bf16 v[10:13], v[162:165], v[216:219], v[10:13]
	v_mfma_f32_16x16x32_bf16 v[62:65], v[158:161], v[192:195], v[62:65]
	v_mfma_f32_16x16x32_bf16 v[58:61], v[166:169], v[192:195], v[58:61]
	v_mfma_f32_16x16x32_bf16 v[46:49], v[158:161], v[204:207], v[46:49]
	v_mfma_f32_16x16x32_bf16 v[42:45], v[166:169], v[204:207], v[42:45]
	v_mfma_f32_16x16x32_bf16 v[30:33], v[158:161], v[212:215], v[30:33]
	v_mfma_f32_16x16x32_bf16 v[26:29], v[166:169], v[212:215], v[26:29]
	v_mfma_f32_16x16x32_bf16 v[14:17], v[158:161], v[220:223], v[14:17]
	v_mfma_f32_16x16x32_bf16 v[10:13], v[166:169], v[220:223], v[10:13]
	v_mfma_f32_16x16x32_bf16 v[54:57], v[170:173], v[188:191], v[54:57]
	v_mfma_f32_16x16x32_bf16 v[50:53], v[180:183], v[188:191], v[50:53]
	v_mfma_f32_16x16x32_bf16 v[38:41], v[170:173], v[196:199], v[38:41]
	v_mfma_f32_16x16x32_bf16 v[34:37], v[180:183], v[196:199], v[34:37]
	v_mfma_f32_16x16x32_bf16 v[22:25], v[170:173], v[208:211], v[22:25]
	v_mfma_f32_16x16x32_bf16 v[18:21], v[180:183], v[208:211], v[18:21]
	v_mfma_f32_16x16x32_bf16 v[6:9], v[170:173], v[216:219], v[6:9]
	v_mfma_f32_16x16x32_bf16 v[2:5], v[180:183], v[216:219], v[2:5]
	v_mfma_f32_16x16x32_bf16 v[54:57], v[174:177], v[192:195], v[54:57]
	v_mfma_f32_16x16x32_bf16 v[50:53], v[184:187], v[192:195], v[50:53]
	v_mfma_f32_16x16x32_bf16 v[38:41], v[174:177], v[204:207], v[38:41]
	v_mfma_f32_16x16x32_bf16 v[34:37], v[184:187], v[204:207], v[34:37]
	v_mfma_f32_16x16x32_bf16 v[22:25], v[174:177], v[212:215], v[22:25]
	v_mfma_f32_16x16x32_bf16 v[18:21], v[184:187], v[212:215], v[18:21]
	v_mfma_f32_16x16x32_bf16 v[6:9], v[174:177], v[220:223], v[6:9]
	v_mfma_f32_16x16x32_bf16 v[2:5], v[184:187], v[220:223], v[2:5]
	s_setprio 0
	s_barrier
; #define PG8_STAGE(bufoff, gbase, voff) do { _Pragma("unroll") for (int _i = 0; _i < 2; ++_i) { unsigned keep_; \
;         asm volatile("s_mov_b32 %0, m0\n\ts_mov_b32 m0, %3\n\ts_nop 0\n\tglobal_load_lds_dwordx4 %1, %2\n\ts_mov_b32 m0, %0" \
;             : "=&s"(keep_) : "v"((voff)[_i]), "s"((const void*)(gbase)), "s"(ldsb0 + (unsigned)(bufoff) + (unsigned)(_i * 8192)) : "memory"); } } while (0)
; #define PG8_LDA(dst, b, h) do { _Pragma("unroll") for (int m = 0; m < 4; ++m) _Pragma("unroll") for (int k = 0; k < 2; ++k) dst[m][k] = *(const LAS bf16x8*)(lds + PG8_SA(b, h) + aoff + m * 2048 + k * 1024); } while (0)
; #define PG8_LDB(dst, b, h) do { _Pragma("unroll") for (int n = 0; n < 2; ++n) _Pragma("unroll") for (int k = 0; k < 2; ++k) dst[n][k] = *(const LAS bf16x8*)(lds + PG8_SB(b, h) + boff + n * 2048 + k * 1024); } while (0)
; #define PG8_WAIT_V(n) asm volatile("s_waitcnt vmcnt(" #n ")" ::: "memory")
; #define PG8_WAIT_L(n) asm volatile("s_waitcnt lgkmcnt(" #n ")" ::: "memory")
; #define PG8_BAR __builtin_amdgcn_s_barrier()
; #define PG8_SCHED __builtin_amdgcn_sched_barrier(0)
; template <class Epi, class Sched, bool ALIGN_EPI>
; __device__ __forceinline__ void gemm_phase(LAS unsigned char* lds, const Gemm g, const Sched& S, const Epi& E) {
;     ...
;             PG8_LDB(B0, 0, 0); PG8_LDB(B1, 0, 1); PG8_SCHED; PG8_LDA(At, 0, 0); PG8_STAGE(PG8_SA(1, 1), a1 + hstepA, voffA);
;             PG8_WAIT_V(8); PG8_WAIT_L(0); PG8_BAR; PG8_MMA(0, 0, At, B0); PG8_MMA(0, 1, At, B1); PG8_BAR; PG8_SCHED;
;             PG8_LDA(At, 0, 1); PG8_STAGE(PG8_SB(0, 0), b2, voffB); PG8_STAGE(PG8_SB(0, 1), b2 + hstepB, voffB); PG8_STAGE(PG8_SA(0, 0), a2, voffA);
;             PG8_WAIT_V(8); PG8_WAIT_L(0); PG8_BAR; PG8_MMA(1, 0, At, B0); PG8_MMA(1, 1, At, B1); PG8_BAR; PG8_SCHED;
;             PG8_LDB(B0, 1, 0); PG8_LDB(B1, 1, 1); PG8_SCHED; PG8_LDA(At, 1, 0); PG8_STAGE(PG8_SA(0, 1), a2 + hstepA, voffA);
;             PG8_WAIT_V(8); PG8_WAIT_L(0); PG8_BAR; PG8_MMA(0, 0, At, B0); PG8_MMA(0, 1, At, B1); PG8_BAR; PG8_SCHED;
;             PG8_LDA(At, 1, 1); PG8_STAGE(PG8_SB(1, 0), b3, voffB); PG8_STAGE(PG8_SB(1, 1), b3 + hstepB, voffB); PG8_STAGE(PG8_SA(1, 0), a3, voffA);
;             PG8_WAIT_V(8); PG8_WAIT_L(0); PG8_BAR; PG8_MMA(1, 0, At, B0); PG8_MMA(1, 1, At, B1); PG8_BAR; PG8_SCHED;
;         }
;         if constexpr (ALIGN_EPI) { if (wr == 0) PG8_BAR; }
	ds_read_b128 v[154:157], v144
	ds_read_b128 v[158:161], v144 offset:1024
	ds_read_b128 v[162:165], v144 offset:2048
	ds_read_b128 v[166:169], v144 offset:3072
	ds_read_b128 v[170:173], v145
	ds_read_b128 v[174:177], v145 offset:1024
	ds_read_b128 v[180:183], v145 offset:2048
	ds_read_b128 v[184:187], v145 offset:3072
	ds_read_b128 v[188:191], v143 offset:32768
	ds_read_b128 v[192:195], v143 offset:33792
	ds_read_b128 v[196:199], v143 offset:34816
	ds_read_b128 v[204:207], v143 offset:35840
	ds_read_b128 v[208:211], v143 offset:36864
	ds_read_b128 v[212:215], v143 offset:37888
	ds_read_b128 v[216:219], v143 offset:38912
	ds_read_b128 v[220:223], v143 offset:39936
	s_add_u32 s34, s42, 0x80000
	s_addc_u32 s35, s43, 0
	s_mov_b32 m0, s52
	s_nop 0
	global_load_lds_dwordx4 v134, s[34:35]
	s_mov_b32 m0, s53
	s_nop 0
	global_load_lds_dwordx4 v136, s[34:35]
	s_waitcnt vmcnt(8)
	s_waitcnt lgkmcnt(0)
	s_barrier
	s_setprio 1
	v_mfma_f32_16x16x32_bf16 v[126:129], v[154:157], v[188:191], v[126:129]
	v_mfma_f32_16x16x32_bf16 v[122:125], v[162:165], v[188:191], v[122:125]
	v_mfma_f32_16x16x32_bf16 v[110:113], v[154:157], v[196:199], v[110:113]
	v_mfma_f32_16x16x32_bf16 v[106:109], v[162:165], v[196:199], v[106:109]
	v_mfma_f32_16x16x32_bf16 v[94:97], v[154:157], v[208:211], v[94:97]
	v_mfma_f32_16x16x32_bf16 v[90:93], v[162:165], v[208:211], v[90:93]
	v_mfma_f32_16x16x32_bf16 v[78:81], v[154:157], v[216:219], v[78:81]
	v_mfma_f32_16x16x32_bf16 v[74:77], v[162:165], v[216:219], v[74:77]
	v_mfma_f32_16x16x32_bf16 v[126:129], v[158:161], v[192:195], v[126:129]
	v_mfma_f32_16x16x32_bf16 v[122:125], v[166:169], v[192:195], v[122:125]
	v_mfma_f32_16x16x32_bf16 v[110:113], v[158:161], v[204:207], v[110:113]
	v_mfma_f32_16x16x32_bf16 v[106:109], v[166:169], v[204:207], v[106:109]
	v_mfma_f32_16x16x32_bf16 v[94:97], v[158:161], v[212:215], v[94:97]
	v_mfma_f32_16x16x32_bf16 v[90:93], v[166:169], v[212:215], v[90:93]
	v_mfma_f32_16x16x32_bf16 v[78:81], v[158:161], v[220:223], v[78:81]
	v_mfma_f32_16x16x32_bf16 v[74:77], v[166:169], v[220:223], v[74:77]
	v_mfma_f32_16x16x32_bf16 v[118:121], v[170:173], v[188:191], v[118:121]
	v_mfma_f32_16x16x32_bf16 v[114:117], v[180:183], v[188:191], v[114:117]
	v_mfma_f32_16x16x32_bf16 v[102:105], v[170:173], v[196:199], v[102:105]
	v_mfma_f32_16x16x32_bf16 v[98:101], v[180:183], v[196:199], v[98:101]
	v_mfma_f32_16x16x32_bf16 v[86:89], v[170:173], v[208:211], v[86:89]
	v_mfma_f32_16x16x32_bf16 v[82:85], v[180:183], v[208:211], v[82:85]
	v_mfma_f32_16x16x32_bf16 v[70:73], v[170:173], v[216:219], v[70:73]
	v_mfma_f32_16x16x32_bf16 v[66:69], v[180:183], v[216:219], v[66:69]
	v_mfma_f32_16x16x32_bf16 v[118:121], v[174:177], v[192:195], v[118:121]
	v_mfma_f32_16x16x32_bf16 v[114:117], v[184:187], v[192:195], v[114:117]
	v_mfma_f32_16x16x32_bf16 v[102:105], v[174:177], v[204:207], v[102:105]
	v_mfma_f32_16x16x32_bf16 v[98:101], v[184:187], v[204:207], v[98:101]
	v_mfma_f32_16x16x32_bf16 v[86:89], v[174:177], v[212:215], v[86:89]
	v_mfma_f32_16x16x32_bf16 v[82:85], v[184:187], v[212:215], v[82:85]
	v_mfma_f32_16x16x32_bf16 v[70:73], v[174:177], v[220:223], v[70:73]
	v_mfma_f32_16x16x32_bf16 v[66:69], v[184:187], v[220:223], v[66:69]
	s_setprio 0
	s_barrier
	ds_read_b128 v[188:191], v143 offset:49152
	ds_read_b128 v[192:195], v143 offset:50176
	ds_read_b128 v[196:199], v143 offset:51200
	ds_read_b128 v[204:207], v143 offset:52224
	ds_read_b128 v[208:211], v143 offset:53248
	ds_read_b128 v[212:215], v143 offset:54272
	ds_read_b128 v[216:219], v143 offset:55296
	ds_read_b128 v[220:223], v143 offset:56320
	s_add_u32 s34, s40, 0x80
	s_addc_u32 s35, s41, 0
	s_mov_b32 m0, s54
	s_nop 0
	global_load_lds_dwordx4 v135, s[34:35]
	s_mov_b32 m0, s55
	s_nop 0
	global_load_lds_dwordx4 v137, s[34:35]
	s_add_u32 s34, s40, 0x80080
	s_addc_u32 s35, s41, 0
	s_mov_b32 m0, s58
	s_nop 0
	global_load_lds_dwordx4 v135, s[34:35]
	s_mov_b32 m0, s59
	s_nop 0
	global_load_lds_dwordx4 v137, s[34:35]
	s_mov_b32 m0, s56
	s_nop 0
	global_load_lds_dwordx4 v134, s[38:39]
	s_mov_b32 m0, s57
	s_nop 0
	global_load_lds_dwordx4 v136, s[38:39]
	s_waitcnt vmcnt(8)
	s_waitcnt lgkmcnt(0)
	s_barrier
	s_setprio 1
	v_mfma_f32_16x16x32_bf16 v[62:65], v[154:157], v[188:191], v[62:65]
	v_mfma_f32_16x16x32_bf16 v[58:61], v[162:165], v[188:191], v[58:61]
	v_mfma_f32_16x16x32_bf16 v[46:49], v[154:157], v[196:199], v[46:49]
	v_mfma_f32_16x16x32_bf16 v[42:45], v[162:165], v[196:199], v[42:45]
	v_mfma_f32_16x16x32_bf16 v[30:33], v[154:157], v[208:211], v[30:33]
	v_mfma_f32_16x16x32_bf16 v[26:29], v[162:165], v[208:211], v[26:29]
	v_mfma_f32_16x16x32_bf16 v[14:17], v[154:157], v[216:219], v[14:17]
	v_mfma_f32_16x16x32_bf16 v[10:13], v[162:165], v[216:219], v[10:13]
	v_mfma_f32_16x16x32_bf16 v[62:65], v[158:161], v[192:195], v[62:65]
	v_mfma_f32_16x16x32_bf16 v[58:61], v[166:169], v[192:195], v[58:61]
	v_mfma_f32_16x16x32_bf16 v[46:49], v[158:161], v[204:207], v[46:49]
	v_mfma_f32_16x16x32_bf16 v[42:45], v[166:169], v[204:207], v[42:45]
	v_mfma_f32_16x16x32_bf16 v[30:33], v[158:161], v[212:215], v[30:33]
	v_mfma_f32_16x16x32_bf16 v[26:29], v[166:169], v[212:215], v[26:29]
	v_mfma_f32_16x16x32_bf16 v[14:17], v[158:161], v[220:223], v[14:17]
	v_mfma_f32_16x16x32_bf16 v[10:13], v[166:169], v[220:223], v[10:13]
	v_mfma_f32_16x16x32_bf16 v[54:57], v[170:173], v[188:191], v[54:57]
	v_mfma_f32_16x16x32_bf16 v[50:53], v[180:183], v[188:191], v[50:53]
	v_mfma_f32_16x16x32_bf16 v[38:41], v[170:173], v[196:199], v[38:41]
	v_mfma_f32_16x16x32_bf16 v[34:37], v[180:183], v[196:199], v[34:37]
	v_mfma_f32_16x16x32_bf16 v[22:25], v[170:173], v[208:211], v[22:25]
	v_mfma_f32_16x16x32_bf16 v[18:21], v[180:183], v[208:211], v[18:21]
	v_mfma_f32_16x16x32_bf16 v[6:9], v[170:173], v[216:219], v[6:9]
	v_mfma_f32_16x16x32_bf16 v[2:5], v[180:183], v[216:219], v[2:5]
	v_mfma_f32_16x16x32_bf16 v[54:57], v[174:177], v[192:195], v[54:57]
	v_mfma_f32_16x16x32_bf16 v[50:53], v[184:187], v[192:195], v[50:53]
	v_mfma_f32_16x16x32_bf16 v[38:41], v[174:177], v[204:207], v[38:41]
	v_mfma_f32_16x16x32_bf16 v[34:37], v[184:187], v[204:207], v[34:37]
	v_mfma_f32_16x16x32_bf16 v[22:25], v[174:177], v[212:215], v[22:25]
	v_mfma_f32_16x16x32_bf16 v[18:21], v[184:187], v[212:215], v[18:21]
	v_mfma_f32_16x16x32_bf16 v[6:9], v[174:177], v[220:223], v[6:9]
	v_mfma_f32_16x16x32_bf16 v[2:5], v[184:187], v[220:223], v[2:5]
	s_setprio 0
	s_barrier
	s_add_i32 s64, s64, 2
	s_add_u32 s19, s19, 0x100
	s_addc_u32 s27, s27, 0
	s_cmp_gt_u32 s64, 29
	s_mov_b64 s[34:35], s[36:37]
	s_cbranch_scc0 .LBB0_1218
	s_and_b64 vcc, exec, s[16:17]
	s_cbranch_vccz .LBB0_1221
	s_barrier
; __device__ __forceinline__ float fexp2(float x) { return __builtin_amdgcn_exp2f(x); }
; __device__ __forceinline__ void st_bf16x8(bf16* p, f32x4 a, f32x4 b) { *(bf16x8*)p = pack8(a, b); }
; __device__ __forceinline__ float rs_val(float ssqv) { return __builtin_amdgcn_rsqf(ssqv * (1.f / DM) + EPS); }
; __device__ __forceinline__ float swiglu1(float g, float u) { return g * u * __builtin_amdgcn_rcpf(1.f + fexp2(-g * LOG2E)); }
;     __device__ __forceinline__ void operator()(const Acc& acc, const pg8::Unit& u, int wr, int wc, int fr, int fq, const float* rsv) const {
;         const int c = u.pn * 128 + wc * 32 + fq * 8;
; #pragma unroll
;         for (int ai = 0; ai < 2; ++ai)
; #pragma unroll
;             for (int m = 0; m < 4; ++m) { const int row = u.pm * 256 + ai * 128 + wr * 64 + m * 16 + fr; const float rs = rs_val(rsv[ai * 4 + m]);
;                 f32x4 o0, o1;
; #pragma unroll
;                 for (int e = 0; e < 4; ++e) { o0[e] = swiglu1(acc[ai][0][m][0][e] * rs, acc[ai][1][m][0][e] * rs); o1[e] = swiglu1(acc[ai][0][m][1][e] * rs, acc[ai][1][m][1][e] * rs); }
;                 st_bf16x8(ACT + (size_t)row * DFF + c, o0, o1); __builtin_amdgcn_sched_barrier(0); }
;     }
.LBB0_1221:
	s_nop 0
	v_fmamk_f32 v153, v153, 0x3a000000, v146
	v_rsq_f32_e32 v156, v153
	v_mov_b32_e32 v158, v126
	v_mov_b32_e32 v159, v118
	v_mov_b32_e32 v160, v122
	v_pk_mul_f32 v[158:159], v[156:157], v[158:159] op_sel_hi:[0,1]
	v_mov_b32_e32 v161, v114
	v_mul_f32_e32 v118, 0xbfb8aa3b, v158
	v_pk_mul_f32 v[160:161], v[156:157], v[160:161] op_sel_hi:[0,1]
	v_exp_f32_e32 v118, v118
	v_mul_f32_e32 v114, 0xbfb8aa3b, v160
	v_exp_f32_e32 v114, v114
	v_mul_f32_e32 v122, v158, v159
	v_add_f32_e32 v118, 1.0, v118
	v_rcp_f32_e32 v118, v118
	v_add_f32_e32 v114, 1.0, v114
	v_rcp_f32_e32 v114, v114
	v_lshl_or_b32 v154, s2, 7, v140
	v_mul_f32_e32 v126, v118, v122
	v_mul_f32_e32 v118, v160, v161
	v_mul_f32_e32 v157, v114, v118
	v_mov_b32_e32 v118, v127
	v_pk_mul_f32 v[118:119], v[156:157], v[118:119] op_sel_hi:[0,1]
	v_mul_f32_e32 v114, 0xbfb8aa3b, v118
	v_exp_f32_e32 v122, v114
	v_mov_b32_e32 v114, v123
	v_pk_mul_f32 v[114:115], v[156:157], v[114:115] op_sel_hi:[0,1]
	v_mul_f32_e32 v123, 0xbfb8aa3b, v114
	v_exp_f32_e32 v123, v123
	v_mul_f32_e32 v127, v118, v119
	v_add_f32_e32 v118, 1.0, v122
	v_rcp_f32_e32 v122, v118
	v_add_f32_e32 v118, 1.0, v123
	v_rcp_f32_e32 v123, v118
	v_mov_b32_e32 v118, v128
	v_mov_b32_e32 v119, v120
	v_pk_mul_f32 v[118:119], v[156:157], v[118:119] op_sel_hi:[0,1]
	v_mul_f32_e32 v120, 0xbfb8aa3b, v118
	v_exp_f32_e32 v120, v120
	v_mul_f32_e32 v114, v114, v115
	v_mul_f32_e32 v128, v123, v114
	v_mov_b32_e32 v115, v116
	v_add_f32_e32 v114, 1.0, v120
	v_rcp_f32_e32 v120, v114
	v_mov_b32_e32 v114, v124
	v_pk_mul_f32 v[114:115], v[156:157], v[114:115] op_sel_hi:[0,1]
	v_mul_f32_e32 v116, 0xbfb8aa3b, v114
	v_exp_f32_e32 v116, v116
	v_mul_f32_e32 v118, v118, v119
	v_mul_f32_e32 v124, v120, v118
	v_mul_f32_e32 v118, v114, v115
	v_add_f32_e32 v114, 1.0, v116
	v_mov_b32_e32 v120, v129
	v_rcp_f32_e32 v119, v114
	v_pk_mul_f32 v[114:115], v[156:157], v[120:121] op_sel_hi:[0,1]
	v_mul_f32_e32 v116, 0xbfb8aa3b, v114
	v_exp_f32_e32 v120, v116
	v_mov_b32_e32 v116, v125
	v_pk_mul_f32 v[116:117], v[156:157], v[116:117] op_sel_hi:[0,1]
	v_mul_f32_e32 v121, 0xbfb8aa3b, v116
	v_exp_f32_e32 v121, v121
	v_mul_f32_e32 v125, v119, v118
	v_add_f32_e32 v118, 1.0, v120
	v_rcp_f32_e32 v118, v118
	v_add_f32_e32 v119, 1.0, v121
	v_rcp_f32_e32 v119, v119
	v_mul_f32_e32 v114, v114, v115
	v_mul_f32_e32 v120, v118, v114
	v_mul_f32_e32 v114, v116, v117
	v_lshl_add_u32 v153, s4, 8, v138
	v_ashrrev_i32_e32 v155, 31, v154
	v_mul_f32_e32 v121, v119, v114
	v_mov_b64_e32 v[114:115], s[14:15]
	v_mad_i64_i32 v[118:119], s[2:3], v153, s63, v[114:115]
	v_lshlrev_b64 v[116:117], 1, v[154:155]
	v_mul_f32_e32 v127, v122, v127
	v_lshl_add_u64 v[122:123], v[118:119], 0, v[116:117]
	v_cvt_pk_bf16_f32 v118, v126, v127
	v_cvt_pk_bf16_f32 v119, v124, v120
	v_cvt_pk_bf16_f32 v120, v157, v128
	v_cvt_pk_bf16_f32 v121, v125, v121
	global_store_dwordx4 v[122:123], v[118:121], off
	s_nop 0
	s_nop 0
	v_fmamk_f32 v118, v152, 0x3a000000, v146
	v_rsq_f32_e32 v118, v118
	v_mov_b32_e32 v120, v110
	v_mov_b32_e32 v121, v102
	v_mov_b32_e32 v122, v106
	v_pk_mul_f32 v[120:121], v[118:119], v[120:121] op_sel_hi:[0,1]
	v_mov_b32_e32 v123, v98
	v_mul_f32_e32 v102, 0xbfb8aa3b, v120
	v_pk_mul_f32 v[122:123], v[118:119], v[122:123] op_sel_hi:[0,1]
	v_exp_f32_e32 v102, v102
	v_mul_f32_e32 v98, 0xbfb8aa3b, v122
	v_exp_f32_e32 v98, v98
	v_mul_f32_e32 v106, v120, v121
	v_add_f32_e32 v102, 1.0, v102
	v_rcp_f32_e32 v102, v102
	v_add_f32_e32 v98, 1.0, v98
	v_rcp_f32_e32 v98, v98
	v_mul_f32_e32 v106, v102, v106
	v_mul_f32_e32 v102, v122, v123
	v_mul_f32_e32 v110, v98, v102
	v_mov_b32_e32 v102, v111
	v_pk_mul_f32 v[102:103], v[118:119], v[102:103] op_sel_hi:[0,1]
	v_mul_f32_e32 v98, 0xbfb8aa3b, v102
	v_exp_f32_e32 v111, v98
	v_mov_b32_e32 v98, v107
	v_pk_mul_f32 v[98:99], v[118:119], v[98:99] op_sel_hi:[0,1]
	v_mul_f32_e32 v107, 0xbfb8aa3b, v98
	v_exp_f32_e32 v107, v107
	v_mul_f32_e32 v119, v102, v103
	v_add_f32_e32 v102, 1.0, v111
	v_rcp_f32_e32 v111, v102
	v_add_f32_e32 v102, 1.0, v107
	v_rcp_f32_e32 v107, v102
	v_mov_b32_e32 v102, v112
	v_mov_b32_e32 v103, v104
	v_pk_mul_f32 v[102:103], v[118:119], v[102:103] op_sel_hi:[0,1]
	v_mul_f32_e32 v104, 0xbfb8aa3b, v102
	v_exp_f32_e32 v104, v104
	v_mul_f32_e32 v98, v98, v99
	v_mul_f32_e32 v107, v107, v98
	v_mov_b32_e32 v99, v100
	v_add_f32_e32 v98, 1.0, v104
	v_rcp_f32_e32 v104, v98
	v_mov_b32_e32 v98, v108
	v_pk_mul_f32 v[98:99], v[118:119], v[98:99] op_sel_hi:[0,1]
	v_mul_f32_e32 v100, 0xbfb8aa3b, v98
	v_exp_f32_e32 v100, v100
	v_mul_f32_e32 v102, v102, v103
	v_mul_f32_e32 v108, v104, v102
	v_mul_f32_e32 v102, v98, v99
	v_add_f32_e32 v98, 1.0, v100
	v_mov_b32_e32 v104, v113
	v_rcp_f32_e32 v103, v98
	v_pk_mul_f32 v[98:99], v[118:119], v[104:105] op_sel_hi:[0,1]
	v_mul_f32_e32 v100, 0xbfb8aa3b, v98
	v_exp_f32_e32 v104, v100
	v_mov_b32_e32 v100, v109
	v_pk_mul_f32 v[100:101], v[118:119], v[100:101] op_sel_hi:[0,1]
	v_mul_f32_e32 v105, 0xbfb8aa3b, v100
	v_exp_f32_e32 v105, v105
	v_mul_f32_e32 v109, v103, v102
	v_add_f32_e32 v102, 1.0, v104
	v_rcp_f32_e32 v102, v102
	v_add_f32_e32 v103, 1.0, v105
	v_rcp_f32_e32 v103, v103
	v_mul_f32_e32 v98, v98, v99
	v_mul_f32_e32 v104, v102, v98
	v_mul_f32_e32 v98, v100, v101
	v_mul_f32_e32 v101, v103, v98
	v_or_b32_e32 v98, 16, v153
	v_mad_i64_i32 v[98:99], s[2:3], v98, s63, v[114:115]
	v_lshl_add_u64 v[102:103], v[98:99], 0, v[116:117]
	v_mul_f32_e32 v111, v111, v119
	v_cvt_pk_bf16_f32 v98, v106, v111
	v_cvt_pk_bf16_f32 v99, v108, v104
	v_cvt_pk_bf16_f32 v100, v110, v107
	v_cvt_pk_bf16_f32 v101, v109, v101
	global_store_dwordx4 v[102:103], v[98:101], off
	s_nop 0
	s_nop 0
	v_fmamk_f32 v98, v151, 0x3a000000, v146
	v_rsq_f32_e32 v98, v98
; __device__ __forceinline__ float fexp2(float x) { return __builtin_amdgcn_exp2f(x); }
; __device__ __forceinline__ void st_bf16x8(bf16* p, f32x4 a, f32x4 b) { *(bf16x8*)p = pack8(a, b); }
; __device__ __forceinline__ float rs_val(float ssqv) { return __builtin_amdgcn_rsqf(ssqv * (1.f / DM) + EPS); }
; __device__ __forceinline__ float swiglu1(float g, float u) { return g * u * __builtin_amdgcn_rcpf(1.f + fexp2(-g * LOG2E)); }
;     __device__ __forceinline__ void operator()(const Acc& acc, const pg8::Unit& u, int wr, int wc, int fr, int fq, const float* rsv) const {
;         const int c = u.pn * 128 + wc * 32 + fq * 8;
; #pragma unroll
;         for (int ai = 0; ai < 2; ++ai)
; #pragma unroll
;             for (int m = 0; m < 4; ++m) { const int row = u.pm * 256 + ai * 128 + wr * 64 + m * 16 + fr; const float rs = rs_val(rsv[ai * 4 + m]);
;                 f32x4 o0, o1;
; #pragma unroll
;                 for (int e = 0; e < 4; ++e) { o0[e] = swiglu1(acc[ai][0][m][0][e] * rs, acc[ai][1][m][0][e] * rs); o1[e] = swiglu1(acc[ai][0][m][1][e] * rs, acc[ai][1][m][1][e] * rs); }
;                 st_bf16x8(ACT + (size_t)row * DFF + c, o0, o1); __builtin_amdgcn_sched_barrier(0); }
;     }
	v_mov_b32_e32 v100, v94
	v_mov_b32_e32 v101, v86
	v_mov_b32_e32 v102, v90
	v_pk_mul_f32 v[100:101], v[98:99], v[100:101] op_sel_hi:[0,1]
	v_mov_b32_e32 v103, v82
	v_mul_f32_e32 v86, 0xbfb8aa3b, v100
	v_pk_mul_f32 v[102:103], v[98:99], v[102:103] op_sel_hi:[0,1]
	v_exp_f32_e32 v86, v86
	v_mul_f32_e32 v82, 0xbfb8aa3b, v102
	v_exp_f32_e32 v82, v82
	v_mul_f32_e32 v90, v100, v101
	v_add_f32_e32 v86, 1.0, v86
	v_rcp_f32_e32 v86, v86
	v_add_f32_e32 v82, 1.0, v82
	v_rcp_f32_e32 v82, v82
	v_mul_f32_e32 v90, v86, v90
	v_mul_f32_e32 v86, v102, v103
	v_mul_f32_e32 v94, v82, v86
	v_mov_b32_e32 v86, v95
	v_pk_mul_f32 v[86:87], v[98:99], v[86:87] op_sel_hi:[0,1]
	v_mul_f32_e32 v82, 0xbfb8aa3b, v86
	v_exp_f32_e32 v95, v82
	v_mov_b32_e32 v82, v91
	v_pk_mul_f32 v[82:83], v[98:99], v[82:83] op_sel_hi:[0,1]
	v_mul_f32_e32 v91, 0xbfb8aa3b, v82
	v_exp_f32_e32 v91, v91
	v_mul_f32_e32 v99, v86, v87
	v_add_f32_e32 v86, 1.0, v95
	v_rcp_f32_e32 v95, v86
	v_add_f32_e32 v86, 1.0, v91
	v_rcp_f32_e32 v91, v86
	v_mov_b32_e32 v86, v96
	v_mov_b32_e32 v87, v88
	v_pk_mul_f32 v[86:87], v[98:99], v[86:87] op_sel_hi:[0,1]
	v_mul_f32_e32 v88, 0xbfb8aa3b, v86
	v_exp_f32_e32 v88, v88
	v_mul_f32_e32 v82, v82, v83
	v_mul_f32_e32 v91, v91, v82
	v_mov_b32_e32 v83, v84
	v_add_f32_e32 v82, 1.0, v88
	v_rcp_f32_e32 v88, v82
	v_mov_b32_e32 v82, v92
	v_pk_mul_f32 v[82:83], v[98:99], v[82:83] op_sel_hi:[0,1]
	v_mul_f32_e32 v84, 0xbfb8aa3b, v82
	v_exp_f32_e32 v84, v84
	v_mul_f32_e32 v86, v86, v87
	v_mul_f32_e32 v92, v88, v86
	v_mul_f32_e32 v86, v82, v83
	v_add_f32_e32 v82, 1.0, v84
	v_mov_b32_e32 v88, v97
	v_rcp_f32_e32 v87, v82
	v_pk_mul_f32 v[82:83], v[98:99], v[88:89] op_sel_hi:[0,1]
	v_mul_f32_e32 v84, 0xbfb8aa3b, v82
	v_exp_f32_e32 v88, v84
	v_mov_b32_e32 v84, v93
	v_pk_mul_f32 v[84:85], v[98:99], v[84:85] op_sel_hi:[0,1]
	v_mul_f32_e32 v89, 0xbfb8aa3b, v84
	v_exp_f32_e32 v89, v89
	v_mul_f32_e32 v93, v87, v86
	v_add_f32_e32 v86, 1.0, v88
	v_rcp_f32_e32 v86, v86
	v_add_f32_e32 v87, 1.0, v89
	v_rcp_f32_e32 v87, v87
	v_mul_f32_e32 v82, v82, v83
	v_mul_f32_e32 v88, v86, v82
	v_mul_f32_e32 v82, v84, v85
	v_mul_f32_e32 v85, v87, v82
	v_or_b32_e32 v82, 32, v153
	v_mad_i64_i32 v[82:83], s[2:3], v82, s63, v[114:115]
	v_lshl_add_u64 v[86:87], v[82:83], 0, v[116:117]
	v_mul_f32_e32 v95, v95, v99
	v_cvt_pk_bf16_f32 v82, v90, v95
	v_cvt_pk_bf16_f32 v83, v92, v88
	v_cvt_pk_bf16_f32 v84, v94, v91
	v_cvt_pk_bf16_f32 v85, v93, v85
	global_store_dwordx4 v[86:87], v[82:85], off
	s_nop 0
	s_nop 0
	v_fmamk_f32 v82, v150, 0x3a000000, v146
	v_rsq_f32_e32 v82, v82
	v_mov_b32_e32 v84, v78
	v_mov_b32_e32 v85, v70
	v_mov_b32_e32 v86, v74
	v_pk_mul_f32 v[84:85], v[82:83], v[84:85] op_sel_hi:[0,1]
	v_mov_b32_e32 v87, v66
	v_mul_f32_e32 v70, 0xbfb8aa3b, v84
	v_pk_mul_f32 v[86:87], v[82:83], v[86:87] op_sel_hi:[0,1]
	v_exp_f32_e32 v70, v70
	v_mul_f32_e32 v66, 0xbfb8aa3b, v86
	v_exp_f32_e32 v66, v66
	v_mul_f32_e32 v74, v84, v85
	v_add_f32_e32 v70, 1.0, v70
	v_rcp_f32_e32 v70, v70
	v_add_f32_e32 v66, 1.0, v66
	v_rcp_f32_e32 v66, v66
	v_mul_f32_e32 v74, v70, v74
	v_mul_f32_e32 v70, v86, v87
	v_mul_f32_e32 v78, v66, v70
	v_mov_b32_e32 v70, v79
	v_pk_mul_f32 v[70:71], v[82:83], v[70:71] op_sel_hi:[0,1]
	v_mul_f32_e32 v66, 0xbfb8aa3b, v70
	v_exp_f32_e32 v79, v66
	v_mov_b32_e32 v66, v75
	v_pk_mul_f32 v[66:67], v[82:83], v[66:67] op_sel_hi:[0,1]
	v_mul_f32_e32 v75, 0xbfb8aa3b, v66
	v_exp_f32_e32 v75, v75
	v_mul_f32_e32 v83, v70, v71
	v_add_f32_e32 v70, 1.0, v79
	v_rcp_f32_e32 v79, v70
	v_add_f32_e32 v70, 1.0, v75
	v_rcp_f32_e32 v75, v70
	v_mov_b32_e32 v70, v80
	v_mov_b32_e32 v71, v72
	v_pk_mul_f32 v[70:71], v[82:83], v[70:71] op_sel_hi:[0,1]
	v_mul_f32_e32 v72, 0xbfb8aa3b, v70
	v_exp_f32_e32 v72, v72
	v_mul_f32_e32 v66, v66, v67
	v_mul_f32_e32 v75, v75, v66
	v_mov_b32_e32 v67, v68
	v_add_f32_e32 v66, 1.0, v72
	v_rcp_f32_e32 v72, v66
	v_mov_b32_e32 v66, v76
	v_pk_mul_f32 v[66:67], v[82:83], v[66:67] op_sel_hi:[0,1]
	v_mul_f32_e32 v68, 0xbfb8aa3b, v66
	v_exp_f32_e32 v68, v68
	v_mul_f32_e32 v70, v70, v71
	v_mul_f32_e32 v76, v72, v70
	v_mul_f32_e32 v70, v66, v67
	v_add_f32_e32 v66, 1.0, v68
	v_mov_b32_e32 v72, v81
	v_rcp_f32_e32 v71, v66
	v_pk_mul_f32 v[66:67], v[82:83], v[72:73] op_sel_hi:[0,1]
	v_mul_f32_e32 v68, 0xbfb8aa3b, v66
	v_exp_f32_e32 v72, v68
	v_mov_b32_e32 v68, v77
	v_pk_mul_f32 v[68:69], v[82:83], v[68:69] op_sel_hi:[0,1]
	v_mul_f32_e32 v73, 0xbfb8aa3b, v68
	v_exp_f32_e32 v73, v73
	v_mul_f32_e32 v77, v71, v70
	v_add_f32_e32 v70, 1.0, v72
	v_rcp_f32_e32 v70, v70
	v_add_f32_e32 v71, 1.0, v73
	v_rcp_f32_e32 v71, v71
	v_mul_f32_e32 v66, v66, v67
	v_mul_f32_e32 v72, v70, v66
	v_mul_f32_e32 v66, v68, v69
	v_mul_f32_e32 v69, v71, v66
	v_or_b32_e32 v66, 48, v153
	v_mad_i64_i32 v[66:67], s[2:3], v66, s63, v[114:115]
	v_lshl_add_u64 v[70:71], v[66:67], 0, v[116:117]
	v_mul_f32_e32 v79, v79, v83
	v_cvt_pk_bf16_f32 v66, v74, v79
	v_cvt_pk_bf16_f32 v67, v76, v72
	v_cvt_pk_bf16_f32 v68, v78, v75
	v_cvt_pk_bf16_f32 v69, v77, v69
	global_store_dwordx4 v[70:71], v[66:69], off
	s_nop 0
	s_nop 0
	v_fmamk_f32 v66, v149, 0x3a000000, v146
	v_rsq_f32_e32 v66, v66
	v_mov_b32_e32 v68, v62
	v_mov_b32_e32 v69, v54
	v_mov_b32_e32 v70, v58
	v_pk_mul_f32 v[68:69], v[66:67], v[68:69] op_sel_hi:[0,1]
	v_mov_b32_e32 v71, v50
	v_mul_f32_e32 v54, 0xbfb8aa3b, v68
	v_pk_mul_f32 v[70:71], v[66:67], v[70:71] op_sel_hi:[0,1]
	v_exp_f32_e32 v54, v54
	v_mul_f32_e32 v50, 0xbfb8aa3b, v70
	v_exp_f32_e32 v50, v50
	v_mul_f32_e32 v62, v68, v69
	v_add_f32_e32 v54, 1.0, v54
	v_rcp_f32_e32 v54, v54
	v_add_f32_e32 v50, 1.0, v50
	v_rcp_f32_e32 v50, v50
	v_add_u32_e32 v58, 0x80, v153
	v_mul_f32_e32 v62, v54, v62
	v_mul_f32_e32 v54, v70, v71
	v_mul_f32_e32 v67, v50, v54
; __device__ __forceinline__ float fexp2(float x) { return __builtin_amdgcn_exp2f(x); }
; __device__ __forceinline__ void st_bf16x8(bf16* p, f32x4 a, f32x4 b) { *(bf16x8*)p = pack8(a, b); }
; __device__ __forceinline__ float rs_val(float ssqv) { return __builtin_amdgcn_rsqf(ssqv * (1.f / DM) + EPS); }
; __device__ __forceinline__ float swiglu1(float g, float u) { return g * u * __builtin_amdgcn_rcpf(1.f + fexp2(-g * LOG2E)); }
;     __device__ __forceinline__ void operator()(const Acc& acc, const pg8::Unit& u, int wr, int wc, int fr, int fq, const float* rsv) const {
;         const int c = u.pn * 128 + wc * 32 + fq * 8;
; #pragma unroll
;         for (int ai = 0; ai < 2; ++ai)
; #pragma unroll
;             for (int m = 0; m < 4; ++m) { const int row = u.pm * 256 + ai * 128 + wr * 64 + m * 16 + fr; const float rs = rs_val(rsv[ai * 4 + m]);
;                 f32x4 o0, o1;
; #pragma unroll
;                 for (int e = 0; e < 4; ++e) { o0[e] = swiglu1(acc[ai][0][m][0][e] * rs, acc[ai][1][m][0][e] * rs); o1[e] = swiglu1(acc[ai][0][m][1][e] * rs, acc[ai][1][m][1][e] * rs); }
;                 st_bf16x8(ACT + (size_t)row * DFF + c, o0, o1); __builtin_amdgcn_sched_barrier(0); }
;     }
	v_mov_b32_e32 v54, v63
	v_pk_mul_f32 v[54:55], v[66:67], v[54:55] op_sel_hi:[0,1]
	v_mul_f32_e32 v50, 0xbfb8aa3b, v54
	v_exp_f32_e32 v63, v50
	v_mov_b32_e32 v50, v59
	v_pk_mul_f32 v[50:51], v[66:67], v[50:51] op_sel_hi:[0,1]
	v_mul_f32_e32 v59, 0xbfb8aa3b, v50
	v_exp_f32_e32 v59, v59
	v_mul_f32_e32 v68, v54, v55
	v_add_f32_e32 v54, 1.0, v63
	v_rcp_f32_e32 v63, v54
	v_add_f32_e32 v54, 1.0, v59
	v_rcp_f32_e32 v59, v54
	v_mov_b32_e32 v54, v64
	v_mov_b32_e32 v55, v56
	v_pk_mul_f32 v[54:55], v[66:67], v[54:55] op_sel_hi:[0,1]
	v_mul_f32_e32 v56, 0xbfb8aa3b, v54
	v_exp_f32_e32 v56, v56
	v_mul_f32_e32 v50, v50, v51
	v_mul_f32_e32 v59, v59, v50
	v_mov_b32_e32 v51, v52
	v_add_f32_e32 v50, 1.0, v56
	v_rcp_f32_e32 v56, v50
	v_mov_b32_e32 v50, v60
	v_pk_mul_f32 v[50:51], v[66:67], v[50:51] op_sel_hi:[0,1]
	v_mul_f32_e32 v52, 0xbfb8aa3b, v50
	v_exp_f32_e32 v52, v52
	v_mul_f32_e32 v54, v54, v55
	v_mul_f32_e32 v60, v56, v54
	v_mul_f32_e32 v54, v50, v51
	v_add_f32_e32 v50, 1.0, v52
	v_mov_b32_e32 v56, v65
	v_rcp_f32_e32 v55, v50
	v_pk_mul_f32 v[50:51], v[66:67], v[56:57] op_sel_hi:[0,1]
	v_mul_f32_e32 v52, 0xbfb8aa3b, v50
	v_exp_f32_e32 v56, v52
	v_mov_b32_e32 v52, v61
	v_pk_mul_f32 v[52:53], v[66:67], v[52:53] op_sel_hi:[0,1]
	v_mul_f32_e32 v57, 0xbfb8aa3b, v52
	v_exp_f32_e32 v57, v57
	v_mul_f32_e32 v61, v55, v54
	v_add_f32_e32 v54, 1.0, v56
	v_rcp_f32_e32 v54, v54
	v_add_f32_e32 v55, 1.0, v57
	v_rcp_f32_e32 v55, v55
	v_mul_f32_e32 v50, v50, v51
	v_mul_f32_e32 v56, v54, v50
	v_mul_f32_e32 v50, v52, v53
	v_mul_f32_e32 v53, v55, v50
	v_mad_i64_i32 v[50:51], s[2:3], v58, s63, v[114:115]
	v_lshl_add_u64 v[54:55], v[50:51], 0, v[116:117]
	v_mul_f32_e32 v63, v63, v68
	v_cvt_pk_bf16_f32 v50, v62, v63
	v_cvt_pk_bf16_f32 v51, v60, v56
	v_cvt_pk_bf16_f32 v52, v67, v59
	v_cvt_pk_bf16_f32 v53, v61, v53
	global_store_dwordx4 v[54:55], v[50:53], off
	s_nop 0
	s_nop 0
	v_fmamk_f32 v50, v148, 0x3a000000, v146
	v_rsq_f32_e32 v50, v50
	v_mov_b32_e32 v52, v46
	v_mov_b32_e32 v53, v38
	v_mov_b32_e32 v54, v42
	v_pk_mul_f32 v[52:53], v[50:51], v[52:53] op_sel_hi:[0,1]
	v_mov_b32_e32 v55, v34
	v_mul_f32_e32 v38, 0xbfb8aa3b, v52
	v_pk_mul_f32 v[54:55], v[50:51], v[54:55] op_sel_hi:[0,1]
	v_exp_f32_e32 v38, v38
	v_mul_f32_e32 v34, 0xbfb8aa3b, v54
	v_exp_f32_e32 v34, v34
	v_mul_f32_e32 v42, v52, v53
	v_add_f32_e32 v38, 1.0, v38
	v_rcp_f32_e32 v38, v38
	v_add_f32_e32 v34, 1.0, v34
	v_rcp_f32_e32 v34, v34
	v_mul_f32_e32 v42, v38, v42
	v_mul_f32_e32 v38, v54, v55
	v_mul_f32_e32 v46, v34, v38
	v_mov_b32_e32 v38, v47
	v_pk_mul_f32 v[38:39], v[50:51], v[38:39] op_sel_hi:[0,1]
	v_mul_f32_e32 v34, 0xbfb8aa3b, v38
	v_exp_f32_e32 v47, v34
	v_mov_b32_e32 v34, v43
	v_pk_mul_f32 v[34:35], v[50:51], v[34:35] op_sel_hi:[0,1]
	v_mul_f32_e32 v43, 0xbfb8aa3b, v34
	v_exp_f32_e32 v43, v43
	v_mul_f32_e32 v51, v38, v39
	v_add_f32_e32 v38, 1.0, v47
	v_rcp_f32_e32 v47, v38
	v_add_f32_e32 v38, 1.0, v43
	v_rcp_f32_e32 v43, v38
	v_mov_b32_e32 v38, v48
	v_mov_b32_e32 v39, v40
	v_pk_mul_f32 v[38:39], v[50:51], v[38:39] op_sel_hi:[0,1]
	v_mul_f32_e32 v40, 0xbfb8aa3b, v38
	v_exp_f32_e32 v40, v40
	v_mul_f32_e32 v34, v34, v35
	v_mul_f32_e32 v43, v43, v34
	v_mov_b32_e32 v35, v36
	v_add_f32_e32 v34, 1.0, v40
	v_rcp_f32_e32 v40, v34
	v_mov_b32_e32 v34, v44
	v_pk_mul_f32 v[34:35], v[50:51], v[34:35] op_sel_hi:[0,1]
	v_mul_f32_e32 v36, 0xbfb8aa3b, v34
	v_exp_f32_e32 v36, v36
	v_mul_f32_e32 v38, v38, v39
	v_mul_f32_e32 v44, v40, v38
	v_mul_f32_e32 v38, v34, v35
	v_add_f32_e32 v34, 1.0, v36
	v_mov_b32_e32 v40, v49
	v_rcp_f32_e32 v39, v34
	v_pk_mul_f32 v[34:35], v[50:51], v[40:41] op_sel_hi:[0,1]
	v_mul_f32_e32 v36, 0xbfb8aa3b, v34
	v_exp_f32_e32 v40, v36
	v_mov_b32_e32 v36, v45
	v_pk_mul_f32 v[36:37], v[50:51], v[36:37] op_sel_hi:[0,1]
	v_mul_f32_e32 v41, 0xbfb8aa3b, v36
	v_exp_f32_e32 v41, v41
	v_mul_f32_e32 v45, v39, v38
	v_add_f32_e32 v38, 1.0, v40
	v_rcp_f32_e32 v38, v38
	v_add_f32_e32 v39, 1.0, v41
	v_rcp_f32_e32 v39, v39
	v_mul_f32_e32 v34, v34, v35
	v_mul_f32_e32 v40, v38, v34
	v_mul_f32_e32 v34, v36, v37
	v_mul_f32_e32 v37, v39, v34
	v_add_u32_e32 v34, 0x90, v153
	v_mad_i64_i32 v[34:35], s[2:3], v34, s63, v[114:115]
	v_lshl_add_u64 v[38:39], v[34:35], 0, v[116:117]
	v_mul_f32_e32 v47, v47, v51
	v_cvt_pk_bf16_f32 v34, v42, v47
	v_cvt_pk_bf16_f32 v35, v44, v40
	v_cvt_pk_bf16_f32 v36, v46, v43
	v_cvt_pk_bf16_f32 v37, v45, v37
	global_store_dwordx4 v[38:39], v[34:37], off
	s_nop 0
	s_nop 0
	v_fmamk_f32 v34, v147, 0x3a000000, v146
	v_rsq_f32_e32 v34, v34
	v_mov_b32_e32 v36, v30
	v_mov_b32_e32 v37, v22
	v_mov_b32_e32 v38, v26
	v_pk_mul_f32 v[36:37], v[34:35], v[36:37] op_sel_hi:[0,1]
	v_mov_b32_e32 v39, v18
	v_mul_f32_e32 v22, 0xbfb8aa3b, v36
	v_pk_mul_f32 v[38:39], v[34:35], v[38:39] op_sel_hi:[0,1]
	v_exp_f32_e32 v22, v22
	v_mul_f32_e32 v18, 0xbfb8aa3b, v38
	v_exp_f32_e32 v18, v18
	v_mul_f32_e32 v26, v36, v37
	v_add_f32_e32 v22, 1.0, v22
	v_rcp_f32_e32 v22, v22
	v_add_f32_e32 v18, 1.0, v18
	v_rcp_f32_e32 v18, v18
	v_mul_f32_e32 v26, v22, v26
	v_mul_f32_e32 v22, v38, v39
	v_mul_f32_e32 v30, v18, v22
; #define PG8_BAR __builtin_amdgcn_s_barrier()
; __device__ __forceinline__ float rs_val(float ssqv) { return __builtin_amdgcn_rsqf(ssqv * (1.f / DM) + EPS); }
; __device__ __forceinline__ void st_bf16x8(bf16* p, f32x4 a, f32x4 b) { *(bf16x8*)p = pack8(a, b); }
; __device__ __forceinline__ float swiglu1(float g, float u) { return g * u * __builtin_amdgcn_rcpf(1.f + fexp2(-g * LOG2E)); }
; template <class Epi, class Sched, bool ALIGN_EPI>
; __device__ __forceinline__ void gemm_phase(LAS unsigned char* lds, const Gemm g, const Sched& S, const Epi& E) {
;     ...
;         cur = nxt; cA = nA; cB = nB; ++ui;
;         if constexpr (Epi::NPRE > 0) E.preload(cur, wr, fr, pre);
;         if constexpr (ALIGN_EPI) { if (wr == 1) PG8_BAR; }
;     __device__ __forceinline__ void preload(const pg8::Unit& u, int wr, int fr, float* rsv) const {
; #pragma unroll
;         for (int k = 0; k < 8; ++k) rsv[k] = ssq[u.pm * 256 + (k >> 2) * 128 + wr * 64 + (k & 3) * 16 + fr]; }
;     __device__ __forceinline__ void operator()(const Acc& acc, const pg8::Unit& u, int wr, int wc, int fr, int fq, const float* rsv) const {
;         const int c = u.pn * 128 + wc * 32 + fq * 8;
; #pragma unroll
;         for (int ai = 0; ai < 2; ++ai)
; #pragma unroll
;             for (int m = 0; m < 4; ++m) { const int row = u.pm * 256 + ai * 128 + wr * 64 + m * 16 + fr; const float rs = rs_val(rsv[ai * 4 + m]);
;                 f32x4 o0, o1;
; #pragma unroll
;                 for (int e = 0; e < 4; ++e) { o0[e] = swiglu1(acc[ai][0][m][0][e] * rs, acc[ai][1][m][0][e] * rs); o1[e] = swiglu1(acc[ai][0][m][1][e] * rs, acc[ai][1][m][1][e] * rs); }
;                 st_bf16x8(ACT + (size_t)row * DFF + c, o0, o1); __builtin_amdgcn_sched_barrier(0); }
;     }
	v_mov_b32_e32 v22, v31
	v_pk_mul_f32 v[22:23], v[34:35], v[22:23] op_sel_hi:[0,1]
	v_mul_f32_e32 v18, 0xbfb8aa3b, v22
	v_exp_f32_e32 v31, v18
	v_mov_b32_e32 v18, v27
	v_pk_mul_f32 v[18:19], v[34:35], v[18:19] op_sel_hi:[0,1]
	v_mul_f32_e32 v27, 0xbfb8aa3b, v18
	v_exp_f32_e32 v27, v27
	v_mul_f32_e32 v35, v22, v23
	v_add_f32_e32 v22, 1.0, v31
	v_rcp_f32_e32 v31, v22
	v_add_f32_e32 v22, 1.0, v27
	v_rcp_f32_e32 v27, v22
	v_mov_b32_e32 v22, v32
	v_mov_b32_e32 v23, v24
	v_pk_mul_f32 v[22:23], v[34:35], v[22:23] op_sel_hi:[0,1]
	v_mul_f32_e32 v24, 0xbfb8aa3b, v22
	v_exp_f32_e32 v24, v24
	v_mul_f32_e32 v18, v18, v19
	v_mul_f32_e32 v27, v27, v18
	v_mov_b32_e32 v19, v20
	v_add_f32_e32 v18, 1.0, v24
	v_rcp_f32_e32 v24, v18
	v_mov_b32_e32 v18, v28
	v_pk_mul_f32 v[18:19], v[34:35], v[18:19] op_sel_hi:[0,1]
	v_mul_f32_e32 v20, 0xbfb8aa3b, v18
	v_exp_f32_e32 v20, v20
	v_mul_f32_e32 v22, v22, v23
	v_mul_f32_e32 v28, v24, v22
	v_mul_f32_e32 v22, v18, v19
	v_add_f32_e32 v18, 1.0, v20
	v_mov_b32_e32 v24, v33
	v_rcp_f32_e32 v23, v18
	v_pk_mul_f32 v[18:19], v[34:35], v[24:25] op_sel_hi:[0,1]
	v_mul_f32_e32 v20, 0xbfb8aa3b, v18
	v_exp_f32_e32 v24, v20
	v_mov_b32_e32 v20, v29
	v_pk_mul_f32 v[20:21], v[34:35], v[20:21] op_sel_hi:[0,1]
	v_mul_f32_e32 v25, 0xbfb8aa3b, v20
	v_exp_f32_e32 v25, v25
	v_mul_f32_e32 v29, v23, v22
	v_add_f32_e32 v22, 1.0, v24
	v_rcp_f32_e32 v22, v22
	v_add_f32_e32 v23, 1.0, v25
	v_rcp_f32_e32 v23, v23
	v_mul_f32_e32 v18, v18, v19
	v_mul_f32_e32 v24, v22, v18
	v_mul_f32_e32 v18, v20, v21
	v_mul_f32_e32 v21, v23, v18
	v_add_u32_e32 v18, 0xa0, v153
	v_mad_i64_i32 v[18:19], s[2:3], v18, s63, v[114:115]
	v_lshl_add_u64 v[22:23], v[18:19], 0, v[116:117]
	v_mul_f32_e32 v31, v31, v35
	v_cvt_pk_bf16_f32 v18, v26, v31
	v_cvt_pk_bf16_f32 v19, v28, v24
	v_cvt_pk_bf16_f32 v20, v30, v27
	v_cvt_pk_bf16_f32 v21, v29, v21
	global_store_dwordx4 v[22:23], v[18:21], off
	s_nop 0
	s_nop 0
	v_fmamk_f32 v18, v139, 0x3a000000, v146
	v_rsq_f32_e32 v18, v18
	v_mov_b32_e32 v20, v14
	v_mov_b32_e32 v21, v6
	v_mov_b32_e32 v22, v10
	v_pk_mul_f32 v[20:21], v[18:19], v[20:21] op_sel_hi:[0,1]
	v_mov_b32_e32 v23, v2
	v_mul_f32_e32 v6, 0xbfb8aa3b, v20
	v_pk_mul_f32 v[22:23], v[18:19], v[22:23] op_sel_hi:[0,1]
	v_exp_f32_e32 v6, v6
	v_mul_f32_e32 v2, 0xbfb8aa3b, v22
	v_exp_f32_e32 v2, v2
	v_mul_f32_e32 v10, v20, v21
	v_add_f32_e32 v6, 1.0, v6
	v_rcp_f32_e32 v6, v6
	v_add_f32_e32 v2, 1.0, v2
	v_rcp_f32_e32 v2, v2
	v_mul_f32_e32 v10, v6, v10
	v_mul_f32_e32 v6, v22, v23
	v_mul_f32_e32 v14, v2, v6
	v_mov_b32_e32 v6, v15
	v_pk_mul_f32 v[6:7], v[18:19], v[6:7] op_sel_hi:[0,1]
	v_mul_f32_e32 v2, 0xbfb8aa3b, v6
	v_exp_f32_e32 v15, v2
	v_mov_b32_e32 v2, v11
	v_pk_mul_f32 v[2:3], v[18:19], v[2:3] op_sel_hi:[0,1]
	v_mul_f32_e32 v11, 0xbfb8aa3b, v2
	v_exp_f32_e32 v11, v11
	v_mul_f32_e32 v19, v6, v7
	v_add_f32_e32 v6, 1.0, v15
	v_rcp_f32_e32 v15, v6
	v_add_f32_e32 v6, 1.0, v11
	v_rcp_f32_e32 v11, v6
	v_mov_b32_e32 v6, v16
	v_mov_b32_e32 v7, v8
	v_pk_mul_f32 v[6:7], v[18:19], v[6:7] op_sel_hi:[0,1]
	v_mul_f32_e32 v8, 0xbfb8aa3b, v6
	v_exp_f32_e32 v8, v8
	v_mul_f32_e32 v2, v2, v3
	v_mul_f32_e32 v11, v11, v2
	v_mov_b32_e32 v3, v4
	v_add_f32_e32 v2, 1.0, v8
	v_rcp_f32_e32 v8, v2
	v_mov_b32_e32 v2, v12
	v_pk_mul_f32 v[2:3], v[18:19], v[2:3] op_sel_hi:[0,1]
	v_mul_f32_e32 v4, 0xbfb8aa3b, v2
	v_exp_f32_e32 v4, v4
	v_mul_f32_e32 v6, v6, v7
	v_mul_f32_e32 v12, v8, v6
	v_mul_f32_e32 v6, v2, v3
	v_add_f32_e32 v2, 1.0, v4
	v_mov_b32_e32 v8, v17
	v_rcp_f32_e32 v7, v2
	v_pk_mul_f32 v[2:3], v[18:19], v[8:9] op_sel_hi:[0,1]
	v_mul_f32_e32 v4, 0xbfb8aa3b, v2
	v_exp_f32_e32 v8, v4
	v_mov_b32_e32 v4, v13
	v_pk_mul_f32 v[4:5], v[18:19], v[4:5] op_sel_hi:[0,1]
	v_mul_f32_e32 v9, 0xbfb8aa3b, v4
	v_exp_f32_e32 v9, v9
	v_mul_f32_e32 v13, v7, v6
	v_add_f32_e32 v6, 1.0, v8
	v_rcp_f32_e32 v6, v6
	v_add_f32_e32 v7, 1.0, v9
	v_rcp_f32_e32 v7, v7
	v_mul_f32_e32 v2, v2, v3
	v_mul_f32_e32 v8, v6, v2
	v_mul_f32_e32 v2, v4, v5
	v_mul_f32_e32 v5, v7, v2
	v_add_u32_e32 v2, 0xb0, v153
	v_mad_i64_i32 v[2:3], s[2:3], v2, s63, v[114:115]
	v_lshl_add_u64 v[6:7], v[2:3], 0, v[116:117]
	v_mul_f32_e32 v15, v15, v19
	v_cvt_pk_bf16_f32 v2, v10, v15
	v_cvt_pk_bf16_f32 v3, v12, v8
	v_cvt_pk_bf16_f32 v4, v14, v11
	v_cvt_pk_bf16_f32 v5, v13, v5
	global_store_dwordx4 v[6:7], v[2:5], off
	s_andn2_b64 vcc, exec, s[10:11]
	s_mov_b64 s[4:5], -1
	s_cbranch_vccnz .LBB0_1210
	v_lshl_add_u32 v2, s26, 8, v138
	v_ashrrev_i32_e32 v3, 31, v2
	v_lshl_add_u64 v[4:5], v[2:3], 2, s[8:9]
	v_add_u32_e32 v2, 0x80, v2
	v_ashrrev_i32_e32 v3, 31, v2
	v_lshl_add_u64 v[2:3], v[2:3], 2, s[8:9]
	global_load_dword v153, v[4:5], off
	global_load_dword v152, v[4:5], off offset:64
	global_load_dword v151, v[4:5], off offset:128
	global_load_dword v150, v[4:5], off offset:192
	global_load_dword v149, v[2:3], off
	global_load_dword v148, v[2:3], off offset:64
	global_load_dword v147, v[2:3], off offset:128
	global_load_dword v139, v[2:3], off offset:192
	s_andn2_b64 vcc, exec, s[12:13]
	s_cbranch_vccnz .LBB0_1209
	s_barrier
	s_branch .LBB0_1209

; #define PG8_STAGE(bufoff, gbase, voff) do { _Pragma("unroll") for (int _i = 0; _i < 2; ++_i) { unsigned keep_; \
;         asm volatile("s_mov_b32 %0, m0\n\ts_mov_b32 m0, %3\n\ts_nop 0\n\tglobal_load_lds_dwordx4 %1, %2\n\ts_mov_b32 m0, %0" \
;             : "=&s"(keep_) : "v"((voff)[_i]), "s"((const void*)(gbase)), "s"(ldsb0 + (unsigned)(bufoff) + (unsigned)(_i * 8192)) : "memory"); } } while (0)
; #define PG8_LDA(dst, b, h) do { _Pragma("unroll") for (int m = 0; m < 4; ++m) _Pragma("unroll") for (int k = 0; k < 2; ++k) dst[m][k] = *(const LAS bf16x8*)(lds + PG8_SA(b, h) + aoff + m * 2048 + k * 1024); } while (0)
; #define PG8_LDB(dst, b, h) do { _Pragma("unroll") for (int n = 0; n < 2; ++n) _Pragma("unroll") for (int k = 0; k < 2; ++k) dst[n][k] = *(const LAS bf16x8*)(lds + PG8_SB(b, h) + boff + n * 2048 + k * 1024); } while (0)
; #define PG8_WAIT_V(n) asm volatile("s_waitcnt vmcnt(" #n ")" ::: "memory")
; #define PG8_WAIT_L(n) asm volatile("s_waitcnt lgkmcnt(" #n ")" ::: "memory")
; #define PG8_BAR __builtin_amdgcn_s_barrier()
; #define PG8_SCHED __builtin_amdgcn_sched_barrier(0)
; template <class Epi, class Sched, bool ALIGN_EPI>
; __device__ __forceinline__ void gemm_phase(LAS unsigned char* lds, const Gemm g, const Sched& S, const Epi& E) {
;     ...
;             PG8_LDB(B0, 0, 0); PG8_LDB(B1, 0, 1); PG8_SCHED; PG8_LDA(At, 0, 0); PG8_STAGE(PG8_SA(1, 1), a1 + hstepA, voffA);
;             PG8_WAIT_V(8); PG8_WAIT_L(0); PG8_BAR; PG8_MMA(0, 0, At, B0); PG8_MMA(0, 1, At, B1); PG8_BAR; PG8_SCHED;
;             PG8_LDA(At, 0, 1); PG8_STAGE(PG8_SB(0, 0), b2, voffB); PG8_STAGE(PG8_SB(0, 1), b2 + hstepB, voffB); PG8_STAGE(PG8_SA(0, 0), a2, voffA);
;             PG8_WAIT_V(8); PG8_WAIT_L(0); PG8_BAR; PG8_MMA(1, 0, At, B0); PG8_MMA(1, 1, At, B1); PG8_BAR; PG8_SCHED;
;             PG8_LDB(B0, 1, 0); PG8_LDB(B1, 1, 1); PG8_SCHED; PG8_LDA(At, 1, 0); PG8_STAGE(PG8_SA(0, 1), a2 + hstepA, voffA);
;             PG8_WAIT_V(8); PG8_WAIT_L(0); PG8_BAR; PG8_MMA(0, 0, At, B0); PG8_MMA(0, 1, At, B1); PG8_BAR; PG8_SCHED;
;             PG8_LDA(At, 1, 1); PG8_STAGE(PG8_SB(1, 0), b3, voffB); PG8_STAGE(PG8_SB(1, 1), b3 + hstepB, voffB); PG8_STAGE(PG8_SA(1, 0), a3, voffA);
;             PG8_WAIT_V(8); PG8_WAIT_L(0); PG8_BAR; PG8_MMA(1, 0, At, B0); PG8_MMA(1, 1, At, B1); PG8_BAR; PG8_SCHED;
.LBB0_1317:
	ds_read_b128 v[110:113], v206
	ds_read_b128 v[126:129], v206 offset:1024
	ds_read_b128 v[130:133], v206 offset:2048
	ds_read_b128 v[142:145], v206 offset:3072
	ds_read_b128 v[146:149], v207
	ds_read_b128 v[150:153], v207 offset:1024
	ds_read_b128 v[154:157], v207 offset:2048
	ds_read_b128 v[158:161], v207 offset:3072
	s_cmpk_eq_i32 s58, 0x54
	s_cselect_b32 s34, s14, s6
	s_cselect_b32 s35, s15, s7
	s_cselect_b32 s30, s26, s56
	s_cselect_b32 s31, s27, s57
	s_add_u32 s28, s34, 0x80
	s_addc_u32 s29, s35, 0
	ds_read_b128 v[162:165], v208
	ds_read_b128 v[166:169], v208 offset:1024
	ds_read_b128 v[170:173], v208 offset:2048
	ds_read_b128 v[174:177], v208 offset:3072
	ds_read_b128 v[188:191], v208 offset:4096
	ds_read_b128 v[192:195], v208 offset:5120
	ds_read_b128 v[196:199], v208 offset:6144
	ds_read_b128 v[212:215], v208 offset:7168
	s_mov_b32 m0, s52
	s_nop 0
	global_load_lds_dwordx4 v179, s[4:5]
	s_mov_b32 m0, s53
	s_nop 0
	global_load_lds_dwordx4 v201, s[4:5]
	s_waitcnt vmcnt(8)
	s_waitcnt lgkmcnt(0)
	s_barrier
	s_setprio 1
	v_mfma_f32_16x16x32_bf16 v[138:141], v[110:113], v[162:165], v[138:141]
	v_mfma_f32_16x16x32_bf16 v[134:137], v[130:133], v[162:165], v[134:137]
	v_mfma_f32_16x16x32_bf16 v[114:117], v[110:113], v[170:173], v[114:117]
	v_mfma_f32_16x16x32_bf16 v[106:109], v[130:133], v[170:173], v[106:109]
	v_mfma_f32_16x16x32_bf16 v[94:97], v[110:113], v[188:191], v[94:97]
	v_mfma_f32_16x16x32_bf16 v[90:93], v[130:133], v[188:191], v[90:93]
	v_mfma_f32_16x16x32_bf16 v[78:81], v[110:113], v[196:199], v[78:81]
	v_mfma_f32_16x16x32_bf16 v[74:77], v[130:133], v[196:199], v[74:77]
	v_mfma_f32_16x16x32_bf16 v[138:141], v[126:129], v[166:169], v[138:141]
	v_mfma_f32_16x16x32_bf16 v[134:137], v[142:145], v[166:169], v[134:137]
	v_mfma_f32_16x16x32_bf16 v[114:117], v[126:129], v[174:177], v[114:117]
	v_mfma_f32_16x16x32_bf16 v[106:109], v[142:145], v[174:177], v[106:109]
	v_mfma_f32_16x16x32_bf16 v[94:97], v[126:129], v[192:195], v[94:97]
	v_mfma_f32_16x16x32_bf16 v[90:93], v[142:145], v[192:195], v[90:93]
	v_mfma_f32_16x16x32_bf16 v[78:81], v[126:129], v[212:215], v[78:81]
	v_mfma_f32_16x16x32_bf16 v[74:77], v[142:145], v[212:215], v[74:77]
	v_mfma_f32_16x16x32_bf16 v[122:125], v[146:149], v[162:165], v[122:125]
	v_mfma_f32_16x16x32_bf16 v[118:121], v[154:157], v[162:165], v[118:121]
	v_mfma_f32_16x16x32_bf16 v[102:105], v[146:149], v[170:173], v[102:105]
	v_mfma_f32_16x16x32_bf16 v[98:101], v[154:157], v[170:173], v[98:101]
	v_mfma_f32_16x16x32_bf16 v[86:89], v[146:149], v[188:191], v[86:89]
	v_mfma_f32_16x16x32_bf16 v[82:85], v[154:157], v[188:191], v[82:85]
	v_mfma_f32_16x16x32_bf16 v[70:73], v[146:149], v[196:199], v[70:73]
	v_mfma_f32_16x16x32_bf16 v[66:69], v[154:157], v[196:199], v[66:69]
	v_mfma_f32_16x16x32_bf16 v[122:125], v[150:153], v[166:169], v[122:125]
	v_mfma_f32_16x16x32_bf16 v[118:121], v[158:161], v[166:169], v[118:121]
	v_mfma_f32_16x16x32_bf16 v[102:105], v[150:153], v[174:177], v[102:105]
	v_mfma_f32_16x16x32_bf16 v[98:101], v[158:161], v[174:177], v[98:101]
	v_mfma_f32_16x16x32_bf16 v[86:89], v[150:153], v[192:195], v[86:89]
	v_mfma_f32_16x16x32_bf16 v[82:85], v[158:161], v[192:195], v[82:85]
	v_mfma_f32_16x16x32_bf16 v[70:73], v[150:153], v[212:215], v[70:73]
	v_mfma_f32_16x16x32_bf16 v[66:69], v[158:161], v[212:215], v[66:69]
	s_setprio 0
	s_barrier
	ds_read_b128 v[162:165], v208 offset:16384
	ds_read_b128 v[166:169], v208 offset:17408
	ds_read_b128 v[170:173], v208 offset:18432
	ds_read_b128 v[174:177], v208 offset:19456
	ds_read_b128 v[188:191], v208 offset:20480
	ds_read_b128 v[192:195], v208 offset:21504
	ds_read_b128 v[196:199], v208 offset:22528
	ds_read_b128 v[212:215], v208 offset:23552
	s_mov_b32 m0, s39
	s_nop 0
	global_load_lds_dwordx4 v200, s[30:31]
	s_add_u32 s62, s30, 0x160000
	s_mov_b32 m0, s40
	s_nop 0
	global_load_lds_dwordx4 v203, s[30:31]
	s_addc_u32 s63, s31, 0
	s_mov_b32 m0, s41
	s_nop 0
	global_load_lds_dwordx4 v200, s[62:63]
	s_mov_b32 m0, s42
	s_nop 0
	global_load_lds_dwordx4 v203, s[62:63]
	s_mov_b32 m0, s38
	s_nop 0
	global_load_lds_dwordx4 v179, s[34:35]
	s_mov_b32 m0, s43
	s_nop 0
	global_load_lds_dwordx4 v201, s[34:35]
	s_waitcnt vmcnt(8)
	s_waitcnt lgkmcnt(0)
	s_barrier
	s_setprio 1
	v_mfma_f32_16x16x32_bf16 v[62:65], v[110:113], v[162:165], v[62:65]
	v_mfma_f32_16x16x32_bf16 v[58:61], v[130:133], v[162:165], v[58:61]
	v_mfma_f32_16x16x32_bf16 v[46:49], v[110:113], v[170:173], v[46:49]
	v_mfma_f32_16x16x32_bf16 v[42:45], v[130:133], v[170:173], v[42:45]
	v_mfma_f32_16x16x32_bf16 v[30:33], v[110:113], v[188:191], v[30:33]
	v_mfma_f32_16x16x32_bf16 v[26:29], v[130:133], v[188:191], v[26:29]
	v_mfma_f32_16x16x32_bf16 v[14:17], v[110:113], v[196:199], v[14:17]
	v_mfma_f32_16x16x32_bf16 v[10:13], v[130:133], v[196:199], v[10:13]
	v_mfma_f32_16x16x32_bf16 v[62:65], v[126:129], v[166:169], v[62:65]
	v_mfma_f32_16x16x32_bf16 v[58:61], v[142:145], v[166:169], v[58:61]
	v_mfma_f32_16x16x32_bf16 v[46:49], v[126:129], v[174:177], v[46:49]
	v_mfma_f32_16x16x32_bf16 v[42:45], v[142:145], v[174:177], v[42:45]
	v_mfma_f32_16x16x32_bf16 v[30:33], v[126:129], v[192:195], v[30:33]
	v_mfma_f32_16x16x32_bf16 v[26:29], v[142:145], v[192:195], v[26:29]
	v_mfma_f32_16x16x32_bf16 v[14:17], v[126:129], v[212:215], v[14:17]
	v_mfma_f32_16x16x32_bf16 v[10:13], v[142:145], v[212:215], v[10:13]
	v_mfma_f32_16x16x32_bf16 v[54:57], v[146:149], v[162:165], v[54:57]
	v_mfma_f32_16x16x32_bf16 v[50:53], v[154:157], v[162:165], v[50:53]
	v_mfma_f32_16x16x32_bf16 v[38:41], v[146:149], v[170:173], v[38:41]
	v_mfma_f32_16x16x32_bf16 v[34:37], v[154:157], v[170:173], v[34:37]
	v_mfma_f32_16x16x32_bf16 v[22:25], v[146:149], v[188:191], v[22:25]
	v_mfma_f32_16x16x32_bf16 v[18:21], v[154:157], v[188:191], v[18:21]
	v_mfma_f32_16x16x32_bf16 v[6:9], v[146:149], v[196:199], v[6:9]
	v_mfma_f32_16x16x32_bf16 v[2:5], v[154:157], v[196:199], v[2:5]
	v_mfma_f32_16x16x32_bf16 v[54:57], v[150:153], v[166:169], v[54:57]
	v_mfma_f32_16x16x32_bf16 v[50:53], v[158:161], v[166:169], v[50:53]
	v_mfma_f32_16x16x32_bf16 v[38:41], v[150:153], v[174:177], v[38:41]
	v_mfma_f32_16x16x32_bf16 v[34:37], v[158:161], v[174:177], v[34:37]
	v_mfma_f32_16x16x32_bf16 v[22:25], v[150:153], v[192:195], v[22:25]
	v_mfma_f32_16x16x32_bf16 v[18:21], v[158:161], v[192:195], v[18:21]
	v_mfma_f32_16x16x32_bf16 v[6:9], v[150:153], v[212:215], v[6:9]
	v_mfma_f32_16x16x32_bf16 v[2:5], v[158:161], v[212:215], v[2:5]
	s_setprio 0
	s_barrier
; #define PG8_STAGE(bufoff, gbase, voff) do { _Pragma("unroll") for (int _i = 0; _i < 2; ++_i) { unsigned keep_; \
;         asm volatile("s_mov_b32 %0, m0\n\ts_mov_b32 m0, %3\n\ts_nop 0\n\tglobal_load_lds_dwordx4 %1, %2\n\ts_mov_b32 m0, %0" \
;             : "=&s"(keep_) : "v"((voff)[_i]), "s"((const void*)(gbase)), "s"(ldsb0 + (unsigned)(bufoff) + (unsigned)(_i * 8192)) : "memory"); } } while (0)
; #define PG8_LDA(dst, b, h) do { _Pragma("unroll") for (int m = 0; m < 4; ++m) _Pragma("unroll") for (int k = 0; k < 2; ++k) dst[m][k] = *(const LAS bf16x8*)(lds + PG8_SA(b, h) + aoff + m * 2048 + k * 1024); } while (0)
; #define PG8_LDB(dst, b, h) do { _Pragma("unroll") for (int n = 0; n < 2; ++n) _Pragma("unroll") for (int k = 0; k < 2; ++k) dst[n][k] = *(const LAS bf16x8*)(lds + PG8_SB(b, h) + boff + n * 2048 + k * 1024); } while (0)
; #define PG8_WAIT_V(n) asm volatile("s_waitcnt vmcnt(" #n ")" ::: "memory")
; #define PG8_WAIT_L(n) asm volatile("s_waitcnt lgkmcnt(" #n ")" ::: "memory")
; #define PG8_BAR __builtin_amdgcn_s_barrier()
; #define PG8_SCHED __builtin_amdgcn_sched_barrier(0)
; template <class Epi, class Sched, bool ALIGN_EPI>
; __device__ __forceinline__ void gemm_phase(LAS unsigned char* lds, const Gemm g, const Sched& S, const Epi& E) {
;     ...
;             PG8_LDB(B0, 0, 0); PG8_LDB(B1, 0, 1); PG8_SCHED; PG8_LDA(At, 0, 0); PG8_STAGE(PG8_SA(1, 1), a1 + hstepA, voffA);
;             PG8_WAIT_V(8); PG8_WAIT_L(0); PG8_BAR; PG8_MMA(0, 0, At, B0); PG8_MMA(0, 1, At, B1); PG8_BAR; PG8_SCHED;
;             PG8_LDA(At, 0, 1); PG8_STAGE(PG8_SB(0, 0), b2, voffB); PG8_STAGE(PG8_SB(0, 1), b2 + hstepB, voffB); PG8_STAGE(PG8_SA(0, 0), a2, voffA);
;             PG8_WAIT_V(8); PG8_WAIT_L(0); PG8_BAR; PG8_MMA(1, 0, At, B0); PG8_MMA(1, 1, At, B1); PG8_BAR; PG8_SCHED;
;             PG8_LDB(B0, 1, 0); PG8_LDB(B1, 1, 1); PG8_SCHED; PG8_LDA(At, 1, 0); PG8_STAGE(PG8_SA(0, 1), a2 + hstepA, voffA);
;             PG8_WAIT_V(8); PG8_WAIT_L(0); PG8_BAR; PG8_MMA(0, 0, At, B0); PG8_MMA(0, 1, At, B1); PG8_BAR; PG8_SCHED;
;             PG8_LDA(At, 1, 1); PG8_STAGE(PG8_SB(1, 0), b3, voffB); PG8_STAGE(PG8_SB(1, 1), b3 + hstepB, voffB); PG8_STAGE(PG8_SA(1, 0), a3, voffA);
;             PG8_WAIT_V(8); PG8_WAIT_L(0); PG8_BAR; PG8_MMA(1, 0, At, B0); PG8_MMA(1, 1, At, B1); PG8_BAR; PG8_SCHED;
;         }
;         if constexpr (ALIGN_EPI) { if (wr == 0) PG8_BAR; }
	ds_read_b128 v[110:113], v209
	ds_read_b128 v[126:129], v209 offset:1024
	ds_read_b128 v[130:133], v209 offset:2048
	ds_read_b128 v[142:145], v209 offset:3072
	ds_read_b128 v[146:149], v210
	ds_read_b128 v[150:153], v210 offset:1024
	ds_read_b128 v[154:157], v210 offset:2048
	ds_read_b128 v[158:161], v210 offset:3072
	ds_read_b128 v[162:165], v208 offset:32768
	ds_read_b128 v[166:169], v208 offset:33792
	ds_read_b128 v[170:173], v208 offset:34816
	ds_read_b128 v[174:177], v208 offset:35840
	ds_read_b128 v[188:191], v208 offset:36864
	ds_read_b128 v[192:195], v208 offset:37888
	ds_read_b128 v[196:199], v208 offset:38912
	ds_read_b128 v[212:215], v208 offset:39936
	s_add_u32 s34, s34, 0x160000
	s_addc_u32 s35, s35, 0
	s_mov_b32 m0, s44
	s_nop 0
	global_load_lds_dwordx4 v179, s[34:35]
	s_mov_b32 m0, s45
	s_nop 0
	global_load_lds_dwordx4 v201, s[34:35]
	s_waitcnt vmcnt(8)
	s_waitcnt lgkmcnt(0)
	s_barrier
	s_setprio 1
	v_mfma_f32_16x16x32_bf16 v[138:141], v[110:113], v[162:165], v[138:141]
	v_mfma_f32_16x16x32_bf16 v[134:137], v[130:133], v[162:165], v[134:137]
	v_mfma_f32_16x16x32_bf16 v[114:117], v[110:113], v[170:173], v[114:117]
	v_mfma_f32_16x16x32_bf16 v[106:109], v[130:133], v[170:173], v[106:109]
	v_mfma_f32_16x16x32_bf16 v[94:97], v[110:113], v[188:191], v[94:97]
	v_mfma_f32_16x16x32_bf16 v[90:93], v[130:133], v[188:191], v[90:93]
	v_mfma_f32_16x16x32_bf16 v[78:81], v[110:113], v[196:199], v[78:81]
	v_mfma_f32_16x16x32_bf16 v[74:77], v[130:133], v[196:199], v[74:77]
	v_mfma_f32_16x16x32_bf16 v[138:141], v[126:129], v[166:169], v[138:141]
	v_mfma_f32_16x16x32_bf16 v[134:137], v[142:145], v[166:169], v[134:137]
	v_mfma_f32_16x16x32_bf16 v[114:117], v[126:129], v[174:177], v[114:117]
	v_mfma_f32_16x16x32_bf16 v[106:109], v[142:145], v[174:177], v[106:109]
	v_mfma_f32_16x16x32_bf16 v[94:97], v[126:129], v[192:195], v[94:97]
	v_mfma_f32_16x16x32_bf16 v[90:93], v[142:145], v[192:195], v[90:93]
	v_mfma_f32_16x16x32_bf16 v[78:81], v[126:129], v[212:215], v[78:81]
	v_mfma_f32_16x16x32_bf16 v[74:77], v[142:145], v[212:215], v[74:77]
	v_mfma_f32_16x16x32_bf16 v[122:125], v[146:149], v[162:165], v[122:125]
	v_mfma_f32_16x16x32_bf16 v[118:121], v[154:157], v[162:165], v[118:121]
	v_mfma_f32_16x16x32_bf16 v[102:105], v[146:149], v[170:173], v[102:105]
	v_mfma_f32_16x16x32_bf16 v[98:101], v[154:157], v[170:173], v[98:101]
	v_mfma_f32_16x16x32_bf16 v[86:89], v[146:149], v[188:191], v[86:89]
	v_mfma_f32_16x16x32_bf16 v[82:85], v[154:157], v[188:191], v[82:85]
	v_mfma_f32_16x16x32_bf16 v[70:73], v[146:149], v[196:199], v[70:73]
	v_mfma_f32_16x16x32_bf16 v[66:69], v[154:157], v[196:199], v[66:69]
	v_mfma_f32_16x16x32_bf16 v[122:125], v[150:153], v[166:169], v[122:125]
	v_mfma_f32_16x16x32_bf16 v[118:121], v[158:161], v[166:169], v[118:121]
	v_mfma_f32_16x16x32_bf16 v[102:105], v[150:153], v[174:177], v[102:105]
	v_mfma_f32_16x16x32_bf16 v[98:101], v[158:161], v[174:177], v[98:101]
	v_mfma_f32_16x16x32_bf16 v[86:89], v[150:153], v[192:195], v[86:89]
	v_mfma_f32_16x16x32_bf16 v[82:85], v[158:161], v[192:195], v[82:85]
	v_mfma_f32_16x16x32_bf16 v[70:73], v[150:153], v[212:215], v[70:73]
	v_mfma_f32_16x16x32_bf16 v[66:69], v[158:161], v[212:215], v[66:69]
	s_setprio 0
	s_barrier
	ds_read_b128 v[162:165], v208 offset:49152
	ds_read_b128 v[166:169], v208 offset:50176
	ds_read_b128 v[170:173], v208 offset:51200
	ds_read_b128 v[174:177], v208 offset:52224
	ds_read_b128 v[188:191], v208 offset:53248
	ds_read_b128 v[192:195], v208 offset:54272
	ds_read_b128 v[196:199], v208 offset:55296
	ds_read_b128 v[212:215], v208 offset:56320
	s_add_u32 s34, s30, 0x80
	s_addc_u32 s35, s31, 0
	s_mov_b32 m0, s46
	s_nop 0
	global_load_lds_dwordx4 v200, s[34:35]
	s_add_u32 s30, s30, 0x160080
	s_mov_b32 m0, s47
	s_nop 0
	global_load_lds_dwordx4 v203, s[34:35]
	s_addc_u32 s31, s31, 0
	s_mov_b32 m0, s50
	s_nop 0
	global_load_lds_dwordx4 v200, s[30:31]
	s_mov_b32 m0, s51
	s_nop 0
	global_load_lds_dwordx4 v203, s[30:31]
	s_mov_b32 m0, s48
	s_nop 0
	global_load_lds_dwordx4 v179, s[28:29]
	s_mov_b32 m0, s49
	s_nop 0
	global_load_lds_dwordx4 v201, s[28:29]
	s_waitcnt vmcnt(8)
	s_waitcnt lgkmcnt(0)
	s_barrier
	s_setprio 1
	v_mfma_f32_16x16x32_bf16 v[62:65], v[110:113], v[162:165], v[62:65]
	v_mfma_f32_16x16x32_bf16 v[58:61], v[130:133], v[162:165], v[58:61]
	v_mfma_f32_16x16x32_bf16 v[46:49], v[110:113], v[170:173], v[46:49]
	v_mfma_f32_16x16x32_bf16 v[42:45], v[130:133], v[170:173], v[42:45]
	v_mfma_f32_16x16x32_bf16 v[30:33], v[110:113], v[188:191], v[30:33]
	v_mfma_f32_16x16x32_bf16 v[26:29], v[130:133], v[188:191], v[26:29]
	v_mfma_f32_16x16x32_bf16 v[14:17], v[110:113], v[196:199], v[14:17]
	v_mfma_f32_16x16x32_bf16 v[10:13], v[130:133], v[196:199], v[10:13]
	v_mfma_f32_16x16x32_bf16 v[62:65], v[126:129], v[166:169], v[62:65]
	v_mfma_f32_16x16x32_bf16 v[58:61], v[142:145], v[166:169], v[58:61]
	v_mfma_f32_16x16x32_bf16 v[46:49], v[126:129], v[174:177], v[46:49]
	v_mfma_f32_16x16x32_bf16 v[42:45], v[142:145], v[174:177], v[42:45]
	v_mfma_f32_16x16x32_bf16 v[30:33], v[126:129], v[192:195], v[30:33]
	v_mfma_f32_16x16x32_bf16 v[26:29], v[142:145], v[192:195], v[26:29]
	v_mfma_f32_16x16x32_bf16 v[14:17], v[126:129], v[212:215], v[14:17]
	v_mfma_f32_16x16x32_bf16 v[10:13], v[142:145], v[212:215], v[10:13]
	v_mfma_f32_16x16x32_bf16 v[54:57], v[146:149], v[162:165], v[54:57]
	v_mfma_f32_16x16x32_bf16 v[50:53], v[154:157], v[162:165], v[50:53]
	v_mfma_f32_16x16x32_bf16 v[38:41], v[146:149], v[170:173], v[38:41]
	v_mfma_f32_16x16x32_bf16 v[34:37], v[154:157], v[170:173], v[34:37]
	v_mfma_f32_16x16x32_bf16 v[22:25], v[146:149], v[188:191], v[22:25]
	v_mfma_f32_16x16x32_bf16 v[18:21], v[154:157], v[188:191], v[18:21]
	v_mfma_f32_16x16x32_bf16 v[6:9], v[146:149], v[196:199], v[6:9]
	v_mfma_f32_16x16x32_bf16 v[2:5], v[154:157], v[196:199], v[2:5]
	v_mfma_f32_16x16x32_bf16 v[54:57], v[150:153], v[166:169], v[54:57]
	v_mfma_f32_16x16x32_bf16 v[50:53], v[158:161], v[166:169], v[50:53]
	v_mfma_f32_16x16x32_bf16 v[38:41], v[150:153], v[174:177], v[38:41]
	v_mfma_f32_16x16x32_bf16 v[34:37], v[158:161], v[174:177], v[34:37]
	v_mfma_f32_16x16x32_bf16 v[22:25], v[150:153], v[192:195], v[22:25]
	v_mfma_f32_16x16x32_bf16 v[18:21], v[158:161], v[192:195], v[18:21]
	v_mfma_f32_16x16x32_bf16 v[6:9], v[150:153], v[212:215], v[6:9]
	v_mfma_f32_16x16x32_bf16 v[2:5], v[158:161], v[212:215], v[2:5]
	s_setprio 0
	s_barrier
	s_add_i32 s58, s58, 2
	s_add_u32 s6, s6, 0x100
	s_addc_u32 s7, s7, 0
	s_add_u32 s56, s56, 0x100
	s_addc_u32 s57, s57, 0
	s_add_u32 s4, s4, 0x100
	s_addc_u32 s5, s5, 0
	s_cmpk_gt_u32 s58, 0x55
	s_cbranch_scc0 .LBB0_1317
	s_and_b64 vcc, exec, s[18:19]
	s_cbranch_vccz .LBB0_1320
	s_barrier

; #define PG8_STAGE(bufoff, gbase, voff) do { _Pragma("unroll") for (int _i = 0; _i < 2; ++_i) { unsigned keep_; \
;         asm volatile("s_mov_b32 %0, m0\n\ts_mov_b32 m0, %3\n\ts_nop 0\n\tglobal_load_lds_dwordx4 %1, %2\n\ts_mov_b32 m0, %0" \
;             : "=&s"(keep_) : "v"((voff)[_i]), "s"((const void*)(gbase)), "s"(ldsb0 + (unsigned)(bufoff) + (unsigned)(_i * 8192)) : "memory"); } } while (0)
; #define PG8_LDA(dst, b, h) do { _Pragma("unroll") for (int m = 0; m < 4; ++m) _Pragma("unroll") for (int k = 0; k < 2; ++k) dst[m][k] = *(const LAS bf16x8*)(lds + PG8_SA(b, h) + aoff + m * 2048 + k * 1024); } while (0)
; #define PG8_LDB(dst, b, h) do { _Pragma("unroll") for (int n = 0; n < 2; ++n) _Pragma("unroll") for (int k = 0; k < 2; ++k) dst[n][k] = *(const LAS bf16x8*)(lds + PG8_SB(b, h) + boff + n * 2048 + k * 1024); } while (0)
; #define PG8_WAIT_V(n) asm volatile("s_waitcnt vmcnt(" #n ")" ::: "memory")
; #define PG8_WAIT_L(n) asm volatile("s_waitcnt lgkmcnt(" #n ")" ::: "memory")
; #define PG8_BAR __builtin_amdgcn_s_barrier()
; #define PG8_SCHED __builtin_amdgcn_sched_barrier(0)
; template <class Epi, class Sched, bool ALIGN_EPI>
; __device__ __forceinline__ void gemm_phase(LAS unsigned char* lds, const Gemm g, const Sched& S, const Epi& E) {
;     ...
;             PG8_LDB(B0, 0, 0); PG8_LDB(B1, 0, 1); PG8_SCHED; PG8_LDA(At, 0, 0); PG8_STAGE(PG8_SA(1, 1), a1 + hstepA, voffA);
;             PG8_WAIT_V(8); PG8_WAIT_L(0); PG8_BAR; PG8_MMA(0, 0, At, B0); PG8_MMA(0, 1, At, B1); PG8_BAR; PG8_SCHED;
;             PG8_LDA(At, 0, 1); PG8_STAGE(PG8_SB(0, 0), b2, voffB); PG8_STAGE(PG8_SB(0, 1), b2 + hstepB, voffB); PG8_STAGE(PG8_SA(0, 0), a2, voffA);
;             PG8_WAIT_V(8); PG8_WAIT_L(0); PG8_BAR; PG8_MMA(1, 0, At, B0); PG8_MMA(1, 1, At, B1); PG8_BAR; PG8_SCHED;
;             PG8_LDB(B0, 1, 0); PG8_LDB(B1, 1, 1); PG8_SCHED; PG8_LDA(At, 1, 0); PG8_STAGE(PG8_SA(0, 1), a2 + hstepA, voffA);
;             PG8_WAIT_V(8); PG8_WAIT_L(0); PG8_BAR; PG8_MMA(0, 0, At, B0); PG8_MMA(0, 1, At, B1); PG8_BAR; PG8_SCHED;
;             PG8_LDA(At, 1, 1); PG8_STAGE(PG8_SB(1, 0), b3, voffB); PG8_STAGE(PG8_SB(1, 1), b3 + hstepB, voffB); PG8_STAGE(PG8_SA(1, 0), a3, voffA);
;             PG8_WAIT_V(8); PG8_WAIT_L(0); PG8_BAR; PG8_MMA(1, 0, At, B0); PG8_MMA(1, 1, At, B1); PG8_BAR; PG8_SCHED;
.LBB0_1409:
	ds_read_b128 v[132:135], v146
	ds_read_b128 v[136:139], v146 offset:1024
	ds_read_b128 v[160:163], v146 offset:2048
	ds_read_b128 v[164:167], v146 offset:3072
	ds_read_b128 v[168:171], v147
	ds_read_b128 v[172:175], v147 offset:1024
	ds_read_b128 v[180:183], v147 offset:2048
	ds_read_b128 v[184:187], v147 offset:3072
	s_add_u32 s8, s4, 0x100
	s_addc_u32 s9, s5, 0
	s_cmp_eq_u32 s39, 28
	s_cselect_b32 s46, s3, s8
	s_cselect_b32 s47, s2, s9
	s_cselect_b32 s12, s7, s23
	s_cselect_b32 s13, s6, s37
	s_add_u32 s10, s46, 0x80
	s_addc_u32 s11, s47, 0
	ds_read_b128 v[188:191], v148
	ds_read_b128 v[192:195], v148 offset:1024
	ds_read_b128 v[196:199], v148 offset:2048
	ds_read_b128 v[204:207], v148 offset:3072
	ds_read_b128 v[208:211], v148 offset:4096
	ds_read_b128 v[212:215], v148 offset:5120
	ds_read_b128 v[216:219], v148 offset:6144
	ds_read_b128 v[220:223], v148 offset:7168
	s_add_u32 s4, s4, 0x80080
	s_addc_u32 s5, s5, 0
	s_mov_b32 m0, s68
	s_nop 0
	global_load_lds_dwordx4 v140, s[4:5]
	s_mov_b32 m0, s69
	s_nop 0
	global_load_lds_dwordx4 v142, s[4:5]
	s_waitcnt vmcnt(8)
	s_waitcnt lgkmcnt(0)
	s_barrier
	s_setprio 1
	v_mfma_f32_16x16x32_bf16 v[126:129], v[132:135], v[188:191], v[126:129]
	v_mfma_f32_16x16x32_bf16 v[122:125], v[160:163], v[188:191], v[122:125]
	v_mfma_f32_16x16x32_bf16 v[110:113], v[132:135], v[196:199], v[110:113]
	v_mfma_f32_16x16x32_bf16 v[106:109], v[160:163], v[196:199], v[106:109]
	v_mfma_f32_16x16x32_bf16 v[94:97], v[132:135], v[208:211], v[94:97]
	v_mfma_f32_16x16x32_bf16 v[90:93], v[160:163], v[208:211], v[90:93]
	v_mfma_f32_16x16x32_bf16 v[78:81], v[132:135], v[216:219], v[78:81]
	v_mfma_f32_16x16x32_bf16 v[74:77], v[160:163], v[216:219], v[74:77]
	v_mfma_f32_16x16x32_bf16 v[126:129], v[136:139], v[192:195], v[126:129]
	v_mfma_f32_16x16x32_bf16 v[122:125], v[164:167], v[192:195], v[122:125]
	v_mfma_f32_16x16x32_bf16 v[110:113], v[136:139], v[204:207], v[110:113]
	v_mfma_f32_16x16x32_bf16 v[106:109], v[164:167], v[204:207], v[106:109]
	v_mfma_f32_16x16x32_bf16 v[94:97], v[136:139], v[212:215], v[94:97]
	v_mfma_f32_16x16x32_bf16 v[90:93], v[164:167], v[212:215], v[90:93]
	v_mfma_f32_16x16x32_bf16 v[78:81], v[136:139], v[220:223], v[78:81]
	v_mfma_f32_16x16x32_bf16 v[74:77], v[164:167], v[220:223], v[74:77]
	v_mfma_f32_16x16x32_bf16 v[118:121], v[168:171], v[188:191], v[118:121]
	v_mfma_f32_16x16x32_bf16 v[114:117], v[180:183], v[188:191], v[114:117]
	v_mfma_f32_16x16x32_bf16 v[102:105], v[168:171], v[196:199], v[102:105]
	v_mfma_f32_16x16x32_bf16 v[98:101], v[180:183], v[196:199], v[98:101]
	v_mfma_f32_16x16x32_bf16 v[86:89], v[168:171], v[208:211], v[86:89]
	v_mfma_f32_16x16x32_bf16 v[82:85], v[180:183], v[208:211], v[82:85]
	v_mfma_f32_16x16x32_bf16 v[70:73], v[168:171], v[216:219], v[70:73]
	v_mfma_f32_16x16x32_bf16 v[66:69], v[180:183], v[216:219], v[66:69]
	v_mfma_f32_16x16x32_bf16 v[118:121], v[172:175], v[192:195], v[118:121]
	v_mfma_f32_16x16x32_bf16 v[114:117], v[184:187], v[192:195], v[114:117]
	v_mfma_f32_16x16x32_bf16 v[102:105], v[172:175], v[204:207], v[102:105]
	v_mfma_f32_16x16x32_bf16 v[98:101], v[184:187], v[204:207], v[98:101]
	v_mfma_f32_16x16x32_bf16 v[86:89], v[172:175], v[212:215], v[86:89]
	v_mfma_f32_16x16x32_bf16 v[82:85], v[184:187], v[212:215], v[82:85]
	v_mfma_f32_16x16x32_bf16 v[70:73], v[172:175], v[220:223], v[70:73]
	v_mfma_f32_16x16x32_bf16 v[66:69], v[184:187], v[220:223], v[66:69]
	s_setprio 0
	s_barrier
	ds_read_b128 v[188:191], v148 offset:16384
	ds_read_b128 v[192:195], v148 offset:17408
	ds_read_b128 v[196:199], v148 offset:18432
	ds_read_b128 v[204:207], v148 offset:19456
	ds_read_b128 v[208:211], v148 offset:20480
	ds_read_b128 v[212:215], v148 offset:21504
	ds_read_b128 v[216:219], v148 offset:22528
	ds_read_b128 v[220:223], v148 offset:23552
	s_mov_b32 m0, s53
	s_nop 0
	global_load_lds_dwordx4 v141, s[12:13]
	s_mov_b32 m0, s54
	s_nop 0
	global_load_lds_dwordx4 v143, s[12:13]
	s_add_u32 s4, s12, 0x80000
	s_addc_u32 s5, s13, 0
	s_mov_b32 m0, s55
	s_nop 0
	global_load_lds_dwordx4 v141, s[4:5]
	s_mov_b32 m0, s56
	s_nop 0
	global_load_lds_dwordx4 v143, s[4:5]
	s_mov_b32 m0, s52
	s_nop 0
	global_load_lds_dwordx4 v140, s[46:47]
	s_mov_b32 m0, s57
	s_nop 0
	global_load_lds_dwordx4 v142, s[46:47]
	s_waitcnt vmcnt(8)
	s_waitcnt lgkmcnt(0)
	s_barrier
	s_setprio 1
	v_mfma_f32_16x16x32_bf16 v[62:65], v[132:135], v[188:191], v[62:65]
	v_mfma_f32_16x16x32_bf16 v[58:61], v[160:163], v[188:191], v[58:61]
	v_mfma_f32_16x16x32_bf16 v[46:49], v[132:135], v[196:199], v[46:49]
	v_mfma_f32_16x16x32_bf16 v[42:45], v[160:163], v[196:199], v[42:45]
	v_mfma_f32_16x16x32_bf16 v[30:33], v[132:135], v[208:211], v[30:33]
	v_mfma_f32_16x16x32_bf16 v[26:29], v[160:163], v[208:211], v[26:29]
	v_mfma_f32_16x16x32_bf16 v[14:17], v[132:135], v[216:219], v[14:17]
	v_mfma_f32_16x16x32_bf16 v[10:13], v[160:163], v[216:219], v[10:13]
	v_mfma_f32_16x16x32_bf16 v[62:65], v[136:139], v[192:195], v[62:65]
	v_mfma_f32_16x16x32_bf16 v[58:61], v[164:167], v[192:195], v[58:61]
	v_mfma_f32_16x16x32_bf16 v[46:49], v[136:139], v[204:207], v[46:49]
	v_mfma_f32_16x16x32_bf16 v[42:45], v[164:167], v[204:207], v[42:45]
	v_mfma_f32_16x16x32_bf16 v[30:33], v[136:139], v[212:215], v[30:33]
	v_mfma_f32_16x16x32_bf16 v[26:29], v[164:167], v[212:215], v[26:29]
	v_mfma_f32_16x16x32_bf16 v[14:17], v[136:139], v[220:223], v[14:17]
	v_mfma_f32_16x16x32_bf16 v[10:13], v[164:167], v[220:223], v[10:13]
	v_mfma_f32_16x16x32_bf16 v[54:57], v[168:171], v[188:191], v[54:57]
	v_mfma_f32_16x16x32_bf16 v[50:53], v[180:183], v[188:191], v[50:53]
	v_mfma_f32_16x16x32_bf16 v[38:41], v[168:171], v[196:199], v[38:41]
	v_mfma_f32_16x16x32_bf16 v[34:37], v[180:183], v[196:199], v[34:37]
	v_mfma_f32_16x16x32_bf16 v[22:25], v[168:171], v[208:211], v[22:25]
	v_mfma_f32_16x16x32_bf16 v[18:21], v[180:183], v[208:211], v[18:21]
	v_mfma_f32_16x16x32_bf16 v[6:9], v[168:171], v[216:219], v[6:9]
	v_mfma_f32_16x16x32_bf16 v[2:5], v[180:183], v[216:219], v[2:5]
	v_mfma_f32_16x16x32_bf16 v[54:57], v[172:175], v[192:195], v[54:57]
	v_mfma_f32_16x16x32_bf16 v[50:53], v[184:187], v[192:195], v[50:53]
	v_mfma_f32_16x16x32_bf16 v[38:41], v[172:175], v[204:207], v[38:41]
	v_mfma_f32_16x16x32_bf16 v[34:37], v[184:187], v[204:207], v[34:37]
	v_mfma_f32_16x16x32_bf16 v[22:25], v[172:175], v[212:215], v[22:25]
	v_mfma_f32_16x16x32_bf16 v[18:21], v[184:187], v[212:215], v[18:21]
	v_mfma_f32_16x16x32_bf16 v[6:9], v[172:175], v[220:223], v[6:9]
	v_mfma_f32_16x16x32_bf16 v[2:5], v[184:187], v[220:223], v[2:5]
	s_setprio 0
	s_barrier
; #define PG8_STAGE(bufoff, gbase, voff) do { _Pragma("unroll") for (int _i = 0; _i < 2; ++_i) { unsigned keep_; \
;         asm volatile("s_mov_b32 %0, m0\n\ts_mov_b32 m0, %3\n\ts_nop 0\n\tglobal_load_lds_dwordx4 %1, %2\n\ts_mov_b32 m0, %0" \
;             : "=&s"(keep_) : "v"((voff)[_i]), "s"((const void*)(gbase)), "s"(ldsb0 + (unsigned)(bufoff) + (unsigned)(_i * 8192)) : "memory"); } } while (0)
; #define PG8_LDA(dst, b, h) do { _Pragma("unroll") for (int m = 0; m < 4; ++m) _Pragma("unroll") for (int k = 0; k < 2; ++k) dst[m][k] = *(const LAS bf16x8*)(lds + PG8_SA(b, h) + aoff + m * 2048 + k * 1024); } while (0)
; #define PG8_LDB(dst, b, h) do { _Pragma("unroll") for (int n = 0; n < 2; ++n) _Pragma("unroll") for (int k = 0; k < 2; ++k) dst[n][k] = *(const LAS bf16x8*)(lds + PG8_SB(b, h) + boff + n * 2048 + k * 1024); } while (0)
; #define PG8_WAIT_V(n) asm volatile("s_waitcnt vmcnt(" #n ")" ::: "memory")
; #define PG8_WAIT_L(n) asm volatile("s_waitcnt lgkmcnt(" #n ")" ::: "memory")
; #define PG8_BAR __builtin_amdgcn_s_barrier()
; #define PG8_SCHED __builtin_amdgcn_sched_barrier(0)
; template <class Epi, class Sched, bool ALIGN_EPI>
; __device__ __forceinline__ void gemm_phase(LAS unsigned char* lds, const Gemm g, const Sched& S, const Epi& E) {
;     ...
;             PG8_LDB(B0, 0, 0); PG8_LDB(B1, 0, 1); PG8_SCHED; PG8_LDA(At, 0, 0); PG8_STAGE(PG8_SA(1, 1), a1 + hstepA, voffA);
;             PG8_WAIT_V(8); PG8_WAIT_L(0); PG8_BAR; PG8_MMA(0, 0, At, B0); PG8_MMA(0, 1, At, B1); PG8_BAR; PG8_SCHED;
;             PG8_LDA(At, 0, 1); PG8_STAGE(PG8_SB(0, 0), b2, voffB); PG8_STAGE(PG8_SB(0, 1), b2 + hstepB, voffB); PG8_STAGE(PG8_SA(0, 0), a2, voffA);
;             PG8_WAIT_V(8); PG8_WAIT_L(0); PG8_BAR; PG8_MMA(1, 0, At, B0); PG8_MMA(1, 1, At, B1); PG8_BAR; PG8_SCHED;
;             PG8_LDB(B0, 1, 0); PG8_LDB(B1, 1, 1); PG8_SCHED; PG8_LDA(At, 1, 0); PG8_STAGE(PG8_SA(0, 1), a2 + hstepA, voffA);
;             PG8_WAIT_V(8); PG8_WAIT_L(0); PG8_BAR; PG8_MMA(0, 0, At, B0); PG8_MMA(0, 1, At, B1); PG8_BAR; PG8_SCHED;
;             PG8_LDA(At, 1, 1); PG8_STAGE(PG8_SB(1, 0), b3, voffB); PG8_STAGE(PG8_SB(1, 1), b3 + hstepB, voffB); PG8_STAGE(PG8_SA(1, 0), a3, voffA);
;             PG8_WAIT_V(8); PG8_WAIT_L(0); PG8_BAR; PG8_MMA(1, 0, At, B0); PG8_MMA(1, 1, At, B1); PG8_BAR; PG8_SCHED;
;         }
;         if constexpr (ALIGN_EPI) { if (wr == 0) PG8_BAR; }
	ds_read_b128 v[132:135], v149
	ds_read_b128 v[136:139], v149 offset:1024
	ds_read_b128 v[160:163], v149 offset:2048
	ds_read_b128 v[164:167], v149 offset:3072
	ds_read_b128 v[168:171], v150
	ds_read_b128 v[172:175], v150 offset:1024
	ds_read_b128 v[180:183], v150 offset:2048
	ds_read_b128 v[184:187], v150 offset:3072
	ds_read_b128 v[188:191], v148 offset:32768
	ds_read_b128 v[192:195], v148 offset:33792
	ds_read_b128 v[196:199], v148 offset:34816
	ds_read_b128 v[204:207], v148 offset:35840
	ds_read_b128 v[208:211], v148 offset:36864
	ds_read_b128 v[212:215], v148 offset:37888
	ds_read_b128 v[216:219], v148 offset:38912
	ds_read_b128 v[220:223], v148 offset:39936
	s_add_u32 s4, s46, 0x80000
	s_addc_u32 s5, s47, 0
	s_mov_b32 m0, s59
	s_nop 0
	global_load_lds_dwordx4 v140, s[4:5]
	s_mov_b32 m0, s61
	s_nop 0
	global_load_lds_dwordx4 v142, s[4:5]
	s_waitcnt vmcnt(8)
	s_waitcnt lgkmcnt(0)
	s_barrier
	s_setprio 1
	v_mfma_f32_16x16x32_bf16 v[126:129], v[132:135], v[188:191], v[126:129]
	v_mfma_f32_16x16x32_bf16 v[122:125], v[160:163], v[188:191], v[122:125]
	v_mfma_f32_16x16x32_bf16 v[110:113], v[132:135], v[196:199], v[110:113]
	v_mfma_f32_16x16x32_bf16 v[106:109], v[160:163], v[196:199], v[106:109]
	v_mfma_f32_16x16x32_bf16 v[94:97], v[132:135], v[208:211], v[94:97]
	v_mfma_f32_16x16x32_bf16 v[90:93], v[160:163], v[208:211], v[90:93]
	v_mfma_f32_16x16x32_bf16 v[78:81], v[132:135], v[216:219], v[78:81]
	v_mfma_f32_16x16x32_bf16 v[74:77], v[160:163], v[216:219], v[74:77]
	v_mfma_f32_16x16x32_bf16 v[126:129], v[136:139], v[192:195], v[126:129]
	v_mfma_f32_16x16x32_bf16 v[122:125], v[164:167], v[192:195], v[122:125]
	v_mfma_f32_16x16x32_bf16 v[110:113], v[136:139], v[204:207], v[110:113]
	v_mfma_f32_16x16x32_bf16 v[106:109], v[164:167], v[204:207], v[106:109]
	v_mfma_f32_16x16x32_bf16 v[94:97], v[136:139], v[212:215], v[94:97]
	v_mfma_f32_16x16x32_bf16 v[90:93], v[164:167], v[212:215], v[90:93]
	v_mfma_f32_16x16x32_bf16 v[78:81], v[136:139], v[220:223], v[78:81]
	v_mfma_f32_16x16x32_bf16 v[74:77], v[164:167], v[220:223], v[74:77]
	v_mfma_f32_16x16x32_bf16 v[118:121], v[168:171], v[188:191], v[118:121]
	v_mfma_f32_16x16x32_bf16 v[114:117], v[180:183], v[188:191], v[114:117]
	v_mfma_f32_16x16x32_bf16 v[102:105], v[168:171], v[196:199], v[102:105]
	v_mfma_f32_16x16x32_bf16 v[98:101], v[180:183], v[196:199], v[98:101]
	v_mfma_f32_16x16x32_bf16 v[86:89], v[168:171], v[208:211], v[86:89]
	v_mfma_f32_16x16x32_bf16 v[82:85], v[180:183], v[208:211], v[82:85]
	v_mfma_f32_16x16x32_bf16 v[70:73], v[168:171], v[216:219], v[70:73]
	v_mfma_f32_16x16x32_bf16 v[66:69], v[180:183], v[216:219], v[66:69]
	v_mfma_f32_16x16x32_bf16 v[118:121], v[172:175], v[192:195], v[118:121]
	v_mfma_f32_16x16x32_bf16 v[114:117], v[184:187], v[192:195], v[114:117]
	v_mfma_f32_16x16x32_bf16 v[102:105], v[172:175], v[204:207], v[102:105]
	v_mfma_f32_16x16x32_bf16 v[98:101], v[184:187], v[204:207], v[98:101]
	v_mfma_f32_16x16x32_bf16 v[86:89], v[172:175], v[212:215], v[86:89]
	v_mfma_f32_16x16x32_bf16 v[82:85], v[184:187], v[212:215], v[82:85]
	v_mfma_f32_16x16x32_bf16 v[70:73], v[172:175], v[220:223], v[70:73]
	v_mfma_f32_16x16x32_bf16 v[66:69], v[184:187], v[220:223], v[66:69]
	s_setprio 0
	s_barrier
	ds_read_b128 v[188:191], v148 offset:49152
	ds_read_b128 v[192:195], v148 offset:50176
	ds_read_b128 v[196:199], v148 offset:51200
	ds_read_b128 v[204:207], v148 offset:52224
	ds_read_b128 v[208:211], v148 offset:53248
	ds_read_b128 v[212:215], v148 offset:54272
	ds_read_b128 v[216:219], v148 offset:55296
	ds_read_b128 v[220:223], v148 offset:56320
	s_add_u32 s4, s12, 0x80
	s_addc_u32 s5, s13, 0
	s_mov_b32 m0, s62
	s_nop 0
	global_load_lds_dwordx4 v141, s[4:5]
	s_mov_b32 m0, s63
	s_nop 0
	global_load_lds_dwordx4 v143, s[4:5]
	s_add_u32 s4, s12, 0x80080
	s_addc_u32 s5, s13, 0
	s_mov_b32 m0, s66
	s_nop 0
	global_load_lds_dwordx4 v141, s[4:5]
	s_mov_b32 m0, s67
	s_nop 0
	global_load_lds_dwordx4 v143, s[4:5]
	s_mov_b32 m0, s64
	s_nop 0
	global_load_lds_dwordx4 v140, s[10:11]
	s_mov_b32 m0, s65
	s_nop 0
	global_load_lds_dwordx4 v142, s[10:11]
	s_waitcnt vmcnt(8)
	s_waitcnt lgkmcnt(0)
	s_barrier
	s_setprio 1
	v_mfma_f32_16x16x32_bf16 v[62:65], v[132:135], v[188:191], v[62:65]
	v_mfma_f32_16x16x32_bf16 v[58:61], v[160:163], v[188:191], v[58:61]
	v_mfma_f32_16x16x32_bf16 v[46:49], v[132:135], v[196:199], v[46:49]
	v_mfma_f32_16x16x32_bf16 v[42:45], v[160:163], v[196:199], v[42:45]
	v_mfma_f32_16x16x32_bf16 v[30:33], v[132:135], v[208:211], v[30:33]
	v_mfma_f32_16x16x32_bf16 v[26:29], v[160:163], v[208:211], v[26:29]
	v_mfma_f32_16x16x32_bf16 v[14:17], v[132:135], v[216:219], v[14:17]
	v_mfma_f32_16x16x32_bf16 v[10:13], v[160:163], v[216:219], v[10:13]
	v_mfma_f32_16x16x32_bf16 v[62:65], v[136:139], v[192:195], v[62:65]
	v_mfma_f32_16x16x32_bf16 v[58:61], v[164:167], v[192:195], v[58:61]
	v_mfma_f32_16x16x32_bf16 v[46:49], v[136:139], v[204:207], v[46:49]
	v_mfma_f32_16x16x32_bf16 v[42:45], v[164:167], v[204:207], v[42:45]
	v_mfma_f32_16x16x32_bf16 v[30:33], v[136:139], v[212:215], v[30:33]
	v_mfma_f32_16x16x32_bf16 v[26:29], v[164:167], v[212:215], v[26:29]
	v_mfma_f32_16x16x32_bf16 v[14:17], v[136:139], v[220:223], v[14:17]
	v_mfma_f32_16x16x32_bf16 v[10:13], v[164:167], v[220:223], v[10:13]
	v_mfma_f32_16x16x32_bf16 v[54:57], v[168:171], v[188:191], v[54:57]
	v_mfma_f32_16x16x32_bf16 v[50:53], v[180:183], v[188:191], v[50:53]
	v_mfma_f32_16x16x32_bf16 v[38:41], v[168:171], v[196:199], v[38:41]
	v_mfma_f32_16x16x32_bf16 v[34:37], v[180:183], v[196:199], v[34:37]
	v_mfma_f32_16x16x32_bf16 v[22:25], v[168:171], v[208:211], v[22:25]
	v_mfma_f32_16x16x32_bf16 v[18:21], v[180:183], v[208:211], v[18:21]
	v_mfma_f32_16x16x32_bf16 v[6:9], v[168:171], v[216:219], v[6:9]
	v_mfma_f32_16x16x32_bf16 v[2:5], v[180:183], v[216:219], v[2:5]
	v_mfma_f32_16x16x32_bf16 v[54:57], v[172:175], v[192:195], v[54:57]
	v_mfma_f32_16x16x32_bf16 v[50:53], v[184:187], v[192:195], v[50:53]
	v_mfma_f32_16x16x32_bf16 v[38:41], v[172:175], v[204:207], v[38:41]
	v_mfma_f32_16x16x32_bf16 v[34:37], v[184:187], v[204:207], v[34:37]
	v_mfma_f32_16x16x32_bf16 v[22:25], v[172:175], v[212:215], v[22:25]
	v_mfma_f32_16x16x32_bf16 v[18:21], v[184:187], v[212:215], v[18:21]
	v_mfma_f32_16x16x32_bf16 v[6:9], v[172:175], v[220:223], v[6:9]
	v_mfma_f32_16x16x32_bf16 v[2:5], v[184:187], v[220:223], v[2:5]
	s_setprio 0
	s_barrier
	s_add_i32 s39, s39, 2
	s_add_u32 s23, s23, 0x100
	s_addc_u32 s37, s37, 0
	s_cmp_gt_u32 s39, 29
	s_mov_b64 s[4:5], s[8:9]
	s_cbranch_scc0 .LBB0_1409
	s_and_b64 vcc, exec, s[34:35]
	s_cbranch_vccz .LBB0_1412
	s_barrier

; #define PG8_STAGE(bufoff, gbase, voff) do { _Pragma("unroll") for (int _i = 0; _i < 2; ++_i) { unsigned keep_; \
;         asm volatile("s_mov_b32 %0, m0\n\ts_mov_b32 m0, %3\n\ts_nop 0\n\tglobal_load_lds_dwordx4 %1, %2\n\ts_mov_b32 m0, %0" \
;             : "=&s"(keep_) : "v"((voff)[_i]), "s"((const void*)(gbase)), "s"(ldsb0 + (unsigned)(bufoff) + (unsigned)(_i * 8192)) : "memory"); } } while (0)
; #define PG8_LDA(dst, b, h) do { _Pragma("unroll") for (int m = 0; m < 4; ++m) _Pragma("unroll") for (int k = 0; k < 2; ++k) dst[m][k] = *(const LAS bf16x8*)(lds + PG8_SA(b, h) + aoff + m * 2048 + k * 1024); } while (0)
; #define PG8_LDB(dst, b, h) do { _Pragma("unroll") for (int n = 0; n < 2; ++n) _Pragma("unroll") for (int k = 0; k < 2; ++k) dst[n][k] = *(const LAS bf16x8*)(lds + PG8_SB(b, h) + boff + n * 2048 + k * 1024); } while (0)
; #define PG8_WAIT_V(n) asm volatile("s_waitcnt vmcnt(" #n ")" ::: "memory")
; #define PG8_WAIT_L(n) asm volatile("s_waitcnt lgkmcnt(" #n ")" ::: "memory")
; #define PG8_BAR __builtin_amdgcn_s_barrier()
; #define PG8_SCHED __builtin_amdgcn_sched_barrier(0)
; template <class Epi, class Sched, bool ALIGN_EPI>
; __device__ __forceinline__ void gemm_phase(LAS unsigned char* lds, const Gemm g, const Sched& S, const Epi& E) {
;     ...
;             PG8_LDB(B0, 0, 0); PG8_LDB(B1, 0, 1); PG8_SCHED; PG8_LDA(At, 0, 0); PG8_STAGE(PG8_SA(1, 1), a1 + hstepA, voffA);
;             PG8_WAIT_V(8); PG8_WAIT_L(0); PG8_BAR; PG8_MMA(0, 0, At, B0); PG8_MMA(0, 1, At, B1); PG8_BAR; PG8_SCHED;
;             PG8_LDA(At, 0, 1); PG8_STAGE(PG8_SB(0, 0), b2, voffB); PG8_STAGE(PG8_SB(0, 1), b2 + hstepB, voffB); PG8_STAGE(PG8_SA(0, 0), a2, voffA);
;             PG8_WAIT_V(8); PG8_WAIT_L(0); PG8_BAR; PG8_MMA(1, 0, At, B0); PG8_MMA(1, 1, At, B1); PG8_BAR; PG8_SCHED;
;             PG8_LDB(B0, 1, 0); PG8_LDB(B1, 1, 1); PG8_SCHED; PG8_LDA(At, 1, 0); PG8_STAGE(PG8_SA(0, 1), a2 + hstepA, voffA);
;             PG8_WAIT_V(8); PG8_WAIT_L(0); PG8_BAR; PG8_MMA(0, 0, At, B0); PG8_MMA(0, 1, At, B1); PG8_BAR; PG8_SCHED;
;             PG8_LDA(At, 1, 1); PG8_STAGE(PG8_SB(1, 0), b3, voffB); PG8_STAGE(PG8_SB(1, 1), b3 + hstepB, voffB); PG8_STAGE(PG8_SA(1, 0), a3, voffA);
;             PG8_WAIT_V(8); PG8_WAIT_L(0); PG8_BAR; PG8_MMA(1, 0, At, B0); PG8_MMA(1, 1, At, B1); PG8_BAR; PG8_SCHED;
.LBB0_1994:
	ds_read_b128 v[110:113], v206
	ds_read_b128 v[126:129], v206 offset:1024
	ds_read_b128 v[130:133], v206 offset:2048
	ds_read_b128 v[142:145], v206 offset:3072
	ds_read_b128 v[146:149], v207
	ds_read_b128 v[150:153], v207 offset:1024
	ds_read_b128 v[154:157], v207 offset:2048
	ds_read_b128 v[158:161], v207 offset:3072
	s_cmp_eq_u32 s59, 28
	s_cselect_b32 s34, s5, s19
	s_cselect_b32 s35, s3, s21
	s_cselect_b32 s30, s7, s57
	s_cselect_b32 s31, s6, s58
	s_add_u32 s28, s34, 0x80
	s_addc_u32 s29, s35, 0
	ds_read_b128 v[162:165], v208
	ds_read_b128 v[166:169], v208 offset:1024
	ds_read_b128 v[170:173], v208 offset:2048
	ds_read_b128 v[174:177], v208 offset:3072
	ds_read_b128 v[188:191], v208 offset:4096
	ds_read_b128 v[192:195], v208 offset:5120
	ds_read_b128 v[196:199], v208 offset:6144
	ds_read_b128 v[212:215], v208 offset:7168
	s_mov_b32 m0, s55
	s_nop 0
	global_load_lds_dwordx4 v179, s[26:27]
	s_mov_b32 m0, s56
	s_nop 0
	global_load_lds_dwordx4 v201, s[26:27]
	s_waitcnt vmcnt(8)
	s_waitcnt lgkmcnt(0)
	s_barrier
	s_setprio 1
	v_mfma_f32_16x16x32_bf16 v[138:141], v[110:113], v[162:165], v[138:141]
	v_mfma_f32_16x16x32_bf16 v[134:137], v[130:133], v[162:165], v[134:137]
	v_mfma_f32_16x16x32_bf16 v[114:117], v[110:113], v[170:173], v[114:117]
	v_mfma_f32_16x16x32_bf16 v[106:109], v[130:133], v[170:173], v[106:109]
	v_mfma_f32_16x16x32_bf16 v[94:97], v[110:113], v[188:191], v[94:97]
	v_mfma_f32_16x16x32_bf16 v[90:93], v[130:133], v[188:191], v[90:93]
	v_mfma_f32_16x16x32_bf16 v[78:81], v[110:113], v[196:199], v[78:81]
	v_mfma_f32_16x16x32_bf16 v[74:77], v[130:133], v[196:199], v[74:77]
	v_mfma_f32_16x16x32_bf16 v[138:141], v[126:129], v[166:169], v[138:141]
	v_mfma_f32_16x16x32_bf16 v[134:137], v[142:145], v[166:169], v[134:137]
	v_mfma_f32_16x16x32_bf16 v[114:117], v[126:129], v[174:177], v[114:117]
	v_mfma_f32_16x16x32_bf16 v[106:109], v[142:145], v[174:177], v[106:109]
	v_mfma_f32_16x16x32_bf16 v[94:97], v[126:129], v[192:195], v[94:97]
	v_mfma_f32_16x16x32_bf16 v[90:93], v[142:145], v[192:195], v[90:93]
	v_mfma_f32_16x16x32_bf16 v[78:81], v[126:129], v[212:215], v[78:81]
	v_mfma_f32_16x16x32_bf16 v[74:77], v[142:145], v[212:215], v[74:77]
	v_mfma_f32_16x16x32_bf16 v[122:125], v[146:149], v[162:165], v[122:125]
	v_mfma_f32_16x16x32_bf16 v[118:121], v[154:157], v[162:165], v[118:121]
	v_mfma_f32_16x16x32_bf16 v[102:105], v[146:149], v[170:173], v[102:105]
	v_mfma_f32_16x16x32_bf16 v[98:101], v[154:157], v[170:173], v[98:101]
	v_mfma_f32_16x16x32_bf16 v[86:89], v[146:149], v[188:191], v[86:89]
	v_mfma_f32_16x16x32_bf16 v[82:85], v[154:157], v[188:191], v[82:85]
	v_mfma_f32_16x16x32_bf16 v[70:73], v[146:149], v[196:199], v[70:73]
	v_mfma_f32_16x16x32_bf16 v[66:69], v[154:157], v[196:199], v[66:69]
	v_mfma_f32_16x16x32_bf16 v[122:125], v[150:153], v[166:169], v[122:125]
	v_mfma_f32_16x16x32_bf16 v[118:121], v[158:161], v[166:169], v[118:121]
	v_mfma_f32_16x16x32_bf16 v[102:105], v[150:153], v[174:177], v[102:105]
	v_mfma_f32_16x16x32_bf16 v[98:101], v[158:161], v[174:177], v[98:101]
	v_mfma_f32_16x16x32_bf16 v[86:89], v[150:153], v[192:195], v[86:89]
	v_mfma_f32_16x16x32_bf16 v[82:85], v[158:161], v[192:195], v[82:85]
	v_mfma_f32_16x16x32_bf16 v[70:73], v[150:153], v[212:215], v[70:73]
	v_mfma_f32_16x16x32_bf16 v[66:69], v[158:161], v[212:215], v[66:69]
	s_setprio 0
	s_barrier
	ds_read_b128 v[162:165], v208 offset:16384
	ds_read_b128 v[166:169], v208 offset:17408
	ds_read_b128 v[170:173], v208 offset:18432
	ds_read_b128 v[174:177], v208 offset:19456
	ds_read_b128 v[188:191], v208 offset:20480
	ds_read_b128 v[192:195], v208 offset:21504
	ds_read_b128 v[196:199], v208 offset:22528
	ds_read_b128 v[212:215], v208 offset:23552
	s_mov_b32 m0, s42
	s_nop 0
	global_load_lds_dwordx4 v200, s[30:31]
	s_mov_b32 m0, s43
	s_nop 0
	global_load_lds_dwordx4 v203, s[30:31]
	s_add_u32 s60, s30, 0x80000
	s_addc_u32 s61, s31, 0
	s_mov_b32 m0, s44
	s_nop 0
	global_load_lds_dwordx4 v200, s[60:61]
	s_mov_b32 m0, s45
	s_nop 0
	global_load_lds_dwordx4 v203, s[60:61]
	s_mov_b32 m0, s41
	s_nop 0
	global_load_lds_dwordx4 v179, s[34:35]
	s_mov_b32 m0, s46
	s_nop 0
	global_load_lds_dwordx4 v201, s[34:35]
	s_waitcnt vmcnt(8)
	s_waitcnt lgkmcnt(0)
	s_barrier
	s_setprio 1
	v_mfma_f32_16x16x32_bf16 v[62:65], v[110:113], v[162:165], v[62:65]
	v_mfma_f32_16x16x32_bf16 v[58:61], v[130:133], v[162:165], v[58:61]
	v_mfma_f32_16x16x32_bf16 v[46:49], v[110:113], v[170:173], v[46:49]
	v_mfma_f32_16x16x32_bf16 v[42:45], v[130:133], v[170:173], v[42:45]
	v_mfma_f32_16x16x32_bf16 v[30:33], v[110:113], v[188:191], v[30:33]
	v_mfma_f32_16x16x32_bf16 v[26:29], v[130:133], v[188:191], v[26:29]
	v_mfma_f32_16x16x32_bf16 v[14:17], v[110:113], v[196:199], v[14:17]
	v_mfma_f32_16x16x32_bf16 v[10:13], v[130:133], v[196:199], v[10:13]
	v_mfma_f32_16x16x32_bf16 v[62:65], v[126:129], v[166:169], v[62:65]
	v_mfma_f32_16x16x32_bf16 v[58:61], v[142:145], v[166:169], v[58:61]
	v_mfma_f32_16x16x32_bf16 v[46:49], v[126:129], v[174:177], v[46:49]
	v_mfma_f32_16x16x32_bf16 v[42:45], v[142:145], v[174:177], v[42:45]
	v_mfma_f32_16x16x32_bf16 v[30:33], v[126:129], v[192:195], v[30:33]
	v_mfma_f32_16x16x32_bf16 v[26:29], v[142:145], v[192:195], v[26:29]
	v_mfma_f32_16x16x32_bf16 v[14:17], v[126:129], v[212:215], v[14:17]
	v_mfma_f32_16x16x32_bf16 v[10:13], v[142:145], v[212:215], v[10:13]
	v_mfma_f32_16x16x32_bf16 v[54:57], v[146:149], v[162:165], v[54:57]
	v_mfma_f32_16x16x32_bf16 v[50:53], v[154:157], v[162:165], v[50:53]
	v_mfma_f32_16x16x32_bf16 v[38:41], v[146:149], v[170:173], v[38:41]
	v_mfma_f32_16x16x32_bf16 v[34:37], v[154:157], v[170:173], v[34:37]
	v_mfma_f32_16x16x32_bf16 v[22:25], v[146:149], v[188:191], v[22:25]
	v_mfma_f32_16x16x32_bf16 v[18:21], v[154:157], v[188:191], v[18:21]
	v_mfma_f32_16x16x32_bf16 v[6:9], v[146:149], v[196:199], v[6:9]
	v_mfma_f32_16x16x32_bf16 v[2:5], v[154:157], v[196:199], v[2:5]
	v_mfma_f32_16x16x32_bf16 v[54:57], v[150:153], v[166:169], v[54:57]
	v_mfma_f32_16x16x32_bf16 v[50:53], v[158:161], v[166:169], v[50:53]
	v_mfma_f32_16x16x32_bf16 v[38:41], v[150:153], v[174:177], v[38:41]
	v_mfma_f32_16x16x32_bf16 v[34:37], v[158:161], v[174:177], v[34:37]
	v_mfma_f32_16x16x32_bf16 v[22:25], v[150:153], v[192:195], v[22:25]
	v_mfma_f32_16x16x32_bf16 v[18:21], v[158:161], v[192:195], v[18:21]
	v_mfma_f32_16x16x32_bf16 v[6:9], v[150:153], v[212:215], v[6:9]
	v_mfma_f32_16x16x32_bf16 v[2:5], v[158:161], v[212:215], v[2:5]
	s_setprio 0
	s_barrier
; #define PG8_STAGE(bufoff, gbase, voff) do { _Pragma("unroll") for (int _i = 0; _i < 2; ++_i) { unsigned keep_; \
;         asm volatile("s_mov_b32 %0, m0\n\ts_mov_b32 m0, %3\n\ts_nop 0\n\tglobal_load_lds_dwordx4 %1, %2\n\ts_mov_b32 m0, %0" \
;             : "=&s"(keep_) : "v"((voff)[_i]), "s"((const void*)(gbase)), "s"(ldsb0 + (unsigned)(bufoff) + (unsigned)(_i * 8192)) : "memory"); } } while (0)
; #define PG8_LDA(dst, b, h) do { _Pragma("unroll") for (int m = 0; m < 4; ++m) _Pragma("unroll") for (int k = 0; k < 2; ++k) dst[m][k] = *(const LAS bf16x8*)(lds + PG8_SA(b, h) + aoff + m * 2048 + k * 1024); } while (0)
; #define PG8_LDB(dst, b, h) do { _Pragma("unroll") for (int n = 0; n < 2; ++n) _Pragma("unroll") for (int k = 0; k < 2; ++k) dst[n][k] = *(const LAS bf16x8*)(lds + PG8_SB(b, h) + boff + n * 2048 + k * 1024); } while (0)
; #define PG8_WAIT_V(n) asm volatile("s_waitcnt vmcnt(" #n ")" ::: "memory")
; #define PG8_WAIT_L(n) asm volatile("s_waitcnt lgkmcnt(" #n ")" ::: "memory")
; #define PG8_BAR __builtin_amdgcn_s_barrier()
; #define PG8_SCHED __builtin_amdgcn_sched_barrier(0)
; template <class Epi, class Sched, bool ALIGN_EPI>
; __device__ __forceinline__ void gemm_phase(LAS unsigned char* lds, const Gemm g, const Sched& S, const Epi& E) {
;     ...
;             PG8_LDB(B0, 0, 0); PG8_LDB(B1, 0, 1); PG8_SCHED; PG8_LDA(At, 0, 0); PG8_STAGE(PG8_SA(1, 1), a1 + hstepA, voffA);
;             PG8_WAIT_V(8); PG8_WAIT_L(0); PG8_BAR; PG8_MMA(0, 0, At, B0); PG8_MMA(0, 1, At, B1); PG8_BAR; PG8_SCHED;
;             PG8_LDA(At, 0, 1); PG8_STAGE(PG8_SB(0, 0), b2, voffB); PG8_STAGE(PG8_SB(0, 1), b2 + hstepB, voffB); PG8_STAGE(PG8_SA(0, 0), a2, voffA);
;             PG8_WAIT_V(8); PG8_WAIT_L(0); PG8_BAR; PG8_MMA(1, 0, At, B0); PG8_MMA(1, 1, At, B1); PG8_BAR; PG8_SCHED;
;             PG8_LDB(B0, 1, 0); PG8_LDB(B1, 1, 1); PG8_SCHED; PG8_LDA(At, 1, 0); PG8_STAGE(PG8_SA(0, 1), a2 + hstepA, voffA);
;             PG8_WAIT_V(8); PG8_WAIT_L(0); PG8_BAR; PG8_MMA(0, 0, At, B0); PG8_MMA(0, 1, At, B1); PG8_BAR; PG8_SCHED;
;             PG8_LDA(At, 1, 1); PG8_STAGE(PG8_SB(1, 0), b3, voffB); PG8_STAGE(PG8_SB(1, 1), b3 + hstepB, voffB); PG8_STAGE(PG8_SA(1, 0), a3, voffA);
;             PG8_WAIT_V(8); PG8_WAIT_L(0); PG8_BAR; PG8_MMA(1, 0, At, B0); PG8_MMA(1, 1, At, B1); PG8_BAR; PG8_SCHED;
;         }
;         if constexpr (ALIGN_EPI) { if (wr == 0) PG8_BAR; }
	ds_read_b128 v[110:113], v209
	ds_read_b128 v[126:129], v209 offset:1024
	ds_read_b128 v[130:133], v209 offset:2048
	ds_read_b128 v[142:145], v209 offset:3072
	ds_read_b128 v[146:149], v210
	ds_read_b128 v[150:153], v210 offset:1024
	ds_read_b128 v[154:157], v210 offset:2048
	ds_read_b128 v[158:161], v210 offset:3072
	ds_read_b128 v[162:165], v208 offset:32768
	ds_read_b128 v[166:169], v208 offset:33792
	ds_read_b128 v[170:173], v208 offset:34816
	ds_read_b128 v[174:177], v208 offset:35840
	ds_read_b128 v[188:191], v208 offset:36864
	ds_read_b128 v[192:195], v208 offset:37888
	ds_read_b128 v[196:199], v208 offset:38912
	ds_read_b128 v[212:215], v208 offset:39936
	s_add_u32 s34, s34, 0x80000
	s_addc_u32 s35, s35, 0
	s_mov_b32 m0, s47
	s_nop 0
	global_load_lds_dwordx4 v179, s[34:35]
	s_mov_b32 m0, s48
	s_nop 0
	global_load_lds_dwordx4 v201, s[34:35]
	s_waitcnt vmcnt(8)
	s_waitcnt lgkmcnt(0)
	s_barrier
	s_setprio 1
	v_mfma_f32_16x16x32_bf16 v[138:141], v[110:113], v[162:165], v[138:141]
	v_mfma_f32_16x16x32_bf16 v[134:137], v[130:133], v[162:165], v[134:137]
	v_mfma_f32_16x16x32_bf16 v[114:117], v[110:113], v[170:173], v[114:117]
	v_mfma_f32_16x16x32_bf16 v[106:109], v[130:133], v[170:173], v[106:109]
	v_mfma_f32_16x16x32_bf16 v[94:97], v[110:113], v[188:191], v[94:97]
	v_mfma_f32_16x16x32_bf16 v[90:93], v[130:133], v[188:191], v[90:93]
	v_mfma_f32_16x16x32_bf16 v[78:81], v[110:113], v[196:199], v[78:81]
	v_mfma_f32_16x16x32_bf16 v[74:77], v[130:133], v[196:199], v[74:77]
	v_mfma_f32_16x16x32_bf16 v[138:141], v[126:129], v[166:169], v[138:141]
	v_mfma_f32_16x16x32_bf16 v[134:137], v[142:145], v[166:169], v[134:137]
	v_mfma_f32_16x16x32_bf16 v[114:117], v[126:129], v[174:177], v[114:117]
	v_mfma_f32_16x16x32_bf16 v[106:109], v[142:145], v[174:177], v[106:109]
	v_mfma_f32_16x16x32_bf16 v[94:97], v[126:129], v[192:195], v[94:97]
	v_mfma_f32_16x16x32_bf16 v[90:93], v[142:145], v[192:195], v[90:93]
	v_mfma_f32_16x16x32_bf16 v[78:81], v[126:129], v[212:215], v[78:81]
	v_mfma_f32_16x16x32_bf16 v[74:77], v[142:145], v[212:215], v[74:77]
	v_mfma_f32_16x16x32_bf16 v[122:125], v[146:149], v[162:165], v[122:125]
	v_mfma_f32_16x16x32_bf16 v[118:121], v[154:157], v[162:165], v[118:121]
	v_mfma_f32_16x16x32_bf16 v[102:105], v[146:149], v[170:173], v[102:105]
	v_mfma_f32_16x16x32_bf16 v[98:101], v[154:157], v[170:173], v[98:101]
	v_mfma_f32_16x16x32_bf16 v[86:89], v[146:149], v[188:191], v[86:89]
	v_mfma_f32_16x16x32_bf16 v[82:85], v[154:157], v[188:191], v[82:85]
	v_mfma_f32_16x16x32_bf16 v[70:73], v[146:149], v[196:199], v[70:73]
	v_mfma_f32_16x16x32_bf16 v[66:69], v[154:157], v[196:199], v[66:69]
	v_mfma_f32_16x16x32_bf16 v[122:125], v[150:153], v[166:169], v[122:125]
	v_mfma_f32_16x16x32_bf16 v[118:121], v[158:161], v[166:169], v[118:121]
	v_mfma_f32_16x16x32_bf16 v[102:105], v[150:153], v[174:177], v[102:105]
	v_mfma_f32_16x16x32_bf16 v[98:101], v[158:161], v[174:177], v[98:101]
	v_mfma_f32_16x16x32_bf16 v[86:89], v[150:153], v[192:195], v[86:89]
	v_mfma_f32_16x16x32_bf16 v[82:85], v[158:161], v[192:195], v[82:85]
	v_mfma_f32_16x16x32_bf16 v[70:73], v[150:153], v[212:215], v[70:73]
	v_mfma_f32_16x16x32_bf16 v[66:69], v[158:161], v[212:215], v[66:69]
	s_setprio 0
	s_barrier
	ds_read_b128 v[162:165], v208 offset:49152
	ds_read_b128 v[166:169], v208 offset:50176
	ds_read_b128 v[170:173], v208 offset:51200
	ds_read_b128 v[174:177], v208 offset:52224
	ds_read_b128 v[188:191], v208 offset:53248
	ds_read_b128 v[192:195], v208 offset:54272
	ds_read_b128 v[196:199], v208 offset:55296
	ds_read_b128 v[212:215], v208 offset:56320
	s_add_u32 s34, s30, 0x80
	s_addc_u32 s35, s31, 0
	s_mov_b32 m0, s49
	s_nop 0
	global_load_lds_dwordx4 v200, s[34:35]
	s_add_u32 s30, s30, 0x80080
	s_mov_b32 m0, s50
	s_nop 0
	global_load_lds_dwordx4 v203, s[34:35]
	s_addc_u32 s31, s31, 0
	s_mov_b32 m0, s53
	s_nop 0
	global_load_lds_dwordx4 v200, s[30:31]
	s_mov_b32 m0, s54
	s_nop 0
	global_load_lds_dwordx4 v203, s[30:31]
	s_mov_b32 m0, s51
	s_nop 0
	global_load_lds_dwordx4 v179, s[28:29]
	s_mov_b32 m0, s52
	s_nop 0
	global_load_lds_dwordx4 v201, s[28:29]
	s_waitcnt vmcnt(8)
	s_waitcnt lgkmcnt(0)
	s_barrier
	s_setprio 1
	v_mfma_f32_16x16x32_bf16 v[62:65], v[110:113], v[162:165], v[62:65]
	v_mfma_f32_16x16x32_bf16 v[58:61], v[130:133], v[162:165], v[58:61]
	v_mfma_f32_16x16x32_bf16 v[46:49], v[110:113], v[170:173], v[46:49]
	v_mfma_f32_16x16x32_bf16 v[42:45], v[130:133], v[170:173], v[42:45]
	v_mfma_f32_16x16x32_bf16 v[30:33], v[110:113], v[188:191], v[30:33]
	v_mfma_f32_16x16x32_bf16 v[26:29], v[130:133], v[188:191], v[26:29]
	v_mfma_f32_16x16x32_bf16 v[14:17], v[110:113], v[196:199], v[14:17]
	v_mfma_f32_16x16x32_bf16 v[10:13], v[130:133], v[196:199], v[10:13]
	v_mfma_f32_16x16x32_bf16 v[62:65], v[126:129], v[166:169], v[62:65]
	v_mfma_f32_16x16x32_bf16 v[58:61], v[142:145], v[166:169], v[58:61]
	v_mfma_f32_16x16x32_bf16 v[46:49], v[126:129], v[174:177], v[46:49]
	v_mfma_f32_16x16x32_bf16 v[42:45], v[142:145], v[174:177], v[42:45]
	v_mfma_f32_16x16x32_bf16 v[30:33], v[126:129], v[192:195], v[30:33]
	v_mfma_f32_16x16x32_bf16 v[26:29], v[142:145], v[192:195], v[26:29]
	v_mfma_f32_16x16x32_bf16 v[14:17], v[126:129], v[212:215], v[14:17]
	v_mfma_f32_16x16x32_bf16 v[10:13], v[142:145], v[212:215], v[10:13]
	v_mfma_f32_16x16x32_bf16 v[54:57], v[146:149], v[162:165], v[54:57]
	v_mfma_f32_16x16x32_bf16 v[50:53], v[154:157], v[162:165], v[50:53]
	v_mfma_f32_16x16x32_bf16 v[38:41], v[146:149], v[170:173], v[38:41]
	v_mfma_f32_16x16x32_bf16 v[34:37], v[154:157], v[170:173], v[34:37]
	v_mfma_f32_16x16x32_bf16 v[22:25], v[146:149], v[188:191], v[22:25]
	v_mfma_f32_16x16x32_bf16 v[18:21], v[154:157], v[188:191], v[18:21]
	v_mfma_f32_16x16x32_bf16 v[6:9], v[146:149], v[196:199], v[6:9]
	v_mfma_f32_16x16x32_bf16 v[2:5], v[154:157], v[196:199], v[2:5]
	v_mfma_f32_16x16x32_bf16 v[54:57], v[150:153], v[166:169], v[54:57]
	v_mfma_f32_16x16x32_bf16 v[50:53], v[158:161], v[166:169], v[50:53]
	v_mfma_f32_16x16x32_bf16 v[38:41], v[150:153], v[174:177], v[38:41]
	v_mfma_f32_16x16x32_bf16 v[34:37], v[158:161], v[174:177], v[34:37]
	v_mfma_f32_16x16x32_bf16 v[22:25], v[150:153], v[192:195], v[22:25]
	v_mfma_f32_16x16x32_bf16 v[18:21], v[158:161], v[192:195], v[18:21]
	v_mfma_f32_16x16x32_bf16 v[6:9], v[150:153], v[212:215], v[6:9]
	v_mfma_f32_16x16x32_bf16 v[2:5], v[158:161], v[212:215], v[2:5]
	s_setprio 0
	s_barrier
	s_add_i32 s59, s59, 2
	s_add_u32 s19, s19, 0x100
	s_addc_u32 s21, s21, 0
	s_add_u32 s57, s57, 0x100
	s_addc_u32 s58, s58, 0
	s_add_u32 s26, s26, 0x100
	s_addc_u32 s27, s27, 0
	s_cmp_gt_u32 s59, 29
	s_cbranch_scc0 .LBB0_1994
	s_and_b64 vcc, exec, s[16:17]
	s_cbranch_vccz .LBB0_1997
	s_barrier

; #define PG8_STAGE(bufoff, gbase, voff) do { _Pragma("unroll") for (int _i = 0; _i < 2; ++_i) { unsigned keep_; \
;         asm volatile("s_mov_b32 %0, m0\n\ts_mov_b32 m0, %3\n\ts_nop 0\n\tglobal_load_lds_dwordx4 %1, %2\n\ts_mov_b32 m0, %0" \
;             : "=&s"(keep_) : "v"((voff)[_i]), "s"((const void*)(gbase)), "s"(ldsb0 + (unsigned)(bufoff) + (unsigned)(_i * 8192)) : "memory"); } } while (0)
; #define PG8_LDA(dst, b, h) do { _Pragma("unroll") for (int m = 0; m < 4; ++m) _Pragma("unroll") for (int k = 0; k < 2; ++k) dst[m][k] = *(const LAS bf16x8*)(lds + PG8_SA(b, h) + aoff + m * 2048 + k * 1024); } while (0)
; #define PG8_LDB(dst, b, h) do { _Pragma("unroll") for (int n = 0; n < 2; ++n) _Pragma("unroll") for (int k = 0; k < 2; ++k) dst[n][k] = *(const LAS bf16x8*)(lds + PG8_SB(b, h) + boff + n * 2048 + k * 1024); } while (0)
; #define PG8_WAIT_V(n) asm volatile("s_waitcnt vmcnt(" #n ")" ::: "memory")
; #define PG8_WAIT_L(n) asm volatile("s_waitcnt lgkmcnt(" #n ")" ::: "memory")
; #define PG8_BAR __builtin_amdgcn_s_barrier()
; #define PG8_SCHED __builtin_amdgcn_sched_barrier(0)
; template <class Epi, class Sched, bool ALIGN_EPI>
; __device__ __forceinline__ void gemm_phase(LAS unsigned char* lds, const Gemm g, const Sched& S, const Epi& E) {
;     ...
;             PG8_LDB(B0, 0, 0); PG8_LDB(B1, 0, 1); PG8_SCHED; PG8_LDA(At, 0, 0); PG8_STAGE(PG8_SA(1, 1), a1 + hstepA, voffA);
;             PG8_WAIT_V(8); PG8_WAIT_L(0); PG8_BAR; PG8_MMA(0, 0, At, B0); PG8_MMA(0, 1, At, B1); PG8_BAR; PG8_SCHED;
;             PG8_LDA(At, 0, 1); PG8_STAGE(PG8_SB(0, 0), b2, voffB); PG8_STAGE(PG8_SB(0, 1), b2 + hstepB, voffB); PG8_STAGE(PG8_SA(0, 0), a2, voffA);
;             PG8_WAIT_V(8); PG8_WAIT_L(0); PG8_BAR; PG8_MMA(1, 0, At, B0); PG8_MMA(1, 1, At, B1); PG8_BAR; PG8_SCHED;
;             PG8_LDB(B0, 1, 0); PG8_LDB(B1, 1, 1); PG8_SCHED; PG8_LDA(At, 1, 0); PG8_STAGE(PG8_SA(0, 1), a2 + hstepA, voffA);
;             PG8_WAIT_V(8); PG8_WAIT_L(0); PG8_BAR; PG8_MMA(0, 0, At, B0); PG8_MMA(0, 1, At, B1); PG8_BAR; PG8_SCHED;
;             PG8_LDA(At, 1, 1); PG8_STAGE(PG8_SB(1, 0), b3, voffB); PG8_STAGE(PG8_SB(1, 1), b3 + hstepB, voffB); PG8_STAGE(PG8_SA(1, 0), a3, voffA);
;             PG8_WAIT_V(8); PG8_WAIT_L(0); PG8_BAR; PG8_MMA(1, 0, At, B0); PG8_MMA(1, 1, At, B1); PG8_BAR; PG8_SCHED;
.LBB0_2075:
	ds_read_b128 v[154:157], v141
	ds_read_b128 v[158:161], v141 offset:1024
	ds_read_b128 v[162:165], v141 offset:2048
	ds_read_b128 v[166:169], v141 offset:3072
	ds_read_b128 v[170:173], v142
	ds_read_b128 v[174:177], v142 offset:1024
	ds_read_b128 v[180:183], v142 offset:2048
	ds_read_b128 v[184:187], v142 offset:3072
	s_add_u32 s28, s26, 0x100
	s_addc_u32 s29, s27, 0
	s_cmp_eq_u32 s60, 28
	s_cselect_b32 s36, s5, s28
	s_cselect_b32 s37, s3, s29
	s_cselect_b32 s34, s7, s19
	s_cselect_b32 s35, s6, s21
	s_add_u32 s30, s36, 0x80
	s_addc_u32 s31, s37, 0
	ds_read_b128 v[188:191], v143
	ds_read_b128 v[192:195], v143 offset:1024
	ds_read_b128 v[196:199], v143 offset:2048
	ds_read_b128 v[204:207], v143 offset:3072
	ds_read_b128 v[208:211], v143 offset:4096
	ds_read_b128 v[212:215], v143 offset:5120
	ds_read_b128 v[216:219], v143 offset:6144
	ds_read_b128 v[220:223], v143 offset:7168
	s_add_u32 s26, s26, 0x80080
	s_addc_u32 s27, s27, 0
	s_mov_b32 m0, s57
	s_nop 0
	global_load_lds_dwordx4 v134, s[26:27]
	s_mov_b32 m0, s58
	s_nop 0
	global_load_lds_dwordx4 v136, s[26:27]
	s_waitcnt vmcnt(8)
	s_waitcnt lgkmcnt(0)
	s_barrier
	s_setprio 1
	v_mfma_f32_16x16x32_bf16 v[126:129], v[154:157], v[188:191], v[126:129]
	v_mfma_f32_16x16x32_bf16 v[122:125], v[162:165], v[188:191], v[122:125]
	v_mfma_f32_16x16x32_bf16 v[110:113], v[154:157], v[196:199], v[110:113]
	v_mfma_f32_16x16x32_bf16 v[106:109], v[162:165], v[196:199], v[106:109]
	v_mfma_f32_16x16x32_bf16 v[94:97], v[154:157], v[208:211], v[94:97]
	v_mfma_f32_16x16x32_bf16 v[90:93], v[162:165], v[208:211], v[90:93]
	v_mfma_f32_16x16x32_bf16 v[78:81], v[154:157], v[216:219], v[78:81]
	v_mfma_f32_16x16x32_bf16 v[74:77], v[162:165], v[216:219], v[74:77]
	v_mfma_f32_16x16x32_bf16 v[126:129], v[158:161], v[192:195], v[126:129]
	v_mfma_f32_16x16x32_bf16 v[122:125], v[166:169], v[192:195], v[122:125]
	v_mfma_f32_16x16x32_bf16 v[110:113], v[158:161], v[204:207], v[110:113]
	v_mfma_f32_16x16x32_bf16 v[106:109], v[166:169], v[204:207], v[106:109]
	v_mfma_f32_16x16x32_bf16 v[94:97], v[158:161], v[212:215], v[94:97]
	v_mfma_f32_16x16x32_bf16 v[90:93], v[166:169], v[212:215], v[90:93]
	v_mfma_f32_16x16x32_bf16 v[78:81], v[158:161], v[220:223], v[78:81]
	v_mfma_f32_16x16x32_bf16 v[74:77], v[166:169], v[220:223], v[74:77]
	v_mfma_f32_16x16x32_bf16 v[118:121], v[170:173], v[188:191], v[118:121]
	v_mfma_f32_16x16x32_bf16 v[114:117], v[180:183], v[188:191], v[114:117]
	v_mfma_f32_16x16x32_bf16 v[102:105], v[170:173], v[196:199], v[102:105]
	v_mfma_f32_16x16x32_bf16 v[98:101], v[180:183], v[196:199], v[98:101]
	v_mfma_f32_16x16x32_bf16 v[86:89], v[170:173], v[208:211], v[86:89]
	v_mfma_f32_16x16x32_bf16 v[82:85], v[180:183], v[208:211], v[82:85]
	v_mfma_f32_16x16x32_bf16 v[70:73], v[170:173], v[216:219], v[70:73]
	v_mfma_f32_16x16x32_bf16 v[66:69], v[180:183], v[216:219], v[66:69]
	v_mfma_f32_16x16x32_bf16 v[118:121], v[174:177], v[192:195], v[118:121]
	v_mfma_f32_16x16x32_bf16 v[114:117], v[184:187], v[192:195], v[114:117]
	v_mfma_f32_16x16x32_bf16 v[102:105], v[174:177], v[204:207], v[102:105]
	v_mfma_f32_16x16x32_bf16 v[98:101], v[184:187], v[204:207], v[98:101]
	v_mfma_f32_16x16x32_bf16 v[86:89], v[174:177], v[212:215], v[86:89]
	v_mfma_f32_16x16x32_bf16 v[82:85], v[184:187], v[212:215], v[82:85]
	v_mfma_f32_16x16x32_bf16 v[70:73], v[174:177], v[220:223], v[70:73]
	v_mfma_f32_16x16x32_bf16 v[66:69], v[184:187], v[220:223], v[66:69]
	s_setprio 0
	s_barrier
	ds_read_b128 v[188:191], v143 offset:16384
	ds_read_b128 v[192:195], v143 offset:17408
	ds_read_b128 v[196:199], v143 offset:18432
	ds_read_b128 v[204:207], v143 offset:19456
	ds_read_b128 v[208:211], v143 offset:20480
	ds_read_b128 v[212:215], v143 offset:21504
	ds_read_b128 v[216:219], v143 offset:22528
	ds_read_b128 v[220:223], v143 offset:23552
	s_mov_b32 m0, s44
	s_nop 0
	global_load_lds_dwordx4 v135, s[34:35]
	s_mov_b32 m0, s45
	s_nop 0
	global_load_lds_dwordx4 v137, s[34:35]
	s_add_u32 s26, s34, 0x80000
	s_addc_u32 s27, s35, 0
	s_mov_b32 m0, s46
	s_nop 0
	global_load_lds_dwordx4 v135, s[26:27]
	s_mov_b32 m0, s47
	s_nop 0
	global_load_lds_dwordx4 v137, s[26:27]
	s_mov_b32 m0, s42
	s_nop 0
	global_load_lds_dwordx4 v134, s[36:37]
	s_mov_b32 m0, s48
	s_nop 0
	global_load_lds_dwordx4 v136, s[36:37]
	s_waitcnt vmcnt(8)
	s_waitcnt lgkmcnt(0)
	s_barrier
	s_setprio 1
	v_mfma_f32_16x16x32_bf16 v[62:65], v[154:157], v[188:191], v[62:65]
	v_mfma_f32_16x16x32_bf16 v[58:61], v[162:165], v[188:191], v[58:61]
	v_mfma_f32_16x16x32_bf16 v[46:49], v[154:157], v[196:199], v[46:49]
	v_mfma_f32_16x16x32_bf16 v[42:45], v[162:165], v[196:199], v[42:45]
	v_mfma_f32_16x16x32_bf16 v[30:33], v[154:157], v[208:211], v[30:33]
	v_mfma_f32_16x16x32_bf16 v[26:29], v[162:165], v[208:211], v[26:29]
	v_mfma_f32_16x16x32_bf16 v[14:17], v[154:157], v[216:219], v[14:17]
	v_mfma_f32_16x16x32_bf16 v[10:13], v[162:165], v[216:219], v[10:13]
	v_mfma_f32_16x16x32_bf16 v[62:65], v[158:161], v[192:195], v[62:65]
	v_mfma_f32_16x16x32_bf16 v[58:61], v[166:169], v[192:195], v[58:61]
	v_mfma_f32_16x16x32_bf16 v[46:49], v[158:161], v[204:207], v[46:49]
	v_mfma_f32_16x16x32_bf16 v[42:45], v[166:169], v[204:207], v[42:45]
	v_mfma_f32_16x16x32_bf16 v[30:33], v[158:161], v[212:215], v[30:33]
	v_mfma_f32_16x16x32_bf16 v[26:29], v[166:169], v[212:215], v[26:29]
	v_mfma_f32_16x16x32_bf16 v[14:17], v[158:161], v[220:223], v[14:17]
	v_mfma_f32_16x16x32_bf16 v[10:13], v[166:169], v[220:223], v[10:13]
	v_mfma_f32_16x16x32_bf16 v[54:57], v[170:173], v[188:191], v[54:57]
	v_mfma_f32_16x16x32_bf16 v[50:53], v[180:183], v[188:191], v[50:53]
	v_mfma_f32_16x16x32_bf16 v[38:41], v[170:173], v[196:199], v[38:41]
	v_mfma_f32_16x16x32_bf16 v[34:37], v[180:183], v[196:199], v[34:37]
	v_mfma_f32_16x16x32_bf16 v[22:25], v[170:173], v[208:211], v[22:25]
	v_mfma_f32_16x16x32_bf16 v[18:21], v[180:183], v[208:211], v[18:21]
	v_mfma_f32_16x16x32_bf16 v[6:9], v[170:173], v[216:219], v[6:9]
	v_mfma_f32_16x16x32_bf16 v[2:5], v[180:183], v[216:219], v[2:5]
	v_mfma_f32_16x16x32_bf16 v[54:57], v[174:177], v[192:195], v[54:57]
	v_mfma_f32_16x16x32_bf16 v[50:53], v[184:187], v[192:195], v[50:53]
	v_mfma_f32_16x16x32_bf16 v[38:41], v[174:177], v[204:207], v[38:41]
	v_mfma_f32_16x16x32_bf16 v[34:37], v[184:187], v[204:207], v[34:37]
	v_mfma_f32_16x16x32_bf16 v[22:25], v[174:177], v[212:215], v[22:25]
	v_mfma_f32_16x16x32_bf16 v[18:21], v[184:187], v[212:215], v[18:21]
	v_mfma_f32_16x16x32_bf16 v[6:9], v[174:177], v[220:223], v[6:9]
	v_mfma_f32_16x16x32_bf16 v[2:5], v[184:187], v[220:223], v[2:5]
	s_setprio 0
	s_barrier
; #define PG8_STAGE(bufoff, gbase, voff) do { _Pragma("unroll") for (int _i = 0; _i < 2; ++_i) { unsigned keep_; \
;         asm volatile("s_mov_b32 %0, m0\n\ts_mov_b32 m0, %3\n\ts_nop 0\n\tglobal_load_lds_dwordx4 %1, %2\n\ts_mov_b32 m0, %0" \
;             : "=&s"(keep_) : "v"((voff)[_i]), "s"((const void*)(gbase)), "s"(ldsb0 + (unsigned)(bufoff) + (unsigned)(_i * 8192)) : "memory"); } } while (0)
; #define PG8_LDA(dst, b, h) do { _Pragma("unroll") for (int m = 0; m < 4; ++m) _Pragma("unroll") for (int k = 0; k < 2; ++k) dst[m][k] = *(const LAS bf16x8*)(lds + PG8_SA(b, h) + aoff + m * 2048 + k * 1024); } while (0)
; #define PG8_LDB(dst, b, h) do { _Pragma("unroll") for (int n = 0; n < 2; ++n) _Pragma("unroll") for (int k = 0; k < 2; ++k) dst[n][k] = *(const LAS bf16x8*)(lds + PG8_SB(b, h) + boff + n * 2048 + k * 1024); } while (0)
; #define PG8_WAIT_V(n) asm volatile("s_waitcnt vmcnt(" #n ")" ::: "memory")
; #define PG8_WAIT_L(n) asm volatile("s_waitcnt lgkmcnt(" #n ")" ::: "memory")
; #define PG8_BAR __builtin_amdgcn_s_barrier()
; #define PG8_SCHED __builtin_amdgcn_sched_barrier(0)
; template <class Epi, class Sched, bool ALIGN_EPI>
; __device__ __forceinline__ void gemm_phase(LAS unsigned char* lds, const Gemm g, const Sched& S, const Epi& E) {
;     ...
;             PG8_LDB(B0, 0, 0); PG8_LDB(B1, 0, 1); PG8_SCHED; PG8_LDA(At, 0, 0); PG8_STAGE(PG8_SA(1, 1), a1 + hstepA, voffA);
;             PG8_WAIT_V(8); PG8_WAIT_L(0); PG8_BAR; PG8_MMA(0, 0, At, B0); PG8_MMA(0, 1, At, B1); PG8_BAR; PG8_SCHED;
;             PG8_LDA(At, 0, 1); PG8_STAGE(PG8_SB(0, 0), b2, voffB); PG8_STAGE(PG8_SB(0, 1), b2 + hstepB, voffB); PG8_STAGE(PG8_SA(0, 0), a2, voffA);
;             PG8_WAIT_V(8); PG8_WAIT_L(0); PG8_BAR; PG8_MMA(1, 0, At, B0); PG8_MMA(1, 1, At, B1); PG8_BAR; PG8_SCHED;
;             PG8_LDB(B0, 1, 0); PG8_LDB(B1, 1, 1); PG8_SCHED; PG8_LDA(At, 1, 0); PG8_STAGE(PG8_SA(0, 1), a2 + hstepA, voffA);
;             PG8_WAIT_V(8); PG8_WAIT_L(0); PG8_BAR; PG8_MMA(0, 0, At, B0); PG8_MMA(0, 1, At, B1); PG8_BAR; PG8_SCHED;
;             PG8_LDA(At, 1, 1); PG8_STAGE(PG8_SB(1, 0), b3, voffB); PG8_STAGE(PG8_SB(1, 1), b3 + hstepB, voffB); PG8_STAGE(PG8_SA(1, 0), a3, voffA);
;             PG8_WAIT_V(8); PG8_WAIT_L(0); PG8_BAR; PG8_MMA(1, 0, At, B0); PG8_MMA(1, 1, At, B1); PG8_BAR; PG8_SCHED;
;         }
;         if constexpr (ALIGN_EPI) { if (wr == 0) PG8_BAR; }
	ds_read_b128 v[154:157], v144
	ds_read_b128 v[158:161], v144 offset:1024
	ds_read_b128 v[162:165], v144 offset:2048
	ds_read_b128 v[166:169], v144 offset:3072
	ds_read_b128 v[170:173], v145
	ds_read_b128 v[174:177], v145 offset:1024
	ds_read_b128 v[180:183], v145 offset:2048
	ds_read_b128 v[184:187], v145 offset:3072
	ds_read_b128 v[188:191], v143 offset:32768
	ds_read_b128 v[192:195], v143 offset:33792
	ds_read_b128 v[196:199], v143 offset:34816
	ds_read_b128 v[204:207], v143 offset:35840
	ds_read_b128 v[208:211], v143 offset:36864
	ds_read_b128 v[212:215], v143 offset:37888
	ds_read_b128 v[216:219], v143 offset:38912
	ds_read_b128 v[220:223], v143 offset:39936
	s_add_u32 s26, s36, 0x80000
	s_addc_u32 s27, s37, 0
	s_mov_b32 m0, s49
	s_nop 0
	global_load_lds_dwordx4 v134, s[26:27]
	s_mov_b32 m0, s50
	s_nop 0
	global_load_lds_dwordx4 v136, s[26:27]
	s_waitcnt vmcnt(8)
	s_waitcnt lgkmcnt(0)
	s_barrier
	s_setprio 1
	v_mfma_f32_16x16x32_bf16 v[126:129], v[154:157], v[188:191], v[126:129]
	v_mfma_f32_16x16x32_bf16 v[122:125], v[162:165], v[188:191], v[122:125]
	v_mfma_f32_16x16x32_bf16 v[110:113], v[154:157], v[196:199], v[110:113]
	v_mfma_f32_16x16x32_bf16 v[106:109], v[162:165], v[196:199], v[106:109]
	v_mfma_f32_16x16x32_bf16 v[94:97], v[154:157], v[208:211], v[94:97]
	v_mfma_f32_16x16x32_bf16 v[90:93], v[162:165], v[208:211], v[90:93]
	v_mfma_f32_16x16x32_bf16 v[78:81], v[154:157], v[216:219], v[78:81]
	v_mfma_f32_16x16x32_bf16 v[74:77], v[162:165], v[216:219], v[74:77]
	v_mfma_f32_16x16x32_bf16 v[126:129], v[158:161], v[192:195], v[126:129]
	v_mfma_f32_16x16x32_bf16 v[122:125], v[166:169], v[192:195], v[122:125]
	v_mfma_f32_16x16x32_bf16 v[110:113], v[158:161], v[204:207], v[110:113]
	v_mfma_f32_16x16x32_bf16 v[106:109], v[166:169], v[204:207], v[106:109]
	v_mfma_f32_16x16x32_bf16 v[94:97], v[158:161], v[212:215], v[94:97]
	v_mfma_f32_16x16x32_bf16 v[90:93], v[166:169], v[212:215], v[90:93]
	v_mfma_f32_16x16x32_bf16 v[78:81], v[158:161], v[220:223], v[78:81]
	v_mfma_f32_16x16x32_bf16 v[74:77], v[166:169], v[220:223], v[74:77]
	v_mfma_f32_16x16x32_bf16 v[118:121], v[170:173], v[188:191], v[118:121]
	v_mfma_f32_16x16x32_bf16 v[114:117], v[180:183], v[188:191], v[114:117]
	v_mfma_f32_16x16x32_bf16 v[102:105], v[170:173], v[196:199], v[102:105]
	v_mfma_f32_16x16x32_bf16 v[98:101], v[180:183], v[196:199], v[98:101]
	v_mfma_f32_16x16x32_bf16 v[86:89], v[170:173], v[208:211], v[86:89]
	v_mfma_f32_16x16x32_bf16 v[82:85], v[180:183], v[208:211], v[82:85]
	v_mfma_f32_16x16x32_bf16 v[70:73], v[170:173], v[216:219], v[70:73]
	v_mfma_f32_16x16x32_bf16 v[66:69], v[180:183], v[216:219], v[66:69]
	v_mfma_f32_16x16x32_bf16 v[118:121], v[174:177], v[192:195], v[118:121]
	v_mfma_f32_16x16x32_bf16 v[114:117], v[184:187], v[192:195], v[114:117]
	v_mfma_f32_16x16x32_bf16 v[102:105], v[174:177], v[204:207], v[102:105]
	v_mfma_f32_16x16x32_bf16 v[98:101], v[184:187], v[204:207], v[98:101]
	v_mfma_f32_16x16x32_bf16 v[86:89], v[174:177], v[212:215], v[86:89]
	v_mfma_f32_16x16x32_bf16 v[82:85], v[184:187], v[212:215], v[82:85]
	v_mfma_f32_16x16x32_bf16 v[70:73], v[174:177], v[220:223], v[70:73]
	v_mfma_f32_16x16x32_bf16 v[66:69], v[184:187], v[220:223], v[66:69]
	s_setprio 0
	s_barrier
	ds_read_b128 v[188:191], v143 offset:49152
	ds_read_b128 v[192:195], v143 offset:50176
	ds_read_b128 v[196:199], v143 offset:51200
	ds_read_b128 v[204:207], v143 offset:52224
	ds_read_b128 v[208:211], v143 offset:53248
	ds_read_b128 v[212:215], v143 offset:54272
	ds_read_b128 v[216:219], v143 offset:55296
	ds_read_b128 v[220:223], v143 offset:56320
	s_add_u32 s26, s34, 0x80
	s_addc_u32 s27, s35, 0
	s_mov_b32 m0, s51
	s_nop 0
	global_load_lds_dwordx4 v135, s[26:27]
	s_mov_b32 m0, s52
	s_nop 0
	global_load_lds_dwordx4 v137, s[26:27]
	s_add_u32 s26, s34, 0x80080
	s_addc_u32 s27, s35, 0
	s_mov_b32 m0, s55
	s_nop 0
	global_load_lds_dwordx4 v135, s[26:27]
	s_mov_b32 m0, s56
	s_nop 0
	global_load_lds_dwordx4 v137, s[26:27]
	s_mov_b32 m0, s53
	s_nop 0
	global_load_lds_dwordx4 v134, s[30:31]
	s_mov_b32 m0, s54
	s_nop 0
	global_load_lds_dwordx4 v136, s[30:31]
	s_waitcnt vmcnt(8)
	s_waitcnt lgkmcnt(0)
	s_barrier
	s_setprio 1
	v_mfma_f32_16x16x32_bf16 v[62:65], v[154:157], v[188:191], v[62:65]
	v_mfma_f32_16x16x32_bf16 v[58:61], v[162:165], v[188:191], v[58:61]
	v_mfma_f32_16x16x32_bf16 v[46:49], v[154:157], v[196:199], v[46:49]
	v_mfma_f32_16x16x32_bf16 v[42:45], v[162:165], v[196:199], v[42:45]
	v_mfma_f32_16x16x32_bf16 v[30:33], v[154:157], v[208:211], v[30:33]
	v_mfma_f32_16x16x32_bf16 v[26:29], v[162:165], v[208:211], v[26:29]
	v_mfma_f32_16x16x32_bf16 v[14:17], v[154:157], v[216:219], v[14:17]
	v_mfma_f32_16x16x32_bf16 v[10:13], v[162:165], v[216:219], v[10:13]
	v_mfma_f32_16x16x32_bf16 v[62:65], v[158:161], v[192:195], v[62:65]
	v_mfma_f32_16x16x32_bf16 v[58:61], v[166:169], v[192:195], v[58:61]
	v_mfma_f32_16x16x32_bf16 v[46:49], v[158:161], v[204:207], v[46:49]
	v_mfma_f32_16x16x32_bf16 v[42:45], v[166:169], v[204:207], v[42:45]
	v_mfma_f32_16x16x32_bf16 v[30:33], v[158:161], v[212:215], v[30:33]
	v_mfma_f32_16x16x32_bf16 v[26:29], v[166:169], v[212:215], v[26:29]
	v_mfma_f32_16x16x32_bf16 v[14:17], v[158:161], v[220:223], v[14:17]
	v_mfma_f32_16x16x32_bf16 v[10:13], v[166:169], v[220:223], v[10:13]
	v_mfma_f32_16x16x32_bf16 v[54:57], v[170:173], v[188:191], v[54:57]
	v_mfma_f32_16x16x32_bf16 v[50:53], v[180:183], v[188:191], v[50:53]
	v_mfma_f32_16x16x32_bf16 v[38:41], v[170:173], v[196:199], v[38:41]
	v_mfma_f32_16x16x32_bf16 v[34:37], v[180:183], v[196:199], v[34:37]
	v_mfma_f32_16x16x32_bf16 v[22:25], v[170:173], v[208:211], v[22:25]
	v_mfma_f32_16x16x32_bf16 v[18:21], v[180:183], v[208:211], v[18:21]
	v_mfma_f32_16x16x32_bf16 v[6:9], v[170:173], v[216:219], v[6:9]
	v_mfma_f32_16x16x32_bf16 v[2:5], v[180:183], v[216:219], v[2:5]
	v_mfma_f32_16x16x32_bf16 v[54:57], v[174:177], v[192:195], v[54:57]
	v_mfma_f32_16x16x32_bf16 v[50:53], v[184:187], v[192:195], v[50:53]
	v_mfma_f32_16x16x32_bf16 v[38:41], v[174:177], v[204:207], v[38:41]
	v_mfma_f32_16x16x32_bf16 v[34:37], v[184:187], v[204:207], v[34:37]
	v_mfma_f32_16x16x32_bf16 v[22:25], v[174:177], v[212:215], v[22:25]
	v_mfma_f32_16x16x32_bf16 v[18:21], v[184:187], v[212:215], v[18:21]
	v_mfma_f32_16x16x32_bf16 v[6:9], v[174:177], v[220:223], v[6:9]
	v_mfma_f32_16x16x32_bf16 v[2:5], v[184:187], v[220:223], v[2:5]
	s_setprio 0
	s_barrier
	s_add_i32 s60, s60, 2
	s_add_u32 s19, s19, 0x100
	s_addc_u32 s21, s21, 0
	s_cmp_gt_u32 s60, 29
	s_mov_b64 s[26:27], s[28:29]
	s_cbranch_scc0 .LBB0_2075
	s_and_b64 vcc, exec, s[16:17]
	s_cbranch_vccz .LBB0_2078
	s_barrier
; __device__ __forceinline__ float fexp2(float x) { return __builtin_amdgcn_exp2f(x); }
; __device__ __forceinline__ void st_bf16x8(bf16* p, f32x4 a, f32x4 b) { *(bf16x8*)p = pack8(a, b); }
; __device__ __forceinline__ float rs_val(float ssqv) { return __builtin_amdgcn_rsqf(ssqv * (1.f / DM) + EPS); }
; __device__ __forceinline__ float swiglu1(float g, float u) { return g * u * __builtin_amdgcn_rcpf(1.f + fexp2(-g * LOG2E)); }
;     __device__ __forceinline__ void operator()(const Acc& acc, const pg8::Unit& u, int wr, int wc, int fr, int fq, const float* rsv) const {
;         const int c = u.pn * 128 + wc * 32 + fq * 8;
; #pragma unroll
;         for (int ai = 0; ai < 2; ++ai)
; #pragma unroll
;             for (int m = 0; m < 4; ++m) { const int row = u.pm * 256 + ai * 128 + wr * 64 + m * 16 + fr; const float rs = rs_val(rsv[ai * 4 + m]);
;                 f32x4 o0, o1;
; #pragma unroll
;                 for (int e = 0; e < 4; ++e) { o0[e] = swiglu1(acc[ai][0][m][0][e] * rs, acc[ai][1][m][0][e] * rs); o1[e] = swiglu1(acc[ai][0][m][1][e] * rs, acc[ai][1][m][1][e] * rs); }
;                 st_bf16x8(ACT + (size_t)row * DFF + c, o0, o1); __builtin_amdgcn_sched_barrier(0); }
;     }
.LBB0_2078:
	s_nop 0
	v_fmamk_f32 v153, v153, 0x3a000000, v146
	v_rsq_f32_e32 v156, v153
	v_mov_b32_e32 v158, v126
	v_mov_b32_e32 v159, v118
	v_mov_b32_e32 v160, v122
	v_pk_mul_f32 v[158:159], v[156:157], v[158:159] op_sel_hi:[0,1]
	v_mov_b32_e32 v161, v114
	v_mul_f32_e32 v118, 0xbfb8aa3b, v158
	v_pk_mul_f32 v[160:161], v[156:157], v[160:161] op_sel_hi:[0,1]
	v_exp_f32_e32 v118, v118
	v_mul_f32_e32 v114, 0xbfb8aa3b, v160
	v_exp_f32_e32 v114, v114
	v_mul_f32_e32 v122, v158, v159
	v_add_f32_e32 v118, 1.0, v118
	v_rcp_f32_e32 v118, v118
	v_add_f32_e32 v114, 1.0, v114
	v_rcp_f32_e32 v114, v114
	v_lshl_or_b32 v154, s2, 7, v140
	v_mul_f32_e32 v126, v118, v122
	v_mul_f32_e32 v118, v160, v161
	v_mul_f32_e32 v157, v114, v118
	v_mov_b32_e32 v118, v127
	v_pk_mul_f32 v[118:119], v[156:157], v[118:119] op_sel_hi:[0,1]
	v_mul_f32_e32 v114, 0xbfb8aa3b, v118
	v_exp_f32_e32 v122, v114
	v_mov_b32_e32 v114, v123
	v_pk_mul_f32 v[114:115], v[156:157], v[114:115] op_sel_hi:[0,1]
	v_mul_f32_e32 v123, 0xbfb8aa3b, v114
	v_exp_f32_e32 v123, v123
	v_mul_f32_e32 v127, v118, v119
	v_add_f32_e32 v118, 1.0, v122
	v_rcp_f32_e32 v122, v118
	v_add_f32_e32 v118, 1.0, v123
	v_rcp_f32_e32 v123, v118
	v_mov_b32_e32 v118, v128
	v_mov_b32_e32 v119, v120
	v_pk_mul_f32 v[118:119], v[156:157], v[118:119] op_sel_hi:[0,1]
	v_mul_f32_e32 v120, 0xbfb8aa3b, v118
	v_exp_f32_e32 v120, v120
	v_mul_f32_e32 v114, v114, v115
	v_mul_f32_e32 v128, v123, v114
	v_mov_b32_e32 v115, v116
	v_add_f32_e32 v114, 1.0, v120
	v_rcp_f32_e32 v120, v114
	v_mov_b32_e32 v114, v124
	v_pk_mul_f32 v[114:115], v[156:157], v[114:115] op_sel_hi:[0,1]
	v_mul_f32_e32 v116, 0xbfb8aa3b, v114
	v_exp_f32_e32 v116, v116
	v_mul_f32_e32 v118, v118, v119
	v_mul_f32_e32 v124, v120, v118
	v_mul_f32_e32 v118, v114, v115
	v_add_f32_e32 v114, 1.0, v116
	v_mov_b32_e32 v120, v129
	v_rcp_f32_e32 v119, v114
	v_pk_mul_f32 v[114:115], v[156:157], v[120:121] op_sel_hi:[0,1]
	v_mul_f32_e32 v116, 0xbfb8aa3b, v114
	v_exp_f32_e32 v120, v116
	v_mov_b32_e32 v116, v125
	v_pk_mul_f32 v[116:117], v[156:157], v[116:117] op_sel_hi:[0,1]
	v_mul_f32_e32 v121, 0xbfb8aa3b, v116
	v_exp_f32_e32 v121, v121
	v_mul_f32_e32 v125, v119, v118
	v_add_f32_e32 v118, 1.0, v120
	v_rcp_f32_e32 v118, v118
	v_add_f32_e32 v119, 1.0, v121
	v_rcp_f32_e32 v119, v119
	v_mul_f32_e32 v114, v114, v115
	v_mul_f32_e32 v120, v118, v114
	v_mul_f32_e32 v114, v116, v117
	v_lshl_add_u32 v153, s4, 8, v138
	v_ashrrev_i32_e32 v155, 31, v154
	v_mul_f32_e32 v121, v119, v114
	v_mov_b64_e32 v[114:115], s[14:15]
	v_mad_i64_i32 v[118:119], s[2:3], v153, s59, v[114:115]
	v_lshlrev_b64 v[116:117], 1, v[154:155]
	v_mul_f32_e32 v127, v122, v127
	v_lshl_add_u64 v[122:123], v[118:119], 0, v[116:117]
	v_cvt_pk_bf16_f32 v118, v126, v127
	v_cvt_pk_bf16_f32 v119, v124, v120
	v_cvt_pk_bf16_f32 v120, v157, v128
	v_cvt_pk_bf16_f32 v121, v125, v121
	global_store_dwordx4 v[122:123], v[118:121], off
	s_nop 0
	s_nop 0
	v_fmamk_f32 v118, v152, 0x3a000000, v146
	v_rsq_f32_e32 v118, v118
	v_mov_b32_e32 v120, v110
	v_mov_b32_e32 v121, v102
	v_mov_b32_e32 v122, v106
	v_pk_mul_f32 v[120:121], v[118:119], v[120:121] op_sel_hi:[0,1]
	v_mov_b32_e32 v123, v98
	v_mul_f32_e32 v102, 0xbfb8aa3b, v120
	v_pk_mul_f32 v[122:123], v[118:119], v[122:123] op_sel_hi:[0,1]
	v_exp_f32_e32 v102, v102
	v_mul_f32_e32 v98, 0xbfb8aa3b, v122
	v_exp_f32_e32 v98, v98
	v_mul_f32_e32 v106, v120, v121
	v_add_f32_e32 v102, 1.0, v102
	v_rcp_f32_e32 v102, v102
	v_add_f32_e32 v98, 1.0, v98
	v_rcp_f32_e32 v98, v98
	v_mul_f32_e32 v106, v102, v106
	v_mul_f32_e32 v102, v122, v123
	v_mul_f32_e32 v110, v98, v102
	v_mov_b32_e32 v102, v111
	v_pk_mul_f32 v[102:103], v[118:119], v[102:103] op_sel_hi:[0,1]
	v_mul_f32_e32 v98, 0xbfb8aa3b, v102
	v_exp_f32_e32 v111, v98
	v_mov_b32_e32 v98, v107
	v_pk_mul_f32 v[98:99], v[118:119], v[98:99] op_sel_hi:[0,1]
	v_mul_f32_e32 v107, 0xbfb8aa3b, v98
	v_exp_f32_e32 v107, v107
	v_mul_f32_e32 v119, v102, v103
	v_add_f32_e32 v102, 1.0, v111
	v_rcp_f32_e32 v111, v102
	v_add_f32_e32 v102, 1.0, v107
	v_rcp_f32_e32 v107, v102
	v_mov_b32_e32 v102, v112
	v_mov_b32_e32 v103, v104
	v_pk_mul_f32 v[102:103], v[118:119], v[102:103] op_sel_hi:[0,1]
	v_mul_f32_e32 v104, 0xbfb8aa3b, v102
	v_exp_f32_e32 v104, v104
	v_mul_f32_e32 v98, v98, v99
	v_mul_f32_e32 v107, v107, v98
	v_mov_b32_e32 v99, v100
	v_add_f32_e32 v98, 1.0, v104
	v_rcp_f32_e32 v104, v98
	v_mov_b32_e32 v98, v108
	v_pk_mul_f32 v[98:99], v[118:119], v[98:99] op_sel_hi:[0,1]
	v_mul_f32_e32 v100, 0xbfb8aa3b, v98
	v_exp_f32_e32 v100, v100
	v_mul_f32_e32 v102, v102, v103
	v_mul_f32_e32 v108, v104, v102
	v_mul_f32_e32 v102, v98, v99
	v_add_f32_e32 v98, 1.0, v100
	v_mov_b32_e32 v104, v113
	v_rcp_f32_e32 v103, v98
	v_pk_mul_f32 v[98:99], v[118:119], v[104:105] op_sel_hi:[0,1]
	v_mul_f32_e32 v100, 0xbfb8aa3b, v98
	v_exp_f32_e32 v104, v100
	v_mov_b32_e32 v100, v109
	v_pk_mul_f32 v[100:101], v[118:119], v[100:101] op_sel_hi:[0,1]
	v_mul_f32_e32 v105, 0xbfb8aa3b, v100
	v_exp_f32_e32 v105, v105
	v_mul_f32_e32 v109, v103, v102
	v_add_f32_e32 v102, 1.0, v104
	v_rcp_f32_e32 v102, v102
	v_add_f32_e32 v103, 1.0, v105
	v_rcp_f32_e32 v103, v103
	v_mul_f32_e32 v98, v98, v99
	v_mul_f32_e32 v104, v102, v98
	v_mul_f32_e32 v98, v100, v101
	v_mul_f32_e32 v101, v103, v98
	v_or_b32_e32 v98, 16, v153
	v_mad_i64_i32 v[98:99], s[2:3], v98, s59, v[114:115]
	v_lshl_add_u64 v[102:103], v[98:99], 0, v[116:117]
	v_mul_f32_e32 v111, v111, v119
	v_cvt_pk_bf16_f32 v98, v106, v111
	v_cvt_pk_bf16_f32 v99, v108, v104
	v_cvt_pk_bf16_f32 v100, v110, v107
	v_cvt_pk_bf16_f32 v101, v109, v101
	global_store_dwordx4 v[102:103], v[98:101], off
	s_nop 0
	s_nop 0
	v_fmamk_f32 v98, v151, 0x3a000000, v146
	v_rsq_f32_e32 v98, v98
; __device__ __forceinline__ float fexp2(float x) { return __builtin_amdgcn_exp2f(x); }
; __device__ __forceinline__ float rs_val(float ssqv) { return __builtin_amdgcn_rsqf(ssqv * (1.f / DM) + EPS); }
; __device__ __forceinline__ void st_bf16x8(bf16* p, f32x4 a, f32x4 b) { *(bf16x8*)p = pack8(a, b); }
; __device__ __forceinline__ float swiglu1(float g, float u) { return g * u * __builtin_amdgcn_rcpf(1.f + fexp2(-g * LOG2E)); }
;     __device__ __forceinline__ void preload(const pg8::Unit& u, int wr, int fr, float* rsv) const {
; #pragma unroll
;         for (int k = 0; k < 8; ++k) rsv[k] = ssq[u.pm * 256 + (k >> 2) * 128 + wr * 64 + (k & 3) * 16 + fr]; }
;     __device__ __forceinline__ void operator()(const Acc& acc, const pg8::Unit& u, int wr, int wc, int fr, int fq, const float* rsv) const {
;         const int c = u.pn * 128 + wc * 32 + fq * 8;
; #pragma unroll
;         for (int ai = 0; ai < 2; ++ai)
; #pragma unroll
;             for (int m = 0; m < 4; ++m) { const int row = u.pm * 256 + ai * 128 + wr * 64 + m * 16 + fr; const float rs = rs_val(rsv[ai * 4 + m]);
;                 f32x4 o0, o1;
; #pragma unroll
;                 for (int e = 0; e < 4; ++e) { o0[e] = swiglu1(acc[ai][0][m][0][e] * rs, acc[ai][1][m][0][e] * rs); o1[e] = swiglu1(acc[ai][0][m][1][e] * rs, acc[ai][1][m][1][e] * rs); }
;                 st_bf16x8(ACT + (size_t)row * DFF + c, o0, o1); __builtin_amdgcn_sched_barrier(0); }
	v_mov_b32_e32 v100, v94
	v_mov_b32_e32 v101, v86
	v_mov_b32_e32 v102, v90
	v_pk_mul_f32 v[100:101], v[98:99], v[100:101] op_sel_hi:[0,1]
	v_mov_b32_e32 v103, v82
	v_mul_f32_e32 v86, 0xbfb8aa3b, v100
	v_pk_mul_f32 v[102:103], v[98:99], v[102:103] op_sel_hi:[0,1]
	v_exp_f32_e32 v86, v86
	v_mul_f32_e32 v82, 0xbfb8aa3b, v102
	v_exp_f32_e32 v82, v82
	v_mul_f32_e32 v90, v100, v101
	v_add_f32_e32 v86, 1.0, v86
	v_rcp_f32_e32 v86, v86
	v_add_f32_e32 v82, 1.0, v82
	v_rcp_f32_e32 v82, v82
	v_mul_f32_e32 v90, v86, v90
	v_mul_f32_e32 v86, v102, v103
	v_mul_f32_e32 v94, v82, v86
	v_mov_b32_e32 v86, v95
	v_pk_mul_f32 v[86:87], v[98:99], v[86:87] op_sel_hi:[0,1]
	v_mul_f32_e32 v82, 0xbfb8aa3b, v86
	v_exp_f32_e32 v95, v82
	v_mov_b32_e32 v82, v91
	v_pk_mul_f32 v[82:83], v[98:99], v[82:83] op_sel_hi:[0,1]
	v_mul_f32_e32 v91, 0xbfb8aa3b, v82
	v_exp_f32_e32 v91, v91
	v_mul_f32_e32 v99, v86, v87
	v_add_f32_e32 v86, 1.0, v95
	v_rcp_f32_e32 v95, v86
	v_add_f32_e32 v86, 1.0, v91
	v_rcp_f32_e32 v91, v86
	v_mov_b32_e32 v86, v96
	v_mov_b32_e32 v87, v88
	v_pk_mul_f32 v[86:87], v[98:99], v[86:87] op_sel_hi:[0,1]
	v_mul_f32_e32 v88, 0xbfb8aa3b, v86
	v_exp_f32_e32 v88, v88
	v_mul_f32_e32 v82, v82, v83
	v_mul_f32_e32 v91, v91, v82
	v_mov_b32_e32 v83, v84
	v_add_f32_e32 v82, 1.0, v88
	v_rcp_f32_e32 v88, v82
	v_mov_b32_e32 v82, v92
	v_pk_mul_f32 v[82:83], v[98:99], v[82:83] op_sel_hi:[0,1]
	v_mul_f32_e32 v84, 0xbfb8aa3b, v82
	v_exp_f32_e32 v84, v84
	v_mul_f32_e32 v86, v86, v87
	v_mul_f32_e32 v92, v88, v86
	v_mul_f32_e32 v86, v82, v83
	v_add_f32_e32 v82, 1.0, v84
	v_mov_b32_e32 v88, v97
	v_rcp_f32_e32 v87, v82
	v_pk_mul_f32 v[82:83], v[98:99], v[88:89] op_sel_hi:[0,1]
	v_mul_f32_e32 v84, 0xbfb8aa3b, v82
	v_exp_f32_e32 v88, v84
	v_mov_b32_e32 v84, v93
	v_pk_mul_f32 v[84:85], v[98:99], v[84:85] op_sel_hi:[0,1]
	v_mul_f32_e32 v89, 0xbfb8aa3b, v84
	v_exp_f32_e32 v89, v89
	v_mul_f32_e32 v93, v87, v86
	v_add_f32_e32 v86, 1.0, v88
	v_rcp_f32_e32 v86, v86
	v_add_f32_e32 v87, 1.0, v89
	v_rcp_f32_e32 v87, v87
	v_mul_f32_e32 v82, v82, v83
	v_mul_f32_e32 v88, v86, v82
	v_mul_f32_e32 v82, v84, v85
	v_mul_f32_e32 v85, v87, v82
	v_or_b32_e32 v82, 32, v153
	v_mad_i64_i32 v[82:83], s[2:3], v82, s59, v[114:115]
	v_lshl_add_u64 v[86:87], v[82:83], 0, v[116:117]
	v_mul_f32_e32 v95, v95, v99
	v_cvt_pk_bf16_f32 v82, v90, v95
	v_cvt_pk_bf16_f32 v83, v92, v88
	v_cvt_pk_bf16_f32 v84, v94, v91
	v_cvt_pk_bf16_f32 v85, v93, v85
	global_store_dwordx4 v[86:87], v[82:85], off
	s_nop 0
	s_nop 0
	v_fmamk_f32 v82, v150, 0x3a000000, v146
	v_rsq_f32_e32 v82, v82
	v_mov_b32_e32 v84, v78
	v_mov_b32_e32 v85, v70
	v_mov_b32_e32 v86, v74
	v_pk_mul_f32 v[84:85], v[82:83], v[84:85] op_sel_hi:[0,1]
	v_mov_b32_e32 v87, v66
	v_mul_f32_e32 v70, 0xbfb8aa3b, v84
	v_pk_mul_f32 v[86:87], v[82:83], v[86:87] op_sel_hi:[0,1]
	v_exp_f32_e32 v70, v70
	v_mul_f32_e32 v66, 0xbfb8aa3b, v86
	v_exp_f32_e32 v66, v66
	v_mul_f32_e32 v74, v84, v85
	v_add_f32_e32 v70, 1.0, v70
	v_rcp_f32_e32 v70, v70
	v_add_f32_e32 v66, 1.0, v66
	v_rcp_f32_e32 v66, v66
	v_mul_f32_e32 v74, v70, v74
	v_mul_f32_e32 v70, v86, v87
	v_mul_f32_e32 v78, v66, v70
	v_mov_b32_e32 v70, v79
	v_pk_mul_f32 v[70:71], v[82:83], v[70:71] op_sel_hi:[0,1]
	v_mul_f32_e32 v66, 0xbfb8aa3b, v70
	v_exp_f32_e32 v79, v66
	v_mov_b32_e32 v66, v75
	v_pk_mul_f32 v[66:67], v[82:83], v[66:67] op_sel_hi:[0,1]
	v_mul_f32_e32 v75, 0xbfb8aa3b, v66
	v_exp_f32_e32 v75, v75
	v_mul_f32_e32 v83, v70, v71
	v_add_f32_e32 v70, 1.0, v79
	v_rcp_f32_e32 v79, v70
	v_add_f32_e32 v70, 1.0, v75
	v_rcp_f32_e32 v75, v70
	v_mov_b32_e32 v70, v80
	v_mov_b32_e32 v71, v72
	v_pk_mul_f32 v[70:71], v[82:83], v[70:71] op_sel_hi:[0,1]
	v_mul_f32_e32 v72, 0xbfb8aa3b, v70
	v_exp_f32_e32 v72, v72
	v_mul_f32_e32 v66, v66, v67
	v_mul_f32_e32 v75, v75, v66
	v_mov_b32_e32 v67, v68
	v_add_f32_e32 v66, 1.0, v72
	v_rcp_f32_e32 v72, v66
	v_mov_b32_e32 v66, v76
	v_pk_mul_f32 v[66:67], v[82:83], v[66:67] op_sel_hi:[0,1]
	v_mul_f32_e32 v68, 0xbfb8aa3b, v66
	v_exp_f32_e32 v68, v68
	v_mul_f32_e32 v70, v70, v71
	v_mul_f32_e32 v76, v72, v70
	v_mul_f32_e32 v70, v66, v67
	v_add_f32_e32 v66, 1.0, v68
	v_mov_b32_e32 v72, v81
	v_rcp_f32_e32 v71, v66
	v_pk_mul_f32 v[66:67], v[82:83], v[72:73] op_sel_hi:[0,1]
	v_mul_f32_e32 v68, 0xbfb8aa3b, v66
	v_exp_f32_e32 v72, v68
	v_mov_b32_e32 v68, v77
	v_pk_mul_f32 v[68:69], v[82:83], v[68:69] op_sel_hi:[0,1]
	v_mul_f32_e32 v73, 0xbfb8aa3b, v68
	v_exp_f32_e32 v73, v73
	v_mul_f32_e32 v77, v71, v70
	v_add_f32_e32 v70, 1.0, v72
	v_rcp_f32_e32 v70, v70
	v_add_f32_e32 v71, 1.0, v73
	v_rcp_f32_e32 v71, v71
	v_mul_f32_e32 v66, v66, v67
	v_mul_f32_e32 v72, v70, v66
	v_mul_f32_e32 v66, v68, v69
	v_mul_f32_e32 v69, v71, v66
	v_or_b32_e32 v66, 48, v153
	v_mad_i64_i32 v[66:67], s[2:3], v66, s59, v[114:115]
	v_lshl_add_u64 v[70:71], v[66:67], 0, v[116:117]
	v_mul_f32_e32 v79, v79, v83
	v_cvt_pk_bf16_f32 v66, v74, v79
	v_cvt_pk_bf16_f32 v67, v76, v72
	v_cvt_pk_bf16_f32 v68, v78, v75
	v_cvt_pk_bf16_f32 v69, v77, v69
	global_store_dwordx4 v[70:71], v[66:69], off
	s_nop 0
	s_nop 0
	v_fmamk_f32 v66, v149, 0x3a000000, v146
	v_rsq_f32_e32 v66, v66
	v_mov_b32_e32 v68, v62
	v_mov_b32_e32 v69, v54
	v_mov_b32_e32 v70, v58
	v_pk_mul_f32 v[68:69], v[66:67], v[68:69] op_sel_hi:[0,1]
	v_mov_b32_e32 v71, v50
	v_mul_f32_e32 v54, 0xbfb8aa3b, v68
	v_pk_mul_f32 v[70:71], v[66:67], v[70:71] op_sel_hi:[0,1]
	v_exp_f32_e32 v54, v54
	v_mul_f32_e32 v50, 0xbfb8aa3b, v70
	v_exp_f32_e32 v50, v50
	v_mul_f32_e32 v62, v68, v69
	v_add_f32_e32 v54, 1.0, v54
	v_rcp_f32_e32 v54, v54
	v_add_f32_e32 v50, 1.0, v50
	v_rcp_f32_e32 v50, v50
	v_add_u32_e32 v58, 0x80, v153
	v_mul_f32_e32 v62, v54, v62
	v_mul_f32_e32 v54, v70, v71
	v_mul_f32_e32 v67, v50, v54
; __device__ __forceinline__ float fexp2(float x) { return __builtin_amdgcn_exp2f(x); }
; __device__ __forceinline__ float rs_val(float ssqv) { return __builtin_amdgcn_rsqf(ssqv * (1.f / DM) + EPS); }
; __device__ __forceinline__ void st_bf16x8(bf16* p, f32x4 a, f32x4 b) { *(bf16x8*)p = pack8(a, b); }
; __device__ __forceinline__ float swiglu1(float g, float u) { return g * u * __builtin_amdgcn_rcpf(1.f + fexp2(-g * LOG2E)); }
;     __device__ __forceinline__ void preload(const pg8::Unit& u, int wr, int fr, float* rsv) const {
; #pragma unroll
;         for (int k = 0; k < 8; ++k) rsv[k] = ssq[u.pm * 256 + (k >> 2) * 128 + wr * 64 + (k & 3) * 16 + fr]; }
;     __device__ __forceinline__ void operator()(const Acc& acc, const pg8::Unit& u, int wr, int wc, int fr, int fq, const float* rsv) const {
;         const int c = u.pn * 128 + wc * 32 + fq * 8;
; #pragma unroll
;         for (int ai = 0; ai < 2; ++ai)
; #pragma unroll
;             for (int m = 0; m < 4; ++m) { const int row = u.pm * 256 + ai * 128 + wr * 64 + m * 16 + fr; const float rs = rs_val(rsv[ai * 4 + m]);
;                 f32x4 o0, o1;
; #pragma unroll
;                 for (int e = 0; e < 4; ++e) { o0[e] = swiglu1(acc[ai][0][m][0][e] * rs, acc[ai][1][m][0][e] * rs); o1[e] = swiglu1(acc[ai][0][m][1][e] * rs, acc[ai][1][m][1][e] * rs); }
;                 st_bf16x8(ACT + (size_t)row * DFF + c, o0, o1); __builtin_amdgcn_sched_barrier(0); }
	v_mov_b32_e32 v54, v63
	v_pk_mul_f32 v[54:55], v[66:67], v[54:55] op_sel_hi:[0,1]
	v_mul_f32_e32 v50, 0xbfb8aa3b, v54
	v_exp_f32_e32 v63, v50
	v_mov_b32_e32 v50, v59
	v_pk_mul_f32 v[50:51], v[66:67], v[50:51] op_sel_hi:[0,1]
	v_mul_f32_e32 v59, 0xbfb8aa3b, v50
	v_exp_f32_e32 v59, v59
	v_mul_f32_e32 v68, v54, v55
	v_add_f32_e32 v54, 1.0, v63
	v_rcp_f32_e32 v63, v54
	v_add_f32_e32 v54, 1.0, v59
	v_rcp_f32_e32 v59, v54
	v_mov_b32_e32 v54, v64
	v_mov_b32_e32 v55, v56
	v_pk_mul_f32 v[54:55], v[66:67], v[54:55] op_sel_hi:[0,1]
	v_mul_f32_e32 v56, 0xbfb8aa3b, v54
	v_exp_f32_e32 v56, v56
	v_mul_f32_e32 v50, v50, v51
	v_mul_f32_e32 v59, v59, v50
	v_mov_b32_e32 v51, v52
	v_add_f32_e32 v50, 1.0, v56
	v_rcp_f32_e32 v56, v50
	v_mov_b32_e32 v50, v60
	v_pk_mul_f32 v[50:51], v[66:67], v[50:51] op_sel_hi:[0,1]
	v_mul_f32_e32 v52, 0xbfb8aa3b, v50
	v_exp_f32_e32 v52, v52
	v_mul_f32_e32 v54, v54, v55
	v_mul_f32_e32 v60, v56, v54
	v_mul_f32_e32 v54, v50, v51
	v_add_f32_e32 v50, 1.0, v52
	v_mov_b32_e32 v56, v65
	v_rcp_f32_e32 v55, v50
	v_pk_mul_f32 v[50:51], v[66:67], v[56:57] op_sel_hi:[0,1]
	v_mul_f32_e32 v52, 0xbfb8aa3b, v50
	v_exp_f32_e32 v56, v52
	v_mov_b32_e32 v52, v61
	v_pk_mul_f32 v[52:53], v[66:67], v[52:53] op_sel_hi:[0,1]
	v_mul_f32_e32 v57, 0xbfb8aa3b, v52
	v_exp_f32_e32 v57, v57
	v_mul_f32_e32 v61, v55, v54
	v_add_f32_e32 v54, 1.0, v56
	v_rcp_f32_e32 v54, v54
	v_add_f32_e32 v55, 1.0, v57
	v_rcp_f32_e32 v55, v55
	v_mul_f32_e32 v50, v50, v51
	v_mul_f32_e32 v56, v54, v50
	v_mul_f32_e32 v50, v52, v53
	v_mul_f32_e32 v53, v55, v50
	v_mad_i64_i32 v[50:51], s[2:3], v58, s59, v[114:115]
	v_lshl_add_u64 v[54:55], v[50:51], 0, v[116:117]
	v_mul_f32_e32 v63, v63, v68
	v_cvt_pk_bf16_f32 v50, v62, v63
	v_cvt_pk_bf16_f32 v51, v60, v56
	v_cvt_pk_bf16_f32 v52, v67, v59
	v_cvt_pk_bf16_f32 v53, v61, v53
	global_store_dwordx4 v[54:55], v[50:53], off
	s_nop 0
	s_nop 0
	v_fmamk_f32 v50, v148, 0x3a000000, v146
	v_rsq_f32_e32 v50, v50
	v_mov_b32_e32 v52, v46
	v_mov_b32_e32 v53, v38
	v_mov_b32_e32 v54, v42
	v_pk_mul_f32 v[52:53], v[50:51], v[52:53] op_sel_hi:[0,1]
	v_mov_b32_e32 v55, v34
	v_mul_f32_e32 v38, 0xbfb8aa3b, v52
	v_pk_mul_f32 v[54:55], v[50:51], v[54:55] op_sel_hi:[0,1]
	v_exp_f32_e32 v38, v38
	v_mul_f32_e32 v34, 0xbfb8aa3b, v54
	v_exp_f32_e32 v34, v34
	v_mul_f32_e32 v42, v52, v53
	v_add_f32_e32 v38, 1.0, v38
	v_rcp_f32_e32 v38, v38
	v_add_f32_e32 v34, 1.0, v34
	v_rcp_f32_e32 v34, v34
	v_mul_f32_e32 v42, v38, v42
	v_mul_f32_e32 v38, v54, v55
	v_mul_f32_e32 v46, v34, v38
	v_mov_b32_e32 v38, v47
	v_pk_mul_f32 v[38:39], v[50:51], v[38:39] op_sel_hi:[0,1]
	v_mul_f32_e32 v34, 0xbfb8aa3b, v38
	v_exp_f32_e32 v47, v34
	v_mov_b32_e32 v34, v43
	v_pk_mul_f32 v[34:35], v[50:51], v[34:35] op_sel_hi:[0,1]
	v_mul_f32_e32 v43, 0xbfb8aa3b, v34
	v_exp_f32_e32 v43, v43
	v_mul_f32_e32 v51, v38, v39
	v_add_f32_e32 v38, 1.0, v47
	v_rcp_f32_e32 v47, v38
	v_add_f32_e32 v38, 1.0, v43
	v_rcp_f32_e32 v43, v38
	v_mov_b32_e32 v38, v48
	v_mov_b32_e32 v39, v40
	v_pk_mul_f32 v[38:39], v[50:51], v[38:39] op_sel_hi:[0,1]
	v_mul_f32_e32 v40, 0xbfb8aa3b, v38
	v_exp_f32_e32 v40, v40
	v_mul_f32_e32 v34, v34, v35
	v_mul_f32_e32 v43, v43, v34
	v_mov_b32_e32 v35, v36
	v_add_f32_e32 v34, 1.0, v40
	v_rcp_f32_e32 v40, v34
	v_mov_b32_e32 v34, v44
	v_pk_mul_f32 v[34:35], v[50:51], v[34:35] op_sel_hi:[0,1]
	v_mul_f32_e32 v36, 0xbfb8aa3b, v34
	v_exp_f32_e32 v36, v36
	v_mul_f32_e32 v38, v38, v39
	v_mul_f32_e32 v44, v40, v38
	v_mul_f32_e32 v38, v34, v35
	v_add_f32_e32 v34, 1.0, v36
	v_mov_b32_e32 v40, v49
	v_rcp_f32_e32 v39, v34
	v_pk_mul_f32 v[34:35], v[50:51], v[40:41] op_sel_hi:[0,1]
	v_mul_f32_e32 v36, 0xbfb8aa3b, v34
	v_exp_f32_e32 v40, v36
	v_mov_b32_e32 v36, v45
	v_pk_mul_f32 v[36:37], v[50:51], v[36:37] op_sel_hi:[0,1]
	v_mul_f32_e32 v41, 0xbfb8aa3b, v36
	v_exp_f32_e32 v41, v41
	v_mul_f32_e32 v45, v39, v38
	v_add_f32_e32 v38, 1.0, v40
	v_rcp_f32_e32 v38, v38
	v_add_f32_e32 v39, 1.0, v41
	v_rcp_f32_e32 v39, v39
	v_mul_f32_e32 v34, v34, v35
	v_mul_f32_e32 v40, v38, v34
	v_mul_f32_e32 v34, v36, v37
	v_mul_f32_e32 v37, v39, v34
	v_add_u32_e32 v34, 0x90, v153
	v_mad_i64_i32 v[34:35], s[2:3], v34, s59, v[114:115]
	v_lshl_add_u64 v[38:39], v[34:35], 0, v[116:117]
	v_mul_f32_e32 v47, v47, v51
	v_cvt_pk_bf16_f32 v34, v42, v47
	v_cvt_pk_bf16_f32 v35, v44, v40
	v_cvt_pk_bf16_f32 v36, v46, v43
	v_cvt_pk_bf16_f32 v37, v45, v37
	global_store_dwordx4 v[38:39], v[34:37], off
	s_nop 0
	s_nop 0
	v_fmamk_f32 v34, v147, 0x3a000000, v146
	v_rsq_f32_e32 v34, v34
	v_mov_b32_e32 v36, v30
	v_mov_b32_e32 v37, v22
	v_mov_b32_e32 v38, v26
	v_pk_mul_f32 v[36:37], v[34:35], v[36:37] op_sel_hi:[0,1]
	v_mov_b32_e32 v39, v18
	v_mul_f32_e32 v22, 0xbfb8aa3b, v36
	v_pk_mul_f32 v[38:39], v[34:35], v[38:39] op_sel_hi:[0,1]
	v_exp_f32_e32 v22, v22
	v_mul_f32_e32 v18, 0xbfb8aa3b, v38
	v_exp_f32_e32 v18, v18
	v_mul_f32_e32 v26, v36, v37
	v_add_f32_e32 v22, 1.0, v22
	v_rcp_f32_e32 v22, v22
	v_add_f32_e32 v18, 1.0, v18
	v_rcp_f32_e32 v18, v18
	v_mul_f32_e32 v26, v22, v26
	v_mul_f32_e32 v22, v38, v39
	v_mul_f32_e32 v30, v18, v22
; __device__ __forceinline__ float rs_val(float ssqv) { return __builtin_amdgcn_rsqf(ssqv * (1.f / DM) + EPS); }
; __device__ __forceinline__ void st_bf16x8(bf16* p, f32x4 a, f32x4 b) { *(bf16x8*)p = pack8(a, b); }
; __device__ __forceinline__ float swiglu1(float g, float u) { return g * u * __builtin_amdgcn_rcpf(1.f + fexp2(-g * LOG2E)); }
;     __device__ __forceinline__ void preload(const pg8::Unit& u, int wr, int fr, float* rsv) const {
; #pragma unroll
;         for (int k = 0; k < 8; ++k) rsv[k] = ssq[u.pm * 256 + (k >> 2) * 128 + wr * 64 + (k & 3) * 16 + fr]; }
;     __device__ __forceinline__ void operator()(const Acc& acc, const pg8::Unit& u, int wr, int wc, int fr, int fq, const float* rsv) const {
;         const int c = u.pn * 128 + wc * 32 + fq * 8;
; #pragma unroll
;         for (int ai = 0; ai < 2; ++ai)
; #pragma unroll
;             for (int m = 0; m < 4; ++m) { const int row = u.pm * 256 + ai * 128 + wr * 64 + m * 16 + fr; const float rs = rs_val(rsv[ai * 4 + m]);
;                 f32x4 o0, o1;
; #pragma unroll
;                 for (int e = 0; e < 4; ++e) { o0[e] = swiglu1(acc[ai][0][m][0][e] * rs, acc[ai][1][m][0][e] * rs); o1[e] = swiglu1(acc[ai][0][m][1][e] * rs, acc[ai][1][m][1][e] * rs); }
;                 st_bf16x8(ACT + (size_t)row * DFF + c, o0, o1); __builtin_amdgcn_sched_barrier(0); }
	v_mov_b32_e32 v22, v31
	v_pk_mul_f32 v[22:23], v[34:35], v[22:23] op_sel_hi:[0,1]
	v_mul_f32_e32 v18, 0xbfb8aa3b, v22
	v_exp_f32_e32 v31, v18
	v_mov_b32_e32 v18, v27
	v_pk_mul_f32 v[18:19], v[34:35], v[18:19] op_sel_hi:[0,1]
	v_mul_f32_e32 v27, 0xbfb8aa3b, v18
	v_exp_f32_e32 v27, v27
	v_mul_f32_e32 v35, v22, v23
	v_add_f32_e32 v22, 1.0, v31
	v_rcp_f32_e32 v31, v22
	v_add_f32_e32 v22, 1.0, v27
	v_rcp_f32_e32 v27, v22
	v_mov_b32_e32 v22, v32
	v_mov_b32_e32 v23, v24
	v_pk_mul_f32 v[22:23], v[34:35], v[22:23] op_sel_hi:[0,1]
	v_mul_f32_e32 v24, 0xbfb8aa3b, v22
	v_exp_f32_e32 v24, v24
	v_mul_f32_e32 v18, v18, v19
	v_mul_f32_e32 v27, v27, v18
	v_mov_b32_e32 v19, v20
	v_add_f32_e32 v18, 1.0, v24
	v_rcp_f32_e32 v24, v18
	v_mov_b32_e32 v18, v28
	v_pk_mul_f32 v[18:19], v[34:35], v[18:19] op_sel_hi:[0,1]
	v_mul_f32_e32 v20, 0xbfb8aa3b, v18
	v_exp_f32_e32 v20, v20
	v_mul_f32_e32 v22, v22, v23
	v_mul_f32_e32 v28, v24, v22
	v_mul_f32_e32 v22, v18, v19
	v_add_f32_e32 v18, 1.0, v20
	v_mov_b32_e32 v24, v33
	v_rcp_f32_e32 v23, v18
	v_pk_mul_f32 v[18:19], v[34:35], v[24:25] op_sel_hi:[0,1]
	v_mul_f32_e32 v20, 0xbfb8aa3b, v18
	v_exp_f32_e32 v24, v20
	v_mov_b32_e32 v20, v29
	v_pk_mul_f32 v[20:21], v[34:35], v[20:21] op_sel_hi:[0,1]
	v_mul_f32_e32 v25, 0xbfb8aa3b, v20
	v_exp_f32_e32 v25, v25
	v_mul_f32_e32 v29, v23, v22
	v_add_f32_e32 v22, 1.0, v24
	v_rcp_f32_e32 v22, v22
	v_add_f32_e32 v23, 1.0, v25
	v_rcp_f32_e32 v23, v23
	v_mul_f32_e32 v18, v18, v19
	v_mul_f32_e32 v24, v22, v18
	v_mul_f32_e32 v18, v20, v21
	v_mul_f32_e32 v21, v23, v18
	v_add_u32_e32 v18, 0xa0, v153
	v_mad_i64_i32 v[18:19], s[2:3], v18, s59, v[114:115]
	v_lshl_add_u64 v[22:23], v[18:19], 0, v[116:117]
	v_mul_f32_e32 v31, v31, v35
	v_cvt_pk_bf16_f32 v18, v26, v31
	v_cvt_pk_bf16_f32 v19, v28, v24
	v_cvt_pk_bf16_f32 v20, v30, v27
	v_cvt_pk_bf16_f32 v21, v29, v21
	global_store_dwordx4 v[22:23], v[18:21], off
	s_nop 0
	s_nop 0
	v_fmamk_f32 v18, v139, 0x3a000000, v146
	v_rsq_f32_e32 v18, v18
	v_mov_b32_e32 v20, v14
	v_mov_b32_e32 v21, v6
	v_mov_b32_e32 v22, v10
	v_pk_mul_f32 v[20:21], v[18:19], v[20:21] op_sel_hi:[0,1]
	v_mov_b32_e32 v23, v2
	v_mul_f32_e32 v6, 0xbfb8aa3b, v20
	v_pk_mul_f32 v[22:23], v[18:19], v[22:23] op_sel_hi:[0,1]
	v_exp_f32_e32 v6, v6
	v_mul_f32_e32 v2, 0xbfb8aa3b, v22
	v_exp_f32_e32 v2, v2
	v_mul_f32_e32 v10, v20, v21
	v_add_f32_e32 v6, 1.0, v6
	v_rcp_f32_e32 v6, v6
	v_add_f32_e32 v2, 1.0, v2
	v_rcp_f32_e32 v2, v2
	v_mul_f32_e32 v10, v6, v10
	v_mul_f32_e32 v6, v22, v23
	v_mul_f32_e32 v14, v2, v6
	v_mov_b32_e32 v6, v15
	v_pk_mul_f32 v[6:7], v[18:19], v[6:7] op_sel_hi:[0,1]
	v_mul_f32_e32 v2, 0xbfb8aa3b, v6
	v_exp_f32_e32 v15, v2
	v_mov_b32_e32 v2, v11
	v_pk_mul_f32 v[2:3], v[18:19], v[2:3] op_sel_hi:[0,1]
	v_mul_f32_e32 v11, 0xbfb8aa3b, v2
	v_exp_f32_e32 v11, v11
	v_mul_f32_e32 v19, v6, v7
	v_add_f32_e32 v6, 1.0, v15
	v_rcp_f32_e32 v15, v6
	v_add_f32_e32 v6, 1.0, v11
	v_rcp_f32_e32 v11, v6
	v_mov_b32_e32 v6, v16
	v_mov_b32_e32 v7, v8
	v_pk_mul_f32 v[6:7], v[18:19], v[6:7] op_sel_hi:[0,1]
	v_mul_f32_e32 v8, 0xbfb8aa3b, v6
	v_exp_f32_e32 v8, v8
	v_mul_f32_e32 v2, v2, v3
	v_mul_f32_e32 v11, v11, v2
	v_mov_b32_e32 v3, v4
	v_add_f32_e32 v2, 1.0, v8
	v_rcp_f32_e32 v8, v2
	v_mov_b32_e32 v2, v12
	v_pk_mul_f32 v[2:3], v[18:19], v[2:3] op_sel_hi:[0,1]
	v_mul_f32_e32 v4, 0xbfb8aa3b, v2
	v_exp_f32_e32 v4, v4
	v_mul_f32_e32 v6, v6, v7
	v_mul_f32_e32 v12, v8, v6
	v_mul_f32_e32 v6, v2, v3
	v_add_f32_e32 v2, 1.0, v4
	v_mov_b32_e32 v8, v17
	v_rcp_f32_e32 v7, v2
	v_pk_mul_f32 v[2:3], v[18:19], v[8:9] op_sel_hi:[0,1]
	v_mul_f32_e32 v4, 0xbfb8aa3b, v2
	v_exp_f32_e32 v8, v4
	v_mov_b32_e32 v4, v13
	v_pk_mul_f32 v[4:5], v[18:19], v[4:5] op_sel_hi:[0,1]
	v_mul_f32_e32 v9, 0xbfb8aa3b, v4
	v_exp_f32_e32 v9, v9
	v_mul_f32_e32 v13, v7, v6
	v_add_f32_e32 v6, 1.0, v8
	v_rcp_f32_e32 v6, v6
	v_add_f32_e32 v7, 1.0, v9
	v_rcp_f32_e32 v7, v7
	v_mul_f32_e32 v2, v2, v3
	v_mul_f32_e32 v8, v6, v2
	v_mul_f32_e32 v2, v4, v5
	v_mul_f32_e32 v5, v7, v2
	v_add_u32_e32 v2, 0xb0, v153
	v_mad_i64_i32 v[2:3], s[2:3], v2, s59, v[114:115]
	v_lshl_add_u64 v[6:7], v[2:3], 0, v[116:117]
	v_mul_f32_e32 v15, v15, v19
	v_cvt_pk_bf16_f32 v2, v10, v15
	v_cvt_pk_bf16_f32 v3, v12, v8
	v_cvt_pk_bf16_f32 v4, v14, v11
	v_cvt_pk_bf16_f32 v5, v13, v5
	global_store_dwordx4 v[6:7], v[2:5], off
	s_andn2_b64 vcc, exec, s[10:11]
	s_mov_b64 s[4:5], -1
	s_cbranch_vccnz .LBB0_2067
	v_lshl_add_u32 v2, s20, 8, v138
	v_ashrrev_i32_e32 v3, 31, v2
	v_lshl_add_u64 v[4:5], v[2:3], 2, s[8:9]
	v_add_u32_e32 v2, 0x80, v2
	v_ashrrev_i32_e32 v3, 31, v2
	v_lshl_add_u64 v[2:3], v[2:3], 2, s[8:9]
	global_load_dword v153, v[4:5], off
	global_load_dword v152, v[4:5], off offset:64
	global_load_dword v151, v[4:5], off offset:128
	global_load_dword v150, v[4:5], off offset:192
	global_load_dword v149, v[2:3], off
	global_load_dword v148, v[2:3], off offset:64
	global_load_dword v147, v[2:3], off offset:128
	global_load_dword v139, v[2:3], off offset:192
	s_andn2_b64 vcc, exec, s[12:13]
	s_cbranch_vccnz .LBB0_2066
	s_barrier
	s_branch .LBB0_2066

; #define PG8_STAGE(bufoff, gbase, voff) do { _Pragma("unroll") for (int _i = 0; _i < 2; ++_i) { unsigned keep_; \
;         asm volatile("s_mov_b32 %0, m0\n\ts_mov_b32 m0, %3\n\ts_nop 0\n\tglobal_load_lds_dwordx4 %1, %2\n\ts_mov_b32 m0, %0" \
;             : "=&s"(keep_) : "v"((voff)[_i]), "s"((const void*)(gbase)), "s"(ldsb0 + (unsigned)(bufoff) + (unsigned)(_i * 8192)) : "memory"); } } while (0)
; #define PG8_LDA(dst, b, h) do { _Pragma("unroll") for (int m = 0; m < 4; ++m) _Pragma("unroll") for (int k = 0; k < 2; ++k) dst[m][k] = *(const LAS bf16x8*)(lds + PG8_SA(b, h) + aoff + m * 2048 + k * 1024); } while (0)
; #define PG8_LDB(dst, b, h) do { _Pragma("unroll") for (int n = 0; n < 2; ++n) _Pragma("unroll") for (int k = 0; k < 2; ++k) dst[n][k] = *(const LAS bf16x8*)(lds + PG8_SB(b, h) + boff + n * 2048 + k * 1024); } while (0)
; template <class Epi, class Sched, bool ALIGN_EPI>
; __device__ __forceinline__ void gemm_phase(LAS unsigned char* lds, const Gemm g, const Sched& S, const Epi& E) {
;     ...
;         for (int t = 0; t < nt; t += 2) {
;             const bool last = (t == nt - 2);
;             const char* a1 = cA + (size_t)(t + 1) * kstep;
;             const char* a2 = last ? nA : cA + (size_t)(t + 2) * kstep; const char* b2 = last ? nB : cB + (size_t)(t + 2) * kstep;
;             const char* a3 = a2 + kstep; const char* b3 = b2 + kstep;
;             PG8_LDB(B0, 0, 0); PG8_LDB(B1, 0, 1); PG8_SCHED; PG8_LDA(At, 0, 0); PG8_STAGE(PG8_SA(1, 1), a1 + hstepA, voffA);
;             PG8_WAIT_V(8); PG8_WAIT_L(0); PG8_BAR; PG8_MMA(0, 0, At, B0); PG8_MMA(0, 1, At, B1); PG8_BAR; PG8_SCHED;
;             PG8_LDA(At, 0, 1); PG8_STAGE(PG8_SB(0, 0), b2, voffB); PG8_STAGE(PG8_SB(0, 1), b2 + hstepB, voffB); PG8_STAGE(PG8_SA(0, 0), a2, voffA);
;             PG8_WAIT_V(8); PG8_WAIT_L(0); PG8_BAR; PG8_MMA(1, 0, At, B0); PG8_MMA(1, 1, At, B1); PG8_BAR; PG8_SCHED;
;             PG8_LDB(B0, 1, 0); PG8_LDB(B1, 1, 1); PG8_SCHED; PG8_LDA(At, 1, 0); PG8_STAGE(PG8_SA(0, 1), a2 + hstepA, voffA);
;             PG8_WAIT_V(8); PG8_WAIT_L(0); PG8_BAR; PG8_MMA(0, 0, At, B0); PG8_MMA(0, 1, At, B1); PG8_BAR; PG8_SCHED;
;             PG8_LDA(At, 1, 1); PG8_STAGE(PG8_SB(1, 0), b3, voffB); PG8_STAGE(PG8_SB(1, 1), b3 + hstepB, voffB); PG8_STAGE(PG8_SA(1, 0), a3, voffA);
;             PG8_WAIT_V(8); PG8_WAIT_L(0); PG8_BAR; PG8_MMA(1, 0, At, B0); PG8_MMA(1, 1, At, B1); PG8_BAR; PG8_SCHED;
.LBB0_2172:
	s_add_u32 s61, s22, s26
	s_addc_u32 s63, s23, s27
	s_add_u32 s28, s61, 0x100
	v_add_u32_e32 v141, 0x10000, v139
	s_addc_u32 s29, s63, 0
	ds_read_b128 v[142:145], v141
	ds_read_b128 v[146:149], v141 offset:1024
	ds_read_b128 v[150:153], v141 offset:2048
	ds_read_b128 v[154:157], v141 offset:3072
	v_add_u32_e32 v141, 0x14000, v139
	s_add_u32 s30, s20, s26
	ds_read_b128 v[158:161], v141
	ds_read_b128 v[162:165], v141 offset:1024
	ds_read_b128 v[166:169], v141 offset:2048
	ds_read_b128 v[170:173], v141 offset:3072
	s_addc_u32 s31, s21, s27
	s_add_u32 s30, s30, 0x100
	s_addc_u32 s31, s31, 0
	s_cmpk_eq_i32 s60, 0x54
	s_cselect_b32 s34, s12, s28
	s_cselect_b32 s35, s13, s29
	s_cselect_b32 s30, s24, s30
	s_cselect_b32 s31, s25, s31
	s_add_u32 s28, s34, 0x80
	s_addc_u32 s29, s35, 0
	ds_read_b128 v[174:177], v140
	ds_read_b128 v[178:181], v140 offset:1024
	ds_read_b128 v[182:185], v140 offset:2048
	ds_read_b128 v[186:189], v140 offset:3072
	ds_read_b128 v[190:193], v140 offset:4096
	ds_read_b128 v[194:197], v140 offset:5120
	ds_read_b128 v[198:201], v140 offset:6144
	ds_read_b128 v[204:207], v140 offset:7168
	s_add_u32 s62, s61, 0x160080
	s_addc_u32 s63, s63, 0
	s_mov_b32 m0, s54
	s_nop 0
	global_load_lds_dwordx4 v131, s[62:63]
	s_mov_b32 m0, s55
	s_nop 0
	global_load_lds_dwordx4 v137, s[62:63]
	s_waitcnt vmcnt(8)
	s_waitcnt lgkmcnt(0)
	s_barrier
	s_setprio 1
	v_mfma_f32_16x16x32_bf16 v[126:129], v[142:145], v[174:177], v[126:129]
	v_mfma_f32_16x16x32_bf16 v[122:125], v[150:153], v[174:177], v[122:125]
	v_mfma_f32_16x16x32_bf16 v[110:113], v[142:145], v[182:185], v[110:113]
	v_mfma_f32_16x16x32_bf16 v[106:109], v[150:153], v[182:185], v[106:109]
	v_mfma_f32_16x16x32_bf16 v[94:97], v[142:145], v[190:193], v[94:97]
	v_mfma_f32_16x16x32_bf16 v[90:93], v[150:153], v[190:193], v[90:93]
	v_mfma_f32_16x16x32_bf16 v[78:81], v[142:145], v[198:201], v[78:81]
	v_mfma_f32_16x16x32_bf16 v[74:77], v[150:153], v[198:201], v[74:77]
	v_mfma_f32_16x16x32_bf16 v[126:129], v[146:149], v[178:181], v[126:129]
	v_mfma_f32_16x16x32_bf16 v[122:125], v[154:157], v[178:181], v[122:125]
	v_mfma_f32_16x16x32_bf16 v[110:113], v[146:149], v[186:189], v[110:113]
	v_mfma_f32_16x16x32_bf16 v[106:109], v[154:157], v[186:189], v[106:109]
	v_mfma_f32_16x16x32_bf16 v[94:97], v[146:149], v[194:197], v[94:97]
	v_mfma_f32_16x16x32_bf16 v[90:93], v[154:157], v[194:197], v[90:93]
	v_mfma_f32_16x16x32_bf16 v[78:81], v[146:149], v[204:207], v[78:81]
	v_mfma_f32_16x16x32_bf16 v[74:77], v[154:157], v[204:207], v[74:77]
	v_mfma_f32_16x16x32_bf16 v[118:121], v[158:161], v[174:177], v[118:121]
	v_mfma_f32_16x16x32_bf16 v[114:117], v[166:169], v[174:177], v[114:117]
	v_mfma_f32_16x16x32_bf16 v[102:105], v[158:161], v[182:185], v[102:105]
	v_mfma_f32_16x16x32_bf16 v[98:101], v[166:169], v[182:185], v[98:101]
	v_mfma_f32_16x16x32_bf16 v[86:89], v[158:161], v[190:193], v[86:89]
	v_mfma_f32_16x16x32_bf16 v[82:85], v[166:169], v[190:193], v[82:85]
	v_mfma_f32_16x16x32_bf16 v[70:73], v[158:161], v[198:201], v[70:73]
	v_mfma_f32_16x16x32_bf16 v[66:69], v[166:169], v[198:201], v[66:69]
	v_mfma_f32_16x16x32_bf16 v[118:121], v[162:165], v[178:181], v[118:121]
	v_mfma_f32_16x16x32_bf16 v[114:117], v[170:173], v[178:181], v[114:117]
	v_mfma_f32_16x16x32_bf16 v[102:105], v[162:165], v[186:189], v[102:105]
	v_mfma_f32_16x16x32_bf16 v[98:101], v[170:173], v[186:189], v[98:101]
	v_mfma_f32_16x16x32_bf16 v[86:89], v[162:165], v[194:197], v[86:89]
	v_mfma_f32_16x16x32_bf16 v[82:85], v[170:173], v[194:197], v[82:85]
	v_mfma_f32_16x16x32_bf16 v[70:73], v[162:165], v[204:207], v[70:73]
	v_mfma_f32_16x16x32_bf16 v[66:69], v[170:173], v[204:207], v[66:69]
	s_setprio 0
	s_barrier
	ds_read_b128 v[174:177], v140 offset:16384
	ds_read_b128 v[178:181], v140 offset:17408
	ds_read_b128 v[182:185], v140 offset:18432
	ds_read_b128 v[186:189], v140 offset:19456
	ds_read_b128 v[190:193], v140 offset:20480
	ds_read_b128 v[194:197], v140 offset:21504
	ds_read_b128 v[198:201], v140 offset:22528
	ds_read_b128 v[204:207], v140 offset:23552
	s_mov_b32 m0, s3
	s_nop 0
	global_load_lds_dwordx4 v136, s[30:31]
	s_add_u32 s62, s30, 0x160000
	s_mov_b32 m0, s41
	s_nop 0
	global_load_lds_dwordx4 v138, s[30:31]
	s_addc_u32 s63, s31, 0
	s_mov_b32 m0, s42
	s_nop 0
	global_load_lds_dwordx4 v136, s[62:63]
	s_mov_b32 m0, s43
	s_nop 0
	global_load_lds_dwordx4 v138, s[62:63]
	s_mov_b32 m0, s2
	s_nop 0
	global_load_lds_dwordx4 v131, s[34:35]
	s_mov_b32 m0, s44
	s_nop 0
	global_load_lds_dwordx4 v137, s[34:35]
	s_waitcnt vmcnt(8)
	s_waitcnt lgkmcnt(0)
	s_barrier
; #define PG8_STAGE(bufoff, gbase, voff) do { _Pragma("unroll") for (int _i = 0; _i < 2; ++_i) { unsigned keep_; \
;         asm volatile("s_mov_b32 %0, m0\n\ts_mov_b32 m0, %3\n\ts_nop 0\n\tglobal_load_lds_dwordx4 %1, %2\n\ts_mov_b32 m0, %0" \
;             : "=&s"(keep_) : "v"((voff)[_i]), "s"((const void*)(gbase)), "s"(ldsb0 + (unsigned)(bufoff) + (unsigned)(_i * 8192)) : "memory"); } } while (0)
; #define PG8_LDA(dst, b, h) do { _Pragma("unroll") for (int m = 0; m < 4; ++m) _Pragma("unroll") for (int k = 0; k < 2; ++k) dst[m][k] = *(const LAS bf16x8*)(lds + PG8_SA(b, h) + aoff + m * 2048 + k * 1024); } while (0)
; #define PG8_LDB(dst, b, h) do { _Pragma("unroll") for (int n = 0; n < 2; ++n) _Pragma("unroll") for (int k = 0; k < 2; ++k) dst[n][k] = *(const LAS bf16x8*)(lds + PG8_SB(b, h) + boff + n * 2048 + k * 1024); } while (0)
; template <class Epi, class Sched, bool ALIGN_EPI>
; __device__ __forceinline__ void gemm_phase(LAS unsigned char* lds, const Gemm g, const Sched& S, const Epi& E) {
;     ...
;         for (int t = 0; t < nt; t += 2) {
;             const bool last = (t == nt - 2);
;             const char* a1 = cA + (size_t)(t + 1) * kstep;
;             const char* a2 = last ? nA : cA + (size_t)(t + 2) * kstep; const char* b2 = last ? nB : cB + (size_t)(t + 2) * kstep;
;             const char* a3 = a2 + kstep; const char* b3 = b2 + kstep;
;             PG8_LDB(B0, 0, 0); PG8_LDB(B1, 0, 1); PG8_SCHED; PG8_LDA(At, 0, 0); PG8_STAGE(PG8_SA(1, 1), a1 + hstepA, voffA);
;             PG8_WAIT_V(8); PG8_WAIT_L(0); PG8_BAR; PG8_MMA(0, 0, At, B0); PG8_MMA(0, 1, At, B1); PG8_BAR; PG8_SCHED;
;             PG8_LDA(At, 0, 1); PG8_STAGE(PG8_SB(0, 0), b2, voffB); PG8_STAGE(PG8_SB(0, 1), b2 + hstepB, voffB); PG8_STAGE(PG8_SA(0, 0), a2, voffA);
;             PG8_WAIT_V(8); PG8_WAIT_L(0); PG8_BAR; PG8_MMA(1, 0, At, B0); PG8_MMA(1, 1, At, B1); PG8_BAR; PG8_SCHED;
;             PG8_LDB(B0, 1, 0); PG8_LDB(B1, 1, 1); PG8_SCHED; PG8_LDA(At, 1, 0); PG8_STAGE(PG8_SA(0, 1), a2 + hstepA, voffA);
;             PG8_WAIT_V(8); PG8_WAIT_L(0); PG8_BAR; PG8_MMA(0, 0, At, B0); PG8_MMA(0, 1, At, B1); PG8_BAR; PG8_SCHED;
;             PG8_LDA(At, 1, 1); PG8_STAGE(PG8_SB(1, 0), b3, voffB); PG8_STAGE(PG8_SB(1, 1), b3 + hstepB, voffB); PG8_STAGE(PG8_SA(1, 0), a3, voffA);
;             PG8_WAIT_V(8); PG8_WAIT_L(0); PG8_BAR; PG8_MMA(1, 0, At, B0); PG8_MMA(1, 1, At, B1); PG8_BAR; PG8_SCHED;
	s_setprio 1
	v_mfma_f32_16x16x32_bf16 v[62:65], v[142:145], v[174:177], v[62:65]
	v_mfma_f32_16x16x32_bf16 v[58:61], v[150:153], v[174:177], v[58:61]
	v_mfma_f32_16x16x32_bf16 v[46:49], v[142:145], v[182:185], v[46:49]
	v_mfma_f32_16x16x32_bf16 v[42:45], v[150:153], v[182:185], v[42:45]
	v_mfma_f32_16x16x32_bf16 v[30:33], v[142:145], v[190:193], v[30:33]
	v_mfma_f32_16x16x32_bf16 v[26:29], v[150:153], v[190:193], v[26:29]
	v_mfma_f32_16x16x32_bf16 v[14:17], v[142:145], v[198:201], v[14:17]
	v_mfma_f32_16x16x32_bf16 v[10:13], v[150:153], v[198:201], v[10:13]
	v_mfma_f32_16x16x32_bf16 v[62:65], v[146:149], v[178:181], v[62:65]
	v_mfma_f32_16x16x32_bf16 v[58:61], v[154:157], v[178:181], v[58:61]
	v_mfma_f32_16x16x32_bf16 v[46:49], v[146:149], v[186:189], v[46:49]
	v_mfma_f32_16x16x32_bf16 v[42:45], v[154:157], v[186:189], v[42:45]
	v_mfma_f32_16x16x32_bf16 v[30:33], v[146:149], v[194:197], v[30:33]
	v_mfma_f32_16x16x32_bf16 v[26:29], v[154:157], v[194:197], v[26:29]
	v_mfma_f32_16x16x32_bf16 v[14:17], v[146:149], v[204:207], v[14:17]
	v_mfma_f32_16x16x32_bf16 v[10:13], v[154:157], v[204:207], v[10:13]
	v_mfma_f32_16x16x32_bf16 v[54:57], v[158:161], v[174:177], v[54:57]
	v_mfma_f32_16x16x32_bf16 v[50:53], v[166:169], v[174:177], v[50:53]
	v_mfma_f32_16x16x32_bf16 v[38:41], v[158:161], v[182:185], v[38:41]
	v_mfma_f32_16x16x32_bf16 v[34:37], v[166:169], v[182:185], v[34:37]
	v_mfma_f32_16x16x32_bf16 v[22:25], v[158:161], v[190:193], v[22:25]
	v_mfma_f32_16x16x32_bf16 v[18:21], v[166:169], v[190:193], v[18:21]
	v_mfma_f32_16x16x32_bf16 v[6:9], v[158:161], v[198:201], v[6:9]
	v_mfma_f32_16x16x32_bf16 v[2:5], v[166:169], v[198:201], v[2:5]
	v_mfma_f32_16x16x32_bf16 v[54:57], v[162:165], v[178:181], v[54:57]
	v_mfma_f32_16x16x32_bf16 v[50:53], v[170:173], v[178:181], v[50:53]
	v_mfma_f32_16x16x32_bf16 v[38:41], v[162:165], v[186:189], v[38:41]
	v_mfma_f32_16x16x32_bf16 v[34:37], v[170:173], v[186:189], v[34:37]
	v_mfma_f32_16x16x32_bf16 v[22:25], v[162:165], v[194:197], v[22:25]
	v_mfma_f32_16x16x32_bf16 v[18:21], v[170:173], v[194:197], v[18:21]
	v_mfma_f32_16x16x32_bf16 v[6:9], v[162:165], v[204:207], v[6:9]
	v_mfma_f32_16x16x32_bf16 v[2:5], v[170:173], v[204:207], v[2:5]
	s_setprio 0
	s_barrier
	v_add_u32_e32 v141, 0x18000, v139
	ds_read_b128 v[142:145], v141
	ds_read_b128 v[146:149], v141 offset:1024
	ds_read_b128 v[150:153], v141 offset:2048
	ds_read_b128 v[154:157], v141 offset:3072
	v_add_u32_e32 v141, 0x1c000, v139
	ds_read_b128 v[158:161], v141
	ds_read_b128 v[162:165], v141 offset:1024
	ds_read_b128 v[166:169], v141 offset:2048
	ds_read_b128 v[170:173], v141 offset:3072
	ds_read_b128 v[174:177], v140 offset:32768
	ds_read_b128 v[178:181], v140 offset:33792
	ds_read_b128 v[182:185], v140 offset:34816
	ds_read_b128 v[186:189], v140 offset:35840
	ds_read_b128 v[190:193], v140 offset:36864
	ds_read_b128 v[194:197], v140 offset:37888
	ds_read_b128 v[198:201], v140 offset:38912
	ds_read_b128 v[204:207], v140 offset:39936
	s_add_u32 s34, s34, 0x160000
	s_addc_u32 s35, s35, 0
	s_mov_b32 m0, s46
	s_nop 0
	global_load_lds_dwordx4 v131, s[34:35]
	s_mov_b32 m0, s47
	s_nop 0
	global_load_lds_dwordx4 v137, s[34:35]
	s_waitcnt vmcnt(8)
	s_waitcnt lgkmcnt(0)
	s_barrier
	s_setprio 1
	v_mfma_f32_16x16x32_bf16 v[126:129], v[142:145], v[174:177], v[126:129]
	v_mfma_f32_16x16x32_bf16 v[122:125], v[150:153], v[174:177], v[122:125]
	v_mfma_f32_16x16x32_bf16 v[110:113], v[142:145], v[182:185], v[110:113]
	v_mfma_f32_16x16x32_bf16 v[106:109], v[150:153], v[182:185], v[106:109]
	v_mfma_f32_16x16x32_bf16 v[94:97], v[142:145], v[190:193], v[94:97]
	v_mfma_f32_16x16x32_bf16 v[90:93], v[150:153], v[190:193], v[90:93]
	v_mfma_f32_16x16x32_bf16 v[78:81], v[142:145], v[198:201], v[78:81]
	v_mfma_f32_16x16x32_bf16 v[74:77], v[150:153], v[198:201], v[74:77]
	v_mfma_f32_16x16x32_bf16 v[126:129], v[146:149], v[178:181], v[126:129]
	v_mfma_f32_16x16x32_bf16 v[122:125], v[154:157], v[178:181], v[122:125]
	v_mfma_f32_16x16x32_bf16 v[110:113], v[146:149], v[186:189], v[110:113]
	v_mfma_f32_16x16x32_bf16 v[106:109], v[154:157], v[186:189], v[106:109]
	v_mfma_f32_16x16x32_bf16 v[94:97], v[146:149], v[194:197], v[94:97]
	v_mfma_f32_16x16x32_bf16 v[90:93], v[154:157], v[194:197], v[90:93]
	v_mfma_f32_16x16x32_bf16 v[78:81], v[146:149], v[204:207], v[78:81]
	v_mfma_f32_16x16x32_bf16 v[74:77], v[154:157], v[204:207], v[74:77]
	v_mfma_f32_16x16x32_bf16 v[118:121], v[158:161], v[174:177], v[118:121]
	v_mfma_f32_16x16x32_bf16 v[114:117], v[166:169], v[174:177], v[114:117]
	v_mfma_f32_16x16x32_bf16 v[102:105], v[158:161], v[182:185], v[102:105]
	v_mfma_f32_16x16x32_bf16 v[98:101], v[166:169], v[182:185], v[98:101]
	v_mfma_f32_16x16x32_bf16 v[86:89], v[158:161], v[190:193], v[86:89]
	v_mfma_f32_16x16x32_bf16 v[82:85], v[166:169], v[190:193], v[82:85]
	v_mfma_f32_16x16x32_bf16 v[70:73], v[158:161], v[198:201], v[70:73]
	v_mfma_f32_16x16x32_bf16 v[66:69], v[166:169], v[198:201], v[66:69]
	v_mfma_f32_16x16x32_bf16 v[118:121], v[162:165], v[178:181], v[118:121]
	v_mfma_f32_16x16x32_bf16 v[114:117], v[170:173], v[178:181], v[114:117]
	v_mfma_f32_16x16x32_bf16 v[102:105], v[162:165], v[186:189], v[102:105]
	v_mfma_f32_16x16x32_bf16 v[98:101], v[170:173], v[186:189], v[98:101]
	v_mfma_f32_16x16x32_bf16 v[86:89], v[162:165], v[194:197], v[86:89]
	v_mfma_f32_16x16x32_bf16 v[82:85], v[170:173], v[194:197], v[82:85]
	v_mfma_f32_16x16x32_bf16 v[70:73], v[162:165], v[204:207], v[70:73]
	v_mfma_f32_16x16x32_bf16 v[66:69], v[170:173], v[204:207], v[66:69]
	s_setprio 0
	s_barrier
; #define PG8_STAGE(bufoff, gbase, voff) do { _Pragma("unroll") for (int _i = 0; _i < 2; ++_i) { unsigned keep_; \
;         asm volatile("s_mov_b32 %0, m0\n\ts_mov_b32 m0, %3\n\ts_nop 0\n\tglobal_load_lds_dwordx4 %1, %2\n\ts_mov_b32 m0, %0" \
;             : "=&s"(keep_) : "v"((voff)[_i]), "s"((const void*)(gbase)), "s"(ldsb0 + (unsigned)(bufoff) + (unsigned)(_i * 8192)) : "memory"); } } while (0)
; #define PG8_LDA(dst, b, h) do { _Pragma("unroll") for (int m = 0; m < 4; ++m) _Pragma("unroll") for (int k = 0; k < 2; ++k) dst[m][k] = *(const LAS bf16x8*)(lds + PG8_SA(b, h) + aoff + m * 2048 + k * 1024); } while (0)
; #define PG8_LDB(dst, b, h) do { _Pragma("unroll") for (int n = 0; n < 2; ++n) _Pragma("unroll") for (int k = 0; k < 2; ++k) dst[n][k] = *(const LAS bf16x8*)(lds + PG8_SB(b, h) + boff + n * 2048 + k * 1024); } while (0)
; #define PG8_WAIT_V(n) asm volatile("s_waitcnt vmcnt(" #n ")" ::: "memory")
; #define PG8_WAIT_L(n) asm volatile("s_waitcnt lgkmcnt(" #n ")" ::: "memory")
; #define PG8_BAR __builtin_amdgcn_s_barrier()
; #define PG8_SCHED __builtin_amdgcn_sched_barrier(0)
; template <class Epi, class Sched, bool ALIGN_EPI>
; __device__ __forceinline__ void gemm_phase(LAS unsigned char* lds, const Gemm g, const Sched& S, const Epi& E) {
;     ...
;             PG8_LDB(B0, 1, 0); PG8_LDB(B1, 1, 1); PG8_SCHED; PG8_LDA(At, 1, 0); PG8_STAGE(PG8_SA(0, 1), a2 + hstepA, voffA);
;             PG8_WAIT_V(8); PG8_WAIT_L(0); PG8_BAR; PG8_MMA(0, 0, At, B0); PG8_MMA(0, 1, At, B1); PG8_BAR; PG8_SCHED;
;             PG8_LDA(At, 1, 1); PG8_STAGE(PG8_SB(1, 0), b3, voffB); PG8_STAGE(PG8_SB(1, 1), b3 + hstepB, voffB); PG8_STAGE(PG8_SA(1, 0), a3, voffA);
;             PG8_WAIT_V(8); PG8_WAIT_L(0); PG8_BAR; PG8_MMA(1, 0, At, B0); PG8_MMA(1, 1, At, B1); PG8_BAR; PG8_SCHED;
;         }
;         if constexpr (ALIGN_EPI) { if (wr == 0) PG8_BAR; }
;         if constexpr (Epi::NPRE > 0) E(acc, cur, wr, wc, fr, fq, pre); else
;         if constexpr (!Epi::AFTER_DRAIN) E(acc, cur, wr, wc, fr, fq);
;         if (!has_next) break;
; #pragma unroll
;         for (int a = 0; a < 2; ++a)
; #pragma unroll
;             for (int b = 0; b < 2; ++b)
; #pragma unroll
;                 for (int m = 0; m < 4; ++m)
; #pragma unroll
;                     for (int n = 0; n < 2; ++n) acc[a][b][m][n] = (f32x4){0.f, 0.f, 0.f, 0.f};
;         cur = nxt; cA = nA; cB = nB; ++ui;
	ds_read_b128 v[174:177], v140 offset:49152
	ds_read_b128 v[178:181], v140 offset:50176
	ds_read_b128 v[182:185], v140 offset:51200
	ds_read_b128 v[186:189], v140 offset:52224
	ds_read_b128 v[190:193], v140 offset:53248
	ds_read_b128 v[194:197], v140 offset:54272
	ds_read_b128 v[198:201], v140 offset:55296
	ds_read_b128 v[204:207], v140 offset:56320
	s_add_u32 s34, s30, 0x80
	s_addc_u32 s35, s31, 0
	s_mov_b32 m0, s48
	s_nop 0
	global_load_lds_dwordx4 v136, s[34:35]
	s_add_u32 s30, s30, 0x160080
	s_mov_b32 m0, s49
	s_nop 0
	global_load_lds_dwordx4 v138, s[34:35]
	s_addc_u32 s31, s31, 0
	s_mov_b32 m0, s52
	s_nop 0
	global_load_lds_dwordx4 v136, s[30:31]
	s_mov_b32 m0, s53
	s_nop 0
	global_load_lds_dwordx4 v138, s[30:31]
	s_mov_b32 m0, s50
	s_nop 0
	global_load_lds_dwordx4 v131, s[28:29]
	s_mov_b32 m0, s51
	s_nop 0
	global_load_lds_dwordx4 v137, s[28:29]
	s_waitcnt vmcnt(8)
	s_waitcnt lgkmcnt(0)
	s_barrier
	s_setprio 1
	v_mfma_f32_16x16x32_bf16 v[62:65], v[142:145], v[174:177], v[62:65]
	v_mfma_f32_16x16x32_bf16 v[58:61], v[150:153], v[174:177], v[58:61]
	v_mfma_f32_16x16x32_bf16 v[46:49], v[142:145], v[182:185], v[46:49]
	v_mfma_f32_16x16x32_bf16 v[42:45], v[150:153], v[182:185], v[42:45]
	v_mfma_f32_16x16x32_bf16 v[30:33], v[142:145], v[190:193], v[30:33]
	v_mfma_f32_16x16x32_bf16 v[26:29], v[150:153], v[190:193], v[26:29]
	v_mfma_f32_16x16x32_bf16 v[14:17], v[142:145], v[198:201], v[14:17]
	v_mfma_f32_16x16x32_bf16 v[10:13], v[150:153], v[198:201], v[10:13]
	v_mfma_f32_16x16x32_bf16 v[62:65], v[146:149], v[178:181], v[62:65]
	v_mfma_f32_16x16x32_bf16 v[58:61], v[154:157], v[178:181], v[58:61]
	v_mfma_f32_16x16x32_bf16 v[46:49], v[146:149], v[186:189], v[46:49]
	v_mfma_f32_16x16x32_bf16 v[42:45], v[154:157], v[186:189], v[42:45]
	v_mfma_f32_16x16x32_bf16 v[30:33], v[146:149], v[194:197], v[30:33]
	v_mfma_f32_16x16x32_bf16 v[26:29], v[154:157], v[194:197], v[26:29]
	v_mfma_f32_16x16x32_bf16 v[14:17], v[146:149], v[204:207], v[14:17]
	v_mfma_f32_16x16x32_bf16 v[10:13], v[154:157], v[204:207], v[10:13]
	v_mfma_f32_16x16x32_bf16 v[54:57], v[158:161], v[174:177], v[54:57]
	v_mfma_f32_16x16x32_bf16 v[50:53], v[166:169], v[174:177], v[50:53]
	v_mfma_f32_16x16x32_bf16 v[38:41], v[158:161], v[182:185], v[38:41]
	v_mfma_f32_16x16x32_bf16 v[34:37], v[166:169], v[182:185], v[34:37]
	v_mfma_f32_16x16x32_bf16 v[22:25], v[158:161], v[190:193], v[22:25]
	v_mfma_f32_16x16x32_bf16 v[18:21], v[166:169], v[190:193], v[18:21]
	v_mfma_f32_16x16x32_bf16 v[6:9], v[158:161], v[198:201], v[6:9]
	v_mfma_f32_16x16x32_bf16 v[2:5], v[166:169], v[198:201], v[2:5]
	v_mfma_f32_16x16x32_bf16 v[54:57], v[162:165], v[178:181], v[54:57]
	v_mfma_f32_16x16x32_bf16 v[50:53], v[170:173], v[178:181], v[50:53]
	v_mfma_f32_16x16x32_bf16 v[38:41], v[162:165], v[186:189], v[38:41]
	v_mfma_f32_16x16x32_bf16 v[34:37], v[170:173], v[186:189], v[34:37]
	v_mfma_f32_16x16x32_bf16 v[22:25], v[162:165], v[194:197], v[22:25]
	v_mfma_f32_16x16x32_bf16 v[18:21], v[170:173], v[194:197], v[18:21]
	v_mfma_f32_16x16x32_bf16 v[6:9], v[162:165], v[204:207], v[6:9]
	v_mfma_f32_16x16x32_bf16 v[2:5], v[170:173], v[204:207], v[2:5]
	s_setprio 0
	s_barrier
	s_add_i32 s60, s60, 2
	s_add_u32 s26, s26, 0x100
	s_addc_u32 s27, s27, 0
	s_cmpk_gt_u32 s60, 0x55
	s_cbranch_scc0 .LBB0_2172
	s_and_b64 vcc, exec, s[10:11]
	s_cbranch_vccnz .LBB0_2160
	v_mov_b32_e32 v2, 0
	s_mov_b32 s45, s57
	s_mov_b32 s17, s58
	s_mov_b64 s[20:21], s[24:25]
	s_mov_b64 s[22:23], s[12:13]
	s_mov_b32 s56, s59
	v_mov_b32_e32 v3, v2
	v_mov_b32_e32 v4, v2
	v_mov_b32_e32 v5, v2
	v_mov_b32_e32 v6, v2
	v_mov_b32_e32 v7, v2
	v_mov_b32_e32 v8, v2
	v_mov_b32_e32 v9, v2
	v_mov_b32_e32 v18, v2
	v_mov_b32_e32 v19, v2
	v_mov_b32_e32 v20, v2
	v_mov_b32_e32 v21, v2
	v_mov_b32_e32 v22, v2
	v_mov_b32_e32 v23, v2
	v_mov_b32_e32 v24, v2
	v_mov_b32_e32 v25, v2
	v_mov_b32_e32 v34, v2
	v_mov_b32_e32 v35, v2
	v_mov_b32_e32 v36, v2
	v_mov_b32_e32 v37, v2
	v_mov_b32_e32 v38, v2
	v_mov_b32_e32 v39, v2
	v_mov_b32_e32 v40, v2
	v_mov_b32_e32 v41, v2
	v_mov_b32_e32 v50, v2
	v_mov_b32_e32 v51, v2
	v_mov_b32_e32 v52, v2
	v_mov_b32_e32 v53, v2
	v_mov_b32_e32 v54, v2
	v_mov_b32_e32 v55, v2
	v_mov_b32_e32 v56, v2
	v_mov_b32_e32 v57, v2
	v_mov_b32_e32 v10, v2
	v_mov_b32_e32 v11, v2
	v_mov_b32_e32 v12, v2
	v_mov_b32_e32 v13, v2
	v_mov_b32_e32 v14, v2
	v_mov_b32_e32 v15, v2
	v_mov_b32_e32 v16, v2
	v_mov_b32_e32 v17, v2
	v_mov_b32_e32 v26, v2
	v_mov_b32_e32 v27, v2
	v_mov_b32_e32 v28, v2
	v_mov_b32_e32 v29, v2
	v_mov_b32_e32 v30, v2
	v_mov_b32_e32 v31, v2
	v_mov_b32_e32 v32, v2
	v_mov_b32_e32 v33, v2
	v_mov_b32_e32 v42, v2
	v_mov_b32_e32 v43, v2
	v_mov_b32_e32 v44, v2
	v_mov_b32_e32 v45, v2
	v_mov_b32_e32 v46, v2
	v_mov_b32_e32 v47, v2
	v_mov_b32_e32 v48, v2
	v_mov_b32_e32 v49, v2
	v_mov_b32_e32 v58, v2
	v_mov_b32_e32 v59, v2
	v_mov_b32_e32 v60, v2
	v_mov_b32_e32 v61, v2
	v_mov_b32_e32 v62, v2
	v_mov_b32_e32 v63, v2
	v_mov_b32_e32 v64, v2
	v_mov_b32_e32 v65, v2
	v_mov_b32_e32 v66, v2
	v_mov_b32_e32 v67, v2
	v_mov_b32_e32 v68, v2
	v_mov_b32_e32 v69, v2
	v_mov_b32_e32 v70, v2
	v_mov_b32_e32 v71, v2
	v_mov_b32_e32 v72, v2
	v_mov_b32_e32 v73, v2
	v_mov_b32_e32 v82, v2
	v_mov_b32_e32 v83, v2
	v_mov_b32_e32 v84, v2
	v_mov_b32_e32 v85, v2
	v_mov_b32_e32 v86, v2
	v_mov_b32_e32 v87, v2
	v_mov_b32_e32 v88, v2
	v_mov_b32_e32 v89, v2
	v_mov_b32_e32 v98, v2
	v_mov_b32_e32 v99, v2
	v_mov_b32_e32 v100, v2
	v_mov_b32_e32 v101, v2
	v_mov_b32_e32 v102, v2
	v_mov_b32_e32 v103, v2
	v_mov_b32_e32 v104, v2
	v_mov_b32_e32 v105, v2
	v_mov_b32_e32 v114, v2
	v_mov_b32_e32 v115, v2
	v_mov_b32_e32 v116, v2
	v_mov_b32_e32 v117, v2
	v_mov_b32_e32 v118, v2
	v_mov_b32_e32 v119, v2
	v_mov_b32_e32 v120, v2
	v_mov_b32_e32 v121, v2
	v_mov_b32_e32 v74, v2
	v_mov_b32_e32 v75, v2
	v_mov_b32_e32 v76, v2
	v_mov_b32_e32 v77, v2
	v_mov_b32_e32 v78, v2
	v_mov_b32_e32 v79, v2
	v_mov_b32_e32 v80, v2
	v_mov_b32_e32 v81, v2
	v_mov_b32_e32 v90, v2
	v_mov_b32_e32 v91, v2
	v_mov_b32_e32 v92, v2
	v_mov_b32_e32 v93, v2
	v_mov_b32_e32 v94, v2
	v_mov_b32_e32 v95, v2
	v_mov_b32_e32 v96, v2
	v_mov_b32_e32 v97, v2
	v_mov_b32_e32 v106, v2
	v_mov_b32_e32 v107, v2
	v_mov_b32_e32 v108, v2
	v_mov_b32_e32 v109, v2
	v_mov_b32_e32 v110, v2
	v_mov_b32_e32 v111, v2
	v_mov_b32_e32 v112, v2
	v_mov_b32_e32 v113, v2
	v_mov_b32_e32 v122, v2
	v_mov_b32_e32 v123, v2
	v_mov_b32_e32 v124, v2
	v_mov_b32_e32 v125, v2
	v_mov_b32_e32 v126, v2
	v_mov_b32_e32 v127, v2
	v_mov_b32_e32 v128, v2
	v_mov_b32_e32 v129, v2
	s_branch .LBB0_2160

; #define LAS __attribute__((address_space(3)))
; __device__ __forceinline__ int otid() { int t = threadIdx.x; asm volatile("" : "+v"(t)); return t; }
; __global__ void __launch_bounds__(NT, 2) fwd(Args args) {
;     extern __shared__ __attribute__((aligned(16))) unsigned char lds_raw[];
;     LAS unsigned char* lds = (LAS unsigned char*)lds_raw;
;     volatile LAS unsigned* MISC = (volatile LAS unsigned*)(lds + MISC_OFF);
;     const int tid = otid(), lane = tid & 63, wave = __builtin_amdgcn_readfirstlane(tid >> 6);
	.amdhsa_kernel _Z3fwd4Args
		.amdhsa_group_segment_fixed_size 0
		.amdhsa_private_segment_fixed_size 0
		.amdhsa_kernarg_size 440
		.amdhsa_user_sgpr_count 2
		.amdhsa_user_sgpr_dispatch_ptr 0
		.amdhsa_user_sgpr_queue_ptr 0
		.amdhsa_user_sgpr_kernarg_segment_ptr 1
		.amdhsa_user_sgpr_dispatch_id 0
		.amdhsa_user_sgpr_kernarg_preload_length 0
		.amdhsa_user_sgpr_kernarg_preload_offset 0
		.amdhsa_user_sgpr_private_segment_size 0
		.amdhsa_uses_dynamic_stack 0
		.amdhsa_enable_private_segment 0
		.amdhsa_system_sgpr_workgroup_id_x 1
		.amdhsa_system_sgpr_workgroup_id_y 0
		.amdhsa_system_sgpr_workgroup_id_z 0
		.amdhsa_system_sgpr_workgroup_info 0
		.amdhsa_system_vgpr_workitem_id 0
		.amdhsa_next_free_vgpr 243
		.amdhsa_next_free_sgpr 100
		.amdhsa_accum_offset 244
		.amdhsa_reserve_vcc 1
		.amdhsa_float_round_mode_32 0
		.amdhsa_float_round_mode_16_64 0
		.amdhsa_float_denorm_mode_32 3
		.amdhsa_float_denorm_mode_16_64 3
		.amdhsa_dx10_clamp 1
		.amdhsa_ieee_mode 1
		.amdhsa_fp16_overflow 0
		.amdhsa_tg_split 0
		.amdhsa_exception_fp_ieee_invalid_op 0
		.amdhsa_exception_fp_denorm_src 0
		.amdhsa_exception_fp_ieee_div_zero 0
		.amdhsa_exception_fp_ieee_overflow 0
		.amdhsa_exception_fp_ieee_underflow 0
		.amdhsa_exception_fp_ieee_inexact 0
		.amdhsa_exception_int_div_zero 0
	.end_amdhsa_kernel

; __global__ void __launch_bounds__(NT, 2) fwd(Args args) {
amdhsa.kernels:
  - .agpr_count:     0
    .args:
      - .offset:         0
        .size:           184
        .value_kind:     by_value
      - .offset:         184
        .size:           4
        .value_kind:     hidden_block_count_x
      - .offset:         188
        .size:           4
        .value_kind:     hidden_block_count_y
      - .offset:         192
        .size:           4
        .value_kind:     hidden_block_count_z
      - .offset:         196
        .size:           2
        .value_kind:     hidden_group_size_x
      - .offset:         198
        .size:           2
        .value_kind:     hidden_group_size_y
      - .offset:         200
        .size:           2
        .value_kind:     hidden_group_size_z
      - .offset:         202
        .size:           2
        .value_kind:     hidden_remainder_x
      - .offset:         204
        .size:           2
        .value_kind:     hidden_remainder_y
      - .offset:         206
        .size:           2
        .value_kind:     hidden_remainder_z
      - .offset:         224
        .size:           8
        .value_kind:     hidden_global_offset_x
      - .offset:         232
        .size:           8
        .value_kind:     hidden_global_offset_y
      - .offset:         240
        .size:           8
        .value_kind:     hidden_global_offset_z
      - .offset:         248
        .size:           2
        .value_kind:     hidden_grid_dims
      - .offset:         304
        .size:           4
        .value_kind:     hidden_dynamic_lds_size
    .group_segment_fixed_size: 0
    .kernarg_segment_align: 8
    .kernarg_segment_size: 440
    .language:       OpenCL C
    .language_version:
      - 2
      - 0
    .max_flat_workgroup_size: 512
    .name:           _Z3fwd4Args
    .private_segment_fixed_size: 0
    .sgpr_count:     106
    .sgpr_spill_count: 26
    .symbol:         _Z3fwd4Args.kd
    .uniform_work_group_size: 1
    .uses_dynamic_stack: false
    .vgpr_count:     243
    .vgpr_spill_count: 0
    .wavefront_size: 64
